# GEMM K-loops: per-segment s_setprio toggles removed (all waves priority 0)
# speedup vs baseline: 1.0242x; 1.0028x over previous
.LBB0_253:
	s_add_u32 s26, s0, 0xfffc0080
	s_addc_u32 s27, s1, -1
	s_add_i32 s55, 0, 0x10000
	s_cmp_eq_u32 s54, 12
	s_cselect_b32 s31, s19, s27
	s_cselect_b32 s30, s50, s26
	v_add_u32_e32 v138, s55, v141
	s_cselect_b32 s27, s11, s53
	s_cselect_b32 s26, s51, s52
	s_add_i32 s58, 0, 0x14000
	ds_read_b128 v[144:147], v138
	ds_read_b128 v[158:161], v138 offset:1024
	ds_read_b128 v[162:165], v138 offset:2048
	ds_read_b128 v[166:169], v138 offset:3072
	v_add_u32_e32 v138, s58, v141
	ds_read_b128 v[170:173], v138
	ds_read_b128 v[174:177], v138 offset:1024
	ds_read_b128 v[178:181], v138 offset:2048
	ds_read_b128 v[182:185], v138 offset:3072
	v_lshl_add_u64 v[138:139], s[0:1], 0, v[134:135]
	s_add_i32 m0, s38, 0xc000
	ds_read_b128 v[186:189], v143
	ds_read_b128 v[190:193], v143 offset:1024
	ds_read_b128 v[194:197], v143 offset:2048
	ds_read_b128 v[198:201], v143 offset:3072
	ds_read_b128 v[202:205], v143 offset:4096
	ds_read_b128 v[218:221], v143 offset:5120
	ds_read_b128 v[222:225], v143 offset:6144
	ds_read_b128 v[226:229], v143 offset:7168
	global_load_lds_dwordx4 v[138:139], off
	v_lshl_add_u64 v[138:139], s[0:1], 0, v[136:137]
	s_add_i32 m0, s38, 0xe000
	s_nop 0
	global_load_lds_dwordx4 v[138:139], off
	s_waitcnt vmcnt(8)
	s_waitcnt lgkmcnt(0)
	s_barrier
	s_waitcnt lgkmcnt(0)
	v_mfma_f32_16x16x32_bf16 v[124:127], v[144:147], v[186:189], v[124:127]
	v_mfma_f32_16x16x32_bf16 v[116:119], v[162:165], v[186:189], v[116:119]
	v_mfma_f32_16x16x32_bf16 v[108:111], v[144:147], v[194:197], v[108:111]
	v_mfma_f32_16x16x32_bf16 v[100:103], v[162:165], v[194:197], v[100:103]
	v_mfma_f32_16x16x32_bf16 v[92:95], v[144:147], v[202:205], v[92:95]
	v_mfma_f32_16x16x32_bf16 v[84:87], v[162:165], v[202:205], v[84:87]
	v_mfma_f32_16x16x32_bf16 v[76:79], v[144:147], v[222:225], v[76:79]
	v_mfma_f32_16x16x32_bf16 v[68:71], v[162:165], v[222:225], v[68:71]
	v_mfma_f32_16x16x32_bf16 v[124:127], v[158:161], v[190:193], v[124:127]
	v_mfma_f32_16x16x32_bf16 v[116:119], v[166:169], v[190:193], v[116:119]
	v_mfma_f32_16x16x32_bf16 v[108:111], v[158:161], v[198:201], v[108:111]
	v_mfma_f32_16x16x32_bf16 v[100:103], v[166:169], v[198:201], v[100:103]
	v_mfma_f32_16x16x32_bf16 v[92:95], v[158:161], v[218:221], v[92:95]
	v_mfma_f32_16x16x32_bf16 v[84:87], v[166:169], v[218:221], v[84:87]
	v_mfma_f32_16x16x32_bf16 v[76:79], v[158:161], v[226:229], v[76:79]
	v_mfma_f32_16x16x32_bf16 v[68:71], v[166:169], v[226:229], v[68:71]
	v_mfma_f32_16x16x32_bf16 v[120:123], v[170:173], v[186:189], v[120:123]
	v_mfma_f32_16x16x32_bf16 v[112:115], v[178:181], v[186:189], v[112:115]
	v_mfma_f32_16x16x32_bf16 v[104:107], v[170:173], v[194:197], v[104:107]
	v_mfma_f32_16x16x32_bf16 v[96:99], v[178:181], v[194:197], v[96:99]
	v_mfma_f32_16x16x32_bf16 v[88:91], v[170:173], v[202:205], v[88:91]
	v_mfma_f32_16x16x32_bf16 v[80:83], v[178:181], v[202:205], v[80:83]
	v_mfma_f32_16x16x32_bf16 v[72:75], v[170:173], v[222:225], v[72:75]
	v_mfma_f32_16x16x32_bf16 v[64:67], v[178:181], v[222:225], v[64:67]
	v_mfma_f32_16x16x32_bf16 v[120:123], v[174:177], v[190:193], v[120:123]
	v_mfma_f32_16x16x32_bf16 v[112:115], v[182:185], v[190:193], v[112:115]
	v_mfma_f32_16x16x32_bf16 v[104:107], v[174:177], v[198:201], v[104:107]
	v_mfma_f32_16x16x32_bf16 v[96:99], v[182:185], v[198:201], v[96:99]
	v_mfma_f32_16x16x32_bf16 v[88:91], v[174:177], v[218:221], v[88:91]
	v_mfma_f32_16x16x32_bf16 v[80:83], v[182:185], v[218:221], v[80:83]
	v_mfma_f32_16x16x32_bf16 v[72:75], v[174:177], v[226:229], v[72:75]
	v_mfma_f32_16x16x32_bf16 v[64:67], v[182:185], v[226:229], v[64:67]
	s_barrier
	s_add_i32 s55, s55, s37
	v_lshl_add_u64 v[138:139], s[26:27], 0, v[148:149]
	s_mov_b32 m0, s55
	ds_read_b128 v[186:189], v143 offset:16384
	ds_read_b128 v[190:193], v143 offset:17408
	ds_read_b128 v[194:197], v143 offset:18432
	ds_read_b128 v[198:201], v143 offset:19456
	ds_read_b128 v[202:205], v143 offset:20480
	ds_read_b128 v[218:221], v143 offset:21504
	ds_read_b128 v[222:225], v143 offset:22528
	ds_read_b128 v[226:229], v143 offset:23552
	global_load_lds_dwordx4 v[138:139], off
	s_add_i32 m0, s55, 0x2000
	s_add_u32 s56, s26, 0x40000
	v_lshl_add_u64 v[154:155], s[26:27], 0, v[128:129]
	s_addc_u32 s57, s27, 0
	s_add_i32 s55, s58, s37
	global_load_lds_dwordx4 v[154:155], off
	v_lshl_add_u64 v[156:157], s[56:57], 0, v[148:149]
	s_mov_b32 m0, s55
	v_lshl_add_u64 v[212:213], s[30:31], 0, v[130:131]
	global_load_lds_dwordx4 v[156:157], off
	v_lshl_add_u64 v[156:157], s[56:57], 0, v[128:129]
	s_add_i32 m0, s55, 0x2000
	s_nop 0
	global_load_lds_dwordx4 v[156:157], off
	v_lshl_add_u64 v[156:157], s[30:31], 0, v[132:133]
	s_mov_b32 m0, s38
	s_nop 0
	global_load_lds_dwordx4 v[156:157], off
	s_mov_b32 m0, s39
	s_nop 0
	global_load_lds_dwordx4 v[212:213], off
	s_waitcnt vmcnt(8)
	s_waitcnt lgkmcnt(0)
	s_barrier
	s_waitcnt lgkmcnt(0)
	v_mfma_f32_16x16x32_bf16 v[60:63], v[144:147], v[186:189], v[60:63]
	v_mfma_f32_16x16x32_bf16 v[52:55], v[162:165], v[186:189], v[52:55]
	v_mfma_f32_16x16x32_bf16 v[44:47], v[144:147], v[194:197], v[44:47]
	v_mfma_f32_16x16x32_bf16 v[36:39], v[162:165], v[194:197], v[36:39]
	v_mfma_f32_16x16x32_bf16 v[28:31], v[144:147], v[202:205], v[28:31]
	v_mfma_f32_16x16x32_bf16 v[20:23], v[162:165], v[202:205], v[20:23]
	v_mfma_f32_16x16x32_bf16 v[12:15], v[144:147], v[222:225], v[12:15]
	v_mfma_f32_16x16x32_bf16 v[4:7], v[162:165], v[222:225], v[4:7]
	v_mfma_f32_16x16x32_bf16 v[60:63], v[158:161], v[190:193], v[60:63]
	v_mfma_f32_16x16x32_bf16 v[52:55], v[166:169], v[190:193], v[52:55]
	v_mfma_f32_16x16x32_bf16 v[44:47], v[158:161], v[198:201], v[44:47]
	v_mfma_f32_16x16x32_bf16 v[36:39], v[166:169], v[198:201], v[36:39]
	v_mfma_f32_16x16x32_bf16 v[28:31], v[158:161], v[218:221], v[28:31]
	v_mfma_f32_16x16x32_bf16 v[20:23], v[166:169], v[218:221], v[20:23]
	v_mfma_f32_16x16x32_bf16 v[12:15], v[158:161], v[226:229], v[12:15]
	v_mfma_f32_16x16x32_bf16 v[4:7], v[166:169], v[226:229], v[4:7]
	v_mfma_f32_16x16x32_bf16 v[56:59], v[170:173], v[186:189], v[56:59]
	v_mfma_f32_16x16x32_bf16 v[48:51], v[178:181], v[186:189], v[48:51]
	v_mfma_f32_16x16x32_bf16 v[40:43], v[170:173], v[194:197], v[40:43]
	v_mfma_f32_16x16x32_bf16 v[32:35], v[178:181], v[194:197], v[32:35]
	v_mfma_f32_16x16x32_bf16 v[24:27], v[170:173], v[202:205], v[24:27]
	v_mfma_f32_16x16x32_bf16 v[16:19], v[178:181], v[202:205], v[16:19]
	v_mfma_f32_16x16x32_bf16 v[8:11], v[170:173], v[222:225], v[8:11]
	v_mfma_f32_16x16x32_bf16 v[0:3], v[178:181], v[222:225], v[0:3]
	v_mfma_f32_16x16x32_bf16 v[56:59], v[174:177], v[190:193], v[56:59]
	v_mfma_f32_16x16x32_bf16 v[48:51], v[182:185], v[190:193], v[48:51]
	v_mfma_f32_16x16x32_bf16 v[40:43], v[174:177], v[198:201], v[40:43]
	v_mfma_f32_16x16x32_bf16 v[32:35], v[182:185], v[198:201], v[32:35]
	v_mfma_f32_16x16x32_bf16 v[24:27], v[174:177], v[218:221], v[24:27]
	v_mfma_f32_16x16x32_bf16 v[16:19], v[182:185], v[218:221], v[16:19]
	v_mfma_f32_16x16x32_bf16 v[8:11], v[174:177], v[226:229], v[8:11]
	v_mfma_f32_16x16x32_bf16 v[0:3], v[182:185], v[226:229], v[0:3]
	s_barrier
	s_add_i32 s55, 0, 0x18000
	v_add_u32_e32 v140, s55, v141
	s_add_i32 s56, 0, 0x1c000
	ds_read_b128 v[144:147], v140
	ds_read_b128 v[158:161], v140 offset:1024
	ds_read_b128 v[162:165], v140 offset:2048
	ds_read_b128 v[166:169], v140 offset:3072
	v_add_u32_e32 v140, s56, v141
	ds_read_b128 v[170:173], v140
	ds_read_b128 v[174:177], v140 offset:1024
	ds_read_b128 v[178:181], v140 offset:2048
	ds_read_b128 v[182:185], v140 offset:3072
	s_add_u32 s30, s30, 0x40000
	s_addc_u32 s31, s31, 0
	s_mov_b32 m0, s40
	v_lshl_add_u64 v[214:215], s[30:31], 0, v[132:133]
	ds_read_b128 v[186:189], v143 offset:32768
	ds_read_b128 v[190:193], v143 offset:33792
	ds_read_b128 v[194:197], v143 offset:34816
	ds_read_b128 v[198:201], v143 offset:35840
	ds_read_b128 v[202:205], v143 offset:36864
	ds_read_b128 v[218:221], v143 offset:37888
	ds_read_b128 v[222:225], v143 offset:38912
	ds_read_b128 v[226:229], v143 offset:39936
	global_load_lds_dwordx4 v[214:215], off
	v_lshl_add_u64 v[214:215], s[30:31], 0, v[130:131]
	s_mov_b32 m0, s41
	s_nop 0
	global_load_lds_dwordx4 v[214:215], off
	s_waitcnt vmcnt(8)
	s_waitcnt lgkmcnt(0)
	s_barrier
	s_waitcnt lgkmcnt(0)
	v_mfma_f32_16x16x32_bf16 v[124:127], v[144:147], v[186:189], v[124:127]
	v_mfma_f32_16x16x32_bf16 v[116:119], v[162:165], v[186:189], v[116:119]
	v_mfma_f32_16x16x32_bf16 v[108:111], v[144:147], v[194:197], v[108:111]
	v_mfma_f32_16x16x32_bf16 v[100:103], v[162:165], v[194:197], v[100:103]
	v_mfma_f32_16x16x32_bf16 v[92:95], v[144:147], v[202:205], v[92:95]
	v_mfma_f32_16x16x32_bf16 v[84:87], v[162:165], v[202:205], v[84:87]
	v_mfma_f32_16x16x32_bf16 v[76:79], v[144:147], v[222:225], v[76:79]
	v_mfma_f32_16x16x32_bf16 v[68:71], v[162:165], v[222:225], v[68:71]
	v_mfma_f32_16x16x32_bf16 v[124:127], v[158:161], v[190:193], v[124:127]
	v_mfma_f32_16x16x32_bf16 v[116:119], v[166:169], v[190:193], v[116:119]
	v_mfma_f32_16x16x32_bf16 v[108:111], v[158:161], v[198:201], v[108:111]
	v_mfma_f32_16x16x32_bf16 v[100:103], v[166:169], v[198:201], v[100:103]
	v_mfma_f32_16x16x32_bf16 v[92:95], v[158:161], v[218:221], v[92:95]
	v_mfma_f32_16x16x32_bf16 v[84:87], v[166:169], v[218:221], v[84:87]
	v_mfma_f32_16x16x32_bf16 v[76:79], v[158:161], v[226:229], v[76:79]
	v_mfma_f32_16x16x32_bf16 v[68:71], v[166:169], v[226:229], v[68:71]
	v_mfma_f32_16x16x32_bf16 v[120:123], v[170:173], v[186:189], v[120:123]
	v_mfma_f32_16x16x32_bf16 v[112:115], v[178:181], v[186:189], v[112:115]
	v_mfma_f32_16x16x32_bf16 v[104:107], v[170:173], v[194:197], v[104:107]
	v_mfma_f32_16x16x32_bf16 v[96:99], v[178:181], v[194:197], v[96:99]
	v_mfma_f32_16x16x32_bf16 v[88:91], v[170:173], v[202:205], v[88:91]
	v_mfma_f32_16x16x32_bf16 v[80:83], v[178:181], v[202:205], v[80:83]
	v_mfma_f32_16x16x32_bf16 v[72:75], v[170:173], v[222:225], v[72:75]
	v_mfma_f32_16x16x32_bf16 v[64:67], v[178:181], v[222:225], v[64:67]
	v_mfma_f32_16x16x32_bf16 v[120:123], v[174:177], v[190:193], v[120:123]
	v_mfma_f32_16x16x32_bf16 v[112:115], v[182:185], v[190:193], v[112:115]
	v_mfma_f32_16x16x32_bf16 v[104:107], v[174:177], v[198:201], v[104:107]
	v_mfma_f32_16x16x32_bf16 v[96:99], v[182:185], v[198:201], v[96:99]
	v_mfma_f32_16x16x32_bf16 v[88:91], v[174:177], v[218:221], v[88:91]
	v_mfma_f32_16x16x32_bf16 v[80:83], v[182:185], v[218:221], v[80:83]
	v_mfma_f32_16x16x32_bf16 v[72:75], v[174:177], v[226:229], v[72:75]
	v_mfma_f32_16x16x32_bf16 v[64:67], v[182:185], v[226:229], v[64:67]
	s_barrier
	s_add_i32 s30, s55, s37
	v_lshl_add_u64 v[138:139], v[138:139], 0, s[28:29]
	s_mov_b32 m0, s30
	ds_read_b128 v[186:189], v143 offset:49152
	ds_read_b128 v[190:193], v143 offset:50176
	ds_read_b128 v[194:197], v143 offset:51200
	ds_read_b128 v[198:201], v143 offset:52224
	ds_read_b128 v[202:205], v143 offset:53248
	ds_read_b128 v[218:221], v143 offset:54272
	ds_read_b128 v[222:225], v143 offset:55296
	ds_read_b128 v[226:229], v143 offset:56320
	global_load_lds_dwordx4 v[138:139], off
	s_add_i32 m0, s30, 0x2000
	s_add_u32 s26, s26, 0x40080
	v_lshl_add_u64 v[138:139], v[154:155], 0, s[28:29]
	s_addc_u32 s27, s27, 0
	s_add_i32 s30, s56, s37
	global_load_lds_dwordx4 v[138:139], off
	v_lshl_add_u64 v[138:139], s[26:27], 0, v[148:149]
	s_mov_b32 m0, s30
	s_nop 0
	global_load_lds_dwordx4 v[138:139], off
	v_lshl_add_u64 v[138:139], s[26:27], 0, v[128:129]
	s_add_i32 m0, s30, 0x2000
	s_nop 0
	global_load_lds_dwordx4 v[138:139], off
	v_lshl_add_u64 v[138:139], v[156:157], 0, s[28:29]
	s_mov_b32 m0, s46
	s_nop 0
	global_load_lds_dwordx4 v[138:139], off
	v_lshl_add_u64 v[138:139], v[212:213], 0, s[28:29]
	s_mov_b32 m0, s47
	s_nop 0
	global_load_lds_dwordx4 v[138:139], off
	s_waitcnt vmcnt(8)
	s_waitcnt lgkmcnt(0)
	s_barrier
	s_waitcnt lgkmcnt(0)
	v_mfma_f32_16x16x32_bf16 v[60:63], v[144:147], v[186:189], v[60:63]
	v_mfma_f32_16x16x32_bf16 v[52:55], v[162:165], v[186:189], v[52:55]
	v_mfma_f32_16x16x32_bf16 v[44:47], v[144:147], v[194:197], v[44:47]
	v_mfma_f32_16x16x32_bf16 v[36:39], v[162:165], v[194:197], v[36:39]
	v_mfma_f32_16x16x32_bf16 v[28:31], v[144:147], v[202:205], v[28:31]
	v_mfma_f32_16x16x32_bf16 v[20:23], v[162:165], v[202:205], v[20:23]
	v_mfma_f32_16x16x32_bf16 v[12:15], v[144:147], v[222:225], v[12:15]
	v_mfma_f32_16x16x32_bf16 v[4:7], v[162:165], v[222:225], v[4:7]
	v_mfma_f32_16x16x32_bf16 v[60:63], v[158:161], v[190:193], v[60:63]
	v_mfma_f32_16x16x32_bf16 v[52:55], v[166:169], v[190:193], v[52:55]
	v_mfma_f32_16x16x32_bf16 v[44:47], v[158:161], v[198:201], v[44:47]
	v_mfma_f32_16x16x32_bf16 v[36:39], v[166:169], v[198:201], v[36:39]
	v_mfma_f32_16x16x32_bf16 v[28:31], v[158:161], v[218:221], v[28:31]
	v_mfma_f32_16x16x32_bf16 v[20:23], v[166:169], v[218:221], v[20:23]
	v_mfma_f32_16x16x32_bf16 v[12:15], v[158:161], v[226:229], v[12:15]
	v_mfma_f32_16x16x32_bf16 v[4:7], v[166:169], v[226:229], v[4:7]
	v_mfma_f32_16x16x32_bf16 v[56:59], v[170:173], v[186:189], v[56:59]
	v_mfma_f32_16x16x32_bf16 v[48:51], v[178:181], v[186:189], v[48:51]
	v_mfma_f32_16x16x32_bf16 v[40:43], v[170:173], v[194:197], v[40:43]
	v_mfma_f32_16x16x32_bf16 v[32:35], v[178:181], v[194:197], v[32:35]
	v_mfma_f32_16x16x32_bf16 v[24:27], v[170:173], v[202:205], v[24:27]
	v_mfma_f32_16x16x32_bf16 v[16:19], v[178:181], v[202:205], v[16:19]
	v_mfma_f32_16x16x32_bf16 v[8:11], v[170:173], v[222:225], v[8:11]
	v_mfma_f32_16x16x32_bf16 v[0:3], v[178:181], v[222:225], v[0:3]
	v_mfma_f32_16x16x32_bf16 v[56:59], v[174:177], v[190:193], v[56:59]
	v_mfma_f32_16x16x32_bf16 v[48:51], v[182:185], v[190:193], v[48:51]
	v_mfma_f32_16x16x32_bf16 v[40:43], v[174:177], v[198:201], v[40:43]
	v_mfma_f32_16x16x32_bf16 v[32:35], v[182:185], v[198:201], v[32:35]
	v_mfma_f32_16x16x32_bf16 v[24:27], v[174:177], v[218:221], v[24:27]
	v_mfma_f32_16x16x32_bf16 v[16:19], v[182:185], v[218:221], v[16:19]
	v_mfma_f32_16x16x32_bf16 v[8:11], v[174:177], v[226:229], v[8:11]
	v_mfma_f32_16x16x32_bf16 v[0:3], v[182:185], v[226:229], v[0:3]
	s_barrier
	s_add_i32 s54, s54, 2
	s_add_u32 s0, s0, 0x100
	s_addc_u32 s1, s1, 0
	s_add_u32 s52, s52, 0x100
	s_addc_u32 s53, s53, 0
	s_cmp_gt_u32 s54, 13
	s_cbranch_scc0 .LBB0_253
	s_and_b64 vcc, exec, s[8:9]
	s_cbranch_vccz .LBB0_256
	s_barrier

.LBB0_360:
	s_add_u32 s0, s4, 0x100
	s_addc_u32 s1, s5, 0
	s_add_i32 s45, 0, 0x10000
	s_cmp_eq_u32 s44, 40
	s_cselect_b32 s9, s39, s1
	s_cselect_b32 s8, s38, s0
	v_add_u32_e32 v146, s45, v168
	s_cselect_b32 s3, s41, s43
	s_cselect_b32 s2, s40, s42
	s_add_i32 s62, 0, 0x14000
	ds_read_b128 v[128:131], v146
	ds_read_b128 v[132:135], v146 offset:1024
	ds_read_b128 v[158:161], v146 offset:2048
	ds_read_b128 v[162:165], v146 offset:3072
	v_add_u32_e32 v146, s62, v168
	ds_read_b128 v[170:173], v146
	ds_read_b128 v[174:177], v146 offset:1024
	ds_read_b128 v[178:181], v146 offset:2048
	ds_read_b128 v[182:185], v146 offset:3072
	v_lshl_add_u64 v[146:147], s[4:5], 0, v[142:143]
	s_add_i32 m0, s50, 0xc000
	ds_read_b128 v[186:189], v169
	ds_read_b128 v[190:193], v169 offset:1024
	ds_read_b128 v[194:197], v169 offset:2048
	ds_read_b128 v[198:201], v169 offset:3072
	ds_read_b128 v[202:205], v169 offset:4096
	ds_read_b128 v[218:221], v169 offset:5120
	ds_read_b128 v[222:225], v169 offset:6144
	ds_read_b128 v[226:229], v169 offset:7168
	global_load_lds_dwordx4 v[146:147], off
	v_lshl_add_u64 v[146:147], s[4:5], 0, v[144:145]
	s_add_i32 m0, s50, 0xe000
	s_nop 0
	global_load_lds_dwordx4 v[146:147], off
	s_waitcnt vmcnt(8)
	s_waitcnt lgkmcnt(0)
	s_barrier
	s_waitcnt lgkmcnt(0)
	v_mfma_f32_16x16x32_bf16 v[124:127], v[128:131], v[186:189], v[124:127]
	v_mfma_f32_16x16x32_bf16 v[120:123], v[158:161], v[186:189], v[120:123]
	v_mfma_f32_16x16x32_bf16 v[108:111], v[128:131], v[194:197], v[108:111]
	v_mfma_f32_16x16x32_bf16 v[104:107], v[158:161], v[194:197], v[104:107]
	v_mfma_f32_16x16x32_bf16 v[92:95], v[128:131], v[202:205], v[92:95]
	v_mfma_f32_16x16x32_bf16 v[88:91], v[158:161], v[202:205], v[88:91]
	v_mfma_f32_16x16x32_bf16 v[76:79], v[128:131], v[222:225], v[76:79]
	v_mfma_f32_16x16x32_bf16 v[72:75], v[158:161], v[222:225], v[72:75]
	v_mfma_f32_16x16x32_bf16 v[124:127], v[132:135], v[190:193], v[124:127]
	v_mfma_f32_16x16x32_bf16 v[120:123], v[162:165], v[190:193], v[120:123]
	v_mfma_f32_16x16x32_bf16 v[108:111], v[132:135], v[198:201], v[108:111]
	v_mfma_f32_16x16x32_bf16 v[104:107], v[162:165], v[198:201], v[104:107]
	v_mfma_f32_16x16x32_bf16 v[92:95], v[132:135], v[218:221], v[92:95]
	v_mfma_f32_16x16x32_bf16 v[88:91], v[162:165], v[218:221], v[88:91]
	v_mfma_f32_16x16x32_bf16 v[76:79], v[132:135], v[226:229], v[76:79]
	v_mfma_f32_16x16x32_bf16 v[72:75], v[162:165], v[226:229], v[72:75]
	v_mfma_f32_16x16x32_bf16 v[116:119], v[170:173], v[186:189], v[116:119]
	v_mfma_f32_16x16x32_bf16 v[112:115], v[178:181], v[186:189], v[112:115]
	v_mfma_f32_16x16x32_bf16 v[100:103], v[170:173], v[194:197], v[100:103]
	v_mfma_f32_16x16x32_bf16 v[96:99], v[178:181], v[194:197], v[96:99]
	v_mfma_f32_16x16x32_bf16 v[84:87], v[170:173], v[202:205], v[84:87]
	v_mfma_f32_16x16x32_bf16 v[80:83], v[178:181], v[202:205], v[80:83]
	v_mfma_f32_16x16x32_bf16 v[68:71], v[170:173], v[222:225], v[68:71]
	v_mfma_f32_16x16x32_bf16 v[64:67], v[178:181], v[222:225], v[64:67]
	v_mfma_f32_16x16x32_bf16 v[116:119], v[174:177], v[190:193], v[116:119]
	v_mfma_f32_16x16x32_bf16 v[112:115], v[182:185], v[190:193], v[112:115]
	v_mfma_f32_16x16x32_bf16 v[100:103], v[174:177], v[198:201], v[100:103]
	v_mfma_f32_16x16x32_bf16 v[96:99], v[182:185], v[198:201], v[96:99]
	v_mfma_f32_16x16x32_bf16 v[84:87], v[174:177], v[218:221], v[84:87]
	v_mfma_f32_16x16x32_bf16 v[80:83], v[182:185], v[218:221], v[80:83]
	v_mfma_f32_16x16x32_bf16 v[68:71], v[174:177], v[226:229], v[68:71]
	v_mfma_f32_16x16x32_bf16 v[64:67], v[182:185], v[226:229], v[64:67]
	s_barrier
	s_add_i32 s4, s45, s49
	v_lshl_add_u64 v[146:147], s[2:3], 0, v[148:149]
	s_mov_b32 m0, s4
	ds_read_b128 v[186:189], v169 offset:16384
	ds_read_b128 v[190:193], v169 offset:17408
	ds_read_b128 v[194:197], v169 offset:18432
	ds_read_b128 v[198:201], v169 offset:19456
	ds_read_b128 v[202:205], v169 offset:20480
	ds_read_b128 v[218:221], v169 offset:21504
	ds_read_b128 v[222:225], v169 offset:22528
	ds_read_b128 v[226:229], v169 offset:23552
	global_load_lds_dwordx4 v[146:147], off
	s_add_i32 m0, s4, 0x2000
	s_add_u32 s4, s2, 0xb0000
	v_lshl_add_u64 v[154:155], s[2:3], 0, v[136:137]
	s_addc_u32 s5, s3, 0
	s_add_i32 s45, s62, s49
	global_load_lds_dwordx4 v[154:155], off
	v_lshl_add_u64 v[156:157], s[4:5], 0, v[148:149]
	s_mov_b32 m0, s45
	v_lshl_add_u64 v[166:167], s[8:9], 0, v[138:139]
	global_load_lds_dwordx4 v[156:157], off
	v_lshl_add_u64 v[156:157], s[4:5], 0, v[136:137]
	s_add_i32 m0, s45, 0x2000
	s_nop 0
	global_load_lds_dwordx4 v[156:157], off
	v_lshl_add_u64 v[156:157], s[8:9], 0, v[140:141]
	s_mov_b32 m0, s50
	s_nop 0
	global_load_lds_dwordx4 v[156:157], off
	s_mov_b32 m0, s51
	s_nop 0
	global_load_lds_dwordx4 v[166:167], off
	s_waitcnt vmcnt(8)
	s_waitcnt lgkmcnt(0)
	s_barrier
	s_waitcnt lgkmcnt(0)
	v_mfma_f32_16x16x32_bf16 v[60:63], v[128:131], v[186:189], v[60:63]
	v_mfma_f32_16x16x32_bf16 v[56:59], v[158:161], v[186:189], v[56:59]
	v_mfma_f32_16x16x32_bf16 v[44:47], v[128:131], v[194:197], v[44:47]
	v_mfma_f32_16x16x32_bf16 v[40:43], v[158:161], v[194:197], v[40:43]
	v_mfma_f32_16x16x32_bf16 v[28:31], v[128:131], v[202:205], v[28:31]
	v_mfma_f32_16x16x32_bf16 v[24:27], v[158:161], v[202:205], v[24:27]
	v_mfma_f32_16x16x32_bf16 v[12:15], v[128:131], v[222:225], v[12:15]
	v_mfma_f32_16x16x32_bf16 v[8:11], v[158:161], v[222:225], v[8:11]
	v_mfma_f32_16x16x32_bf16 v[60:63], v[132:135], v[190:193], v[60:63]
	v_mfma_f32_16x16x32_bf16 v[56:59], v[162:165], v[190:193], v[56:59]
	v_mfma_f32_16x16x32_bf16 v[44:47], v[132:135], v[198:201], v[44:47]
	v_mfma_f32_16x16x32_bf16 v[40:43], v[162:165], v[198:201], v[40:43]
	v_mfma_f32_16x16x32_bf16 v[28:31], v[132:135], v[218:221], v[28:31]
	v_mfma_f32_16x16x32_bf16 v[24:27], v[162:165], v[218:221], v[24:27]
	v_mfma_f32_16x16x32_bf16 v[12:15], v[132:135], v[226:229], v[12:15]
	v_mfma_f32_16x16x32_bf16 v[8:11], v[162:165], v[226:229], v[8:11]
	v_mfma_f32_16x16x32_bf16 v[52:55], v[170:173], v[186:189], v[52:55]
	v_mfma_f32_16x16x32_bf16 v[48:51], v[178:181], v[186:189], v[48:51]
	v_mfma_f32_16x16x32_bf16 v[36:39], v[170:173], v[194:197], v[36:39]
	v_mfma_f32_16x16x32_bf16 v[32:35], v[178:181], v[194:197], v[32:35]
	v_mfma_f32_16x16x32_bf16 v[20:23], v[170:173], v[202:205], v[20:23]
	v_mfma_f32_16x16x32_bf16 v[16:19], v[178:181], v[202:205], v[16:19]
	v_mfma_f32_16x16x32_bf16 v[4:7], v[170:173], v[222:225], v[4:7]
	v_mfma_f32_16x16x32_bf16 v[0:3], v[178:181], v[222:225], v[0:3]
	v_mfma_f32_16x16x32_bf16 v[52:55], v[174:177], v[190:193], v[52:55]
	v_mfma_f32_16x16x32_bf16 v[48:51], v[182:185], v[190:193], v[48:51]
	v_mfma_f32_16x16x32_bf16 v[36:39], v[174:177], v[198:201], v[36:39]
	v_mfma_f32_16x16x32_bf16 v[32:35], v[182:185], v[198:201], v[32:35]
	v_mfma_f32_16x16x32_bf16 v[20:23], v[174:177], v[218:221], v[20:23]
	v_mfma_f32_16x16x32_bf16 v[16:19], v[182:185], v[218:221], v[16:19]
	v_mfma_f32_16x16x32_bf16 v[4:7], v[174:177], v[226:229], v[4:7]
	v_mfma_f32_16x16x32_bf16 v[0:3], v[182:185], v[226:229], v[0:3]
	s_barrier
	s_add_i32 s45, 0, 0x18000
	v_add_u32_e32 v150, s45, v168
	s_add_i32 s62, 0, 0x1c000
	ds_read_b128 v[128:131], v150
	ds_read_b128 v[132:135], v150 offset:1024
	ds_read_b128 v[158:161], v150 offset:2048
	ds_read_b128 v[162:165], v150 offset:3072
	v_add_u32_e32 v150, s62, v168
	ds_read_b128 v[170:173], v150
	ds_read_b128 v[174:177], v150 offset:1024
	ds_read_b128 v[178:181], v150 offset:2048
	ds_read_b128 v[182:185], v150 offset:3072
	s_add_u32 s4, s8, 0xb0000
	s_addc_u32 s5, s9, 0
	s_mov_b32 m0, s52
	v_lshl_add_u64 v[212:213], s[4:5], 0, v[140:141]
	ds_read_b128 v[186:189], v169 offset:32768
	ds_read_b128 v[190:193], v169 offset:33792
	ds_read_b128 v[194:197], v169 offset:34816
	ds_read_b128 v[198:201], v169 offset:35840
	ds_read_b128 v[202:205], v169 offset:36864
	ds_read_b128 v[218:221], v169 offset:37888
	ds_read_b128 v[222:225], v169 offset:38912
	ds_read_b128 v[226:229], v169 offset:39936
	global_load_lds_dwordx4 v[212:213], off
	v_lshl_add_u64 v[212:213], s[4:5], 0, v[138:139]
	s_mov_b32 m0, s53
	s_nop 0
	global_load_lds_dwordx4 v[212:213], off
	s_waitcnt vmcnt(8)
	s_waitcnt lgkmcnt(0)
	s_barrier
	s_waitcnt lgkmcnt(0)
	v_mfma_f32_16x16x32_bf16 v[124:127], v[128:131], v[186:189], v[124:127]
	v_mfma_f32_16x16x32_bf16 v[120:123], v[158:161], v[186:189], v[120:123]
	v_mfma_f32_16x16x32_bf16 v[108:111], v[128:131], v[194:197], v[108:111]
	v_mfma_f32_16x16x32_bf16 v[104:107], v[158:161], v[194:197], v[104:107]
	v_mfma_f32_16x16x32_bf16 v[92:95], v[128:131], v[202:205], v[92:95]
	v_mfma_f32_16x16x32_bf16 v[88:91], v[158:161], v[202:205], v[88:91]
	v_mfma_f32_16x16x32_bf16 v[76:79], v[128:131], v[222:225], v[76:79]
	v_mfma_f32_16x16x32_bf16 v[72:75], v[158:161], v[222:225], v[72:75]
	v_mfma_f32_16x16x32_bf16 v[124:127], v[132:135], v[190:193], v[124:127]
	v_mfma_f32_16x16x32_bf16 v[120:123], v[162:165], v[190:193], v[120:123]
	v_mfma_f32_16x16x32_bf16 v[108:111], v[132:135], v[198:201], v[108:111]
	v_mfma_f32_16x16x32_bf16 v[104:107], v[162:165], v[198:201], v[104:107]
	v_mfma_f32_16x16x32_bf16 v[92:95], v[132:135], v[218:221], v[92:95]
	v_mfma_f32_16x16x32_bf16 v[88:91], v[162:165], v[218:221], v[88:91]
	v_mfma_f32_16x16x32_bf16 v[76:79], v[132:135], v[226:229], v[76:79]
	v_mfma_f32_16x16x32_bf16 v[72:75], v[162:165], v[226:229], v[72:75]
	v_mfma_f32_16x16x32_bf16 v[116:119], v[170:173], v[186:189], v[116:119]
	v_mfma_f32_16x16x32_bf16 v[112:115], v[178:181], v[186:189], v[112:115]
	v_mfma_f32_16x16x32_bf16 v[100:103], v[170:173], v[194:197], v[100:103]
	v_mfma_f32_16x16x32_bf16 v[96:99], v[178:181], v[194:197], v[96:99]
	v_mfma_f32_16x16x32_bf16 v[84:87], v[170:173], v[202:205], v[84:87]
	v_mfma_f32_16x16x32_bf16 v[80:83], v[178:181], v[202:205], v[80:83]
	v_mfma_f32_16x16x32_bf16 v[68:71], v[170:173], v[222:225], v[68:71]
	v_mfma_f32_16x16x32_bf16 v[64:67], v[178:181], v[222:225], v[64:67]
	v_mfma_f32_16x16x32_bf16 v[116:119], v[174:177], v[190:193], v[116:119]
	v_mfma_f32_16x16x32_bf16 v[112:115], v[182:185], v[190:193], v[112:115]
	v_mfma_f32_16x16x32_bf16 v[100:103], v[174:177], v[198:201], v[100:103]
	v_mfma_f32_16x16x32_bf16 v[96:99], v[182:185], v[198:201], v[96:99]
	v_mfma_f32_16x16x32_bf16 v[84:87], v[174:177], v[218:221], v[84:87]
	v_mfma_f32_16x16x32_bf16 v[80:83], v[182:185], v[218:221], v[80:83]
	v_mfma_f32_16x16x32_bf16 v[68:71], v[174:177], v[226:229], v[68:71]
	v_mfma_f32_16x16x32_bf16 v[64:67], v[182:185], v[226:229], v[64:67]
	s_barrier
	s_add_i32 s4, s45, s49
	v_lshl_add_u64 v[146:147], v[146:147], 0, s[28:29]
	s_mov_b32 m0, s4
	ds_read_b128 v[186:189], v169 offset:49152
	ds_read_b128 v[190:193], v169 offset:50176
	ds_read_b128 v[194:197], v169 offset:51200
	ds_read_b128 v[198:201], v169 offset:52224
	ds_read_b128 v[202:205], v169 offset:53248
	ds_read_b128 v[218:221], v169 offset:54272
	ds_read_b128 v[222:225], v169 offset:55296
	ds_read_b128 v[226:229], v169 offset:56320
	global_load_lds_dwordx4 v[146:147], off
	s_add_i32 m0, s4, 0x2000
	s_add_u32 s2, s2, 0xb0080
	v_lshl_add_u64 v[146:147], v[154:155], 0, s[28:29]
	s_addc_u32 s3, s3, 0
	s_add_i32 s4, s62, s49
	global_load_lds_dwordx4 v[146:147], off
	v_lshl_add_u64 v[146:147], s[2:3], 0, v[148:149]
	s_mov_b32 m0, s4
	s_nop 0
	global_load_lds_dwordx4 v[146:147], off
	v_lshl_add_u64 v[146:147], s[2:3], 0, v[136:137]
	s_add_i32 m0, s4, 0x2000
	s_nop 0
	global_load_lds_dwordx4 v[146:147], off
	v_lshl_add_u64 v[146:147], v[156:157], 0, s[28:29]
	s_mov_b32 m0, s57
	s_nop 0
	global_load_lds_dwordx4 v[146:147], off
	v_lshl_add_u64 v[146:147], v[166:167], 0, s[28:29]
	s_mov_b32 m0, s58
	s_nop 0
	global_load_lds_dwordx4 v[146:147], off
	s_waitcnt vmcnt(8)
	s_waitcnt lgkmcnt(0)
	s_barrier
	s_waitcnt lgkmcnt(0)
	v_mfma_f32_16x16x32_bf16 v[60:63], v[128:131], v[186:189], v[60:63]
	v_mfma_f32_16x16x32_bf16 v[56:59], v[158:161], v[186:189], v[56:59]
	v_mfma_f32_16x16x32_bf16 v[44:47], v[128:131], v[194:197], v[44:47]
	v_mfma_f32_16x16x32_bf16 v[40:43], v[158:161], v[194:197], v[40:43]
	v_mfma_f32_16x16x32_bf16 v[28:31], v[128:131], v[202:205], v[28:31]
	v_mfma_f32_16x16x32_bf16 v[24:27], v[158:161], v[202:205], v[24:27]
	v_mfma_f32_16x16x32_bf16 v[12:15], v[128:131], v[222:225], v[12:15]
	v_mfma_f32_16x16x32_bf16 v[8:11], v[158:161], v[222:225], v[8:11]
	v_mfma_f32_16x16x32_bf16 v[60:63], v[132:135], v[190:193], v[60:63]
	v_mfma_f32_16x16x32_bf16 v[56:59], v[162:165], v[190:193], v[56:59]
	v_mfma_f32_16x16x32_bf16 v[44:47], v[132:135], v[198:201], v[44:47]
	v_mfma_f32_16x16x32_bf16 v[40:43], v[162:165], v[198:201], v[40:43]
	v_mfma_f32_16x16x32_bf16 v[28:31], v[132:135], v[218:221], v[28:31]
	v_mfma_f32_16x16x32_bf16 v[24:27], v[162:165], v[218:221], v[24:27]
	v_mfma_f32_16x16x32_bf16 v[12:15], v[132:135], v[226:229], v[12:15]
	v_mfma_f32_16x16x32_bf16 v[8:11], v[162:165], v[226:229], v[8:11]
	v_mfma_f32_16x16x32_bf16 v[52:55], v[170:173], v[186:189], v[52:55]
	v_mfma_f32_16x16x32_bf16 v[48:51], v[178:181], v[186:189], v[48:51]
	v_mfma_f32_16x16x32_bf16 v[36:39], v[170:173], v[194:197], v[36:39]
	v_mfma_f32_16x16x32_bf16 v[32:35], v[178:181], v[194:197], v[32:35]
	v_mfma_f32_16x16x32_bf16 v[20:23], v[170:173], v[202:205], v[20:23]
	v_mfma_f32_16x16x32_bf16 v[16:19], v[178:181], v[202:205], v[16:19]
	v_mfma_f32_16x16x32_bf16 v[4:7], v[170:173], v[222:225], v[4:7]
	v_mfma_f32_16x16x32_bf16 v[0:3], v[178:181], v[222:225], v[0:3]
	v_mfma_f32_16x16x32_bf16 v[52:55], v[174:177], v[190:193], v[52:55]
	v_mfma_f32_16x16x32_bf16 v[48:51], v[182:185], v[190:193], v[48:51]
	v_mfma_f32_16x16x32_bf16 v[36:39], v[174:177], v[198:201], v[36:39]
	v_mfma_f32_16x16x32_bf16 v[32:35], v[182:185], v[198:201], v[32:35]
	v_mfma_f32_16x16x32_bf16 v[20:23], v[174:177], v[218:221], v[20:23]
	v_mfma_f32_16x16x32_bf16 v[16:19], v[182:185], v[218:221], v[16:19]
	v_mfma_f32_16x16x32_bf16 v[4:7], v[174:177], v[226:229], v[4:7]
	v_mfma_f32_16x16x32_bf16 v[0:3], v[182:185], v[226:229], v[0:3]
	s_barrier
	s_add_i32 s44, s44, 2
	s_add_u32 s42, s42, 0x100
	s_addc_u32 s43, s43, 0
	s_cmp_gt_u32 s44, 41
	s_mov_b64 s[4:5], s[0:1]
	s_cbranch_scc0 .LBB0_360
	s_and_b64 vcc, exec, s[30:31]
	s_cbranch_vccz .LBB0_363
	s_barrier

.LBB0_588:
	s_add_u32 s12, s10, 0xfffc0080
	s_addc_u32 s13, s11, -1
	s_add_i32 s44, 0, 0x10000
	s_cmp_eq_u32 s43, 12
	s_cselect_b32 s15, s9, s13
	s_cselect_b32 s14, s16, s12
	v_add_u32_e32 v146, s44, v144
	s_cselect_b32 s13, s17, s42
	s_cselect_b32 s12, s35, s37
	s_add_i32 s46, 0, 0x14000
	ds_read_b128 v[140:143], v146
	ds_read_b128 v[158:161], v146 offset:1024
	ds_read_b128 v[162:165], v146 offset:2048
	ds_read_b128 v[166:169], v146 offset:3072
	v_add_u32_e32 v146, s46, v144
	ds_read_b128 v[174:177], v146
	ds_read_b128 v[178:181], v146 offset:1024
	ds_read_b128 v[182:185], v146 offset:2048
	ds_read_b128 v[186:189], v146 offset:3072
	v_lshl_add_u64 v[146:147], s[10:11], 0, v[136:137]
	s_add_i32 m0, s57, 0xc000
	ds_read_b128 v[190:193], v145
	ds_read_b128 v[194:197], v145 offset:1024
	ds_read_b128 v[198:201], v145 offset:2048
	ds_read_b128 v[202:205], v145 offset:3072
	ds_read_b128 v[218:221], v145 offset:4096
	ds_read_b128 v[222:225], v145 offset:5120
	ds_read_b128 v[226:229], v145 offset:6144
	ds_read_b128 v[230:233], v145 offset:7168
	global_load_lds_dwordx4 v[146:147], off
	v_lshl_add_u64 v[146:147], s[10:11], 0, v[138:139]
	s_add_i32 m0, s57, 0xe000
	s_nop 0
	global_load_lds_dwordx4 v[146:147], off
	s_waitcnt vmcnt(8)
	s_waitcnt lgkmcnt(0)
	s_barrier
	s_waitcnt lgkmcnt(0)
	v_mfma_f32_16x16x32_bf16 v[124:127], v[140:143], v[190:193], v[124:127]
	v_mfma_f32_16x16x32_bf16 v[120:123], v[162:165], v[190:193], v[120:123]
	v_mfma_f32_16x16x32_bf16 v[108:111], v[140:143], v[198:201], v[108:111]
	v_mfma_f32_16x16x32_bf16 v[104:107], v[162:165], v[198:201], v[104:107]
	v_mfma_f32_16x16x32_bf16 v[92:95], v[140:143], v[218:221], v[92:95]
	v_mfma_f32_16x16x32_bf16 v[88:91], v[162:165], v[218:221], v[88:91]
	v_mfma_f32_16x16x32_bf16 v[76:79], v[140:143], v[226:229], v[76:79]
	v_mfma_f32_16x16x32_bf16 v[72:75], v[162:165], v[226:229], v[72:75]
	v_mfma_f32_16x16x32_bf16 v[124:127], v[158:161], v[194:197], v[124:127]
	v_mfma_f32_16x16x32_bf16 v[120:123], v[166:169], v[194:197], v[120:123]
	v_mfma_f32_16x16x32_bf16 v[108:111], v[158:161], v[202:205], v[108:111]
	v_mfma_f32_16x16x32_bf16 v[104:107], v[166:169], v[202:205], v[104:107]
	v_mfma_f32_16x16x32_bf16 v[92:95], v[158:161], v[222:225], v[92:95]
	v_mfma_f32_16x16x32_bf16 v[88:91], v[166:169], v[222:225], v[88:91]
	v_mfma_f32_16x16x32_bf16 v[76:79], v[158:161], v[230:233], v[76:79]
	v_mfma_f32_16x16x32_bf16 v[72:75], v[166:169], v[230:233], v[72:75]
	v_mfma_f32_16x16x32_bf16 v[116:119], v[174:177], v[190:193], v[116:119]
	v_mfma_f32_16x16x32_bf16 v[112:115], v[182:185], v[190:193], v[112:115]
	v_mfma_f32_16x16x32_bf16 v[100:103], v[174:177], v[198:201], v[100:103]
	v_mfma_f32_16x16x32_bf16 v[96:99], v[182:185], v[198:201], v[96:99]
	v_mfma_f32_16x16x32_bf16 v[84:87], v[174:177], v[218:221], v[84:87]
	v_mfma_f32_16x16x32_bf16 v[80:83], v[182:185], v[218:221], v[80:83]
	v_mfma_f32_16x16x32_bf16 v[68:71], v[174:177], v[226:229], v[68:71]
	v_mfma_f32_16x16x32_bf16 v[64:67], v[182:185], v[226:229], v[64:67]
	v_mfma_f32_16x16x32_bf16 v[116:119], v[178:181], v[194:197], v[116:119]
	v_mfma_f32_16x16x32_bf16 v[112:115], v[186:189], v[194:197], v[112:115]
	v_mfma_f32_16x16x32_bf16 v[100:103], v[178:181], v[202:205], v[100:103]
	v_mfma_f32_16x16x32_bf16 v[96:99], v[186:189], v[202:205], v[96:99]
	v_mfma_f32_16x16x32_bf16 v[84:87], v[178:181], v[222:225], v[84:87]
	v_mfma_f32_16x16x32_bf16 v[80:83], v[186:189], v[222:225], v[80:83]
	v_mfma_f32_16x16x32_bf16 v[68:71], v[178:181], v[230:233], v[68:71]
	v_mfma_f32_16x16x32_bf16 v[64:67], v[186:189], v[230:233], v[64:67]
	s_barrier
	s_add_i32 s44, s44, s56
	v_lshl_add_u64 v[146:147], s[12:13], 0, v[132:133]
	s_mov_b32 m0, s44
	ds_read_b128 v[190:193], v145 offset:16384
	ds_read_b128 v[194:197], v145 offset:17408
	ds_read_b128 v[198:201], v145 offset:18432
	ds_read_b128 v[202:205], v145 offset:19456
	ds_read_b128 v[218:221], v145 offset:20480
	ds_read_b128 v[222:225], v145 offset:21504
	ds_read_b128 v[226:229], v145 offset:22528
	ds_read_b128 v[230:233], v145 offset:23552
	global_load_lds_dwordx4 v[146:147], off
	s_add_i32 m0, s44, 0x2000
	s_add_u32 s44, s12, 0x40000
	v_lshl_add_u64 v[154:155], s[12:13], 0, v[128:129]
	s_addc_u32 s45, s13, 0
	s_add_i32 s46, s46, s56
	global_load_lds_dwordx4 v[154:155], off
	v_lshl_add_u64 v[156:157], s[44:45], 0, v[132:133]
	s_mov_b32 m0, s46
	v_lshl_add_u64 v[170:171], s[14:15], 0, v[130:131]
	global_load_lds_dwordx4 v[156:157], off
	v_lshl_add_u64 v[156:157], s[44:45], 0, v[128:129]
	s_add_i32 m0, s46, 0x2000
	s_nop 0
	global_load_lds_dwordx4 v[156:157], off
	v_lshl_add_u64 v[156:157], s[14:15], 0, v[134:135]
	s_mov_b32 m0, s57
	s_nop 0
	global_load_lds_dwordx4 v[156:157], off
	s_mov_b32 m0, s58
	s_nop 0
	global_load_lds_dwordx4 v[170:171], off
	s_waitcnt vmcnt(8)
	s_waitcnt lgkmcnt(0)
	s_barrier
	s_waitcnt lgkmcnt(0)
	v_mfma_f32_16x16x32_bf16 v[60:63], v[140:143], v[190:193], v[60:63]
	v_mfma_f32_16x16x32_bf16 v[56:59], v[162:165], v[190:193], v[56:59]
	v_mfma_f32_16x16x32_bf16 v[44:47], v[140:143], v[198:201], v[44:47]
	v_mfma_f32_16x16x32_bf16 v[40:43], v[162:165], v[198:201], v[40:43]
	v_mfma_f32_16x16x32_bf16 v[28:31], v[140:143], v[218:221], v[28:31]
	v_mfma_f32_16x16x32_bf16 v[24:27], v[162:165], v[218:221], v[24:27]
	v_mfma_f32_16x16x32_bf16 v[12:15], v[140:143], v[226:229], v[12:15]
	v_mfma_f32_16x16x32_bf16 v[8:11], v[162:165], v[226:229], v[8:11]
	v_mfma_f32_16x16x32_bf16 v[60:63], v[158:161], v[194:197], v[60:63]
	v_mfma_f32_16x16x32_bf16 v[56:59], v[166:169], v[194:197], v[56:59]
	v_mfma_f32_16x16x32_bf16 v[44:47], v[158:161], v[202:205], v[44:47]
	v_mfma_f32_16x16x32_bf16 v[40:43], v[166:169], v[202:205], v[40:43]
	v_mfma_f32_16x16x32_bf16 v[28:31], v[158:161], v[222:225], v[28:31]
	v_mfma_f32_16x16x32_bf16 v[24:27], v[166:169], v[222:225], v[24:27]
	v_mfma_f32_16x16x32_bf16 v[12:15], v[158:161], v[230:233], v[12:15]
	v_mfma_f32_16x16x32_bf16 v[8:11], v[166:169], v[230:233], v[8:11]
	v_mfma_f32_16x16x32_bf16 v[52:55], v[174:177], v[190:193], v[52:55]
	v_mfma_f32_16x16x32_bf16 v[48:51], v[182:185], v[190:193], v[48:51]
	v_mfma_f32_16x16x32_bf16 v[36:39], v[174:177], v[198:201], v[36:39]
	v_mfma_f32_16x16x32_bf16 v[32:35], v[182:185], v[198:201], v[32:35]
	v_mfma_f32_16x16x32_bf16 v[20:23], v[174:177], v[218:221], v[20:23]
	v_mfma_f32_16x16x32_bf16 v[16:19], v[182:185], v[218:221], v[16:19]
	v_mfma_f32_16x16x32_bf16 v[4:7], v[174:177], v[226:229], v[4:7]
	v_mfma_f32_16x16x32_bf16 v[0:3], v[182:185], v[226:229], v[0:3]
	v_mfma_f32_16x16x32_bf16 v[52:55], v[178:181], v[194:197], v[52:55]
	v_mfma_f32_16x16x32_bf16 v[48:51], v[186:189], v[194:197], v[48:51]
	v_mfma_f32_16x16x32_bf16 v[36:39], v[178:181], v[202:205], v[36:39]
	v_mfma_f32_16x16x32_bf16 v[32:35], v[186:189], v[202:205], v[32:35]
	v_mfma_f32_16x16x32_bf16 v[20:23], v[178:181], v[222:225], v[20:23]
	v_mfma_f32_16x16x32_bf16 v[16:19], v[186:189], v[222:225], v[16:19]
	v_mfma_f32_16x16x32_bf16 v[4:7], v[178:181], v[230:233], v[4:7]
	v_mfma_f32_16x16x32_bf16 v[0:3], v[186:189], v[230:233], v[0:3]
	s_barrier
	s_add_i32 s44, 0, 0x18000
	v_add_u32_e32 v148, s44, v144
	s_add_i32 s45, 0, 0x1c000
	ds_read_b128 v[140:143], v148
	ds_read_b128 v[158:161], v148 offset:1024
	ds_read_b128 v[162:165], v148 offset:2048
	ds_read_b128 v[166:169], v148 offset:3072
	v_add_u32_e32 v148, s45, v144
	ds_read_b128 v[174:177], v148
	ds_read_b128 v[178:181], v148 offset:1024
	ds_read_b128 v[182:185], v148 offset:2048
	ds_read_b128 v[186:189], v148 offset:3072
	s_add_u32 s14, s14, 0x40000
	s_addc_u32 s15, s15, 0
	s_mov_b32 m0, s59
	v_lshl_add_u64 v[212:213], s[14:15], 0, v[134:135]
	ds_read_b128 v[190:193], v145 offset:32768
	ds_read_b128 v[194:197], v145 offset:33792
	ds_read_b128 v[198:201], v145 offset:34816
	ds_read_b128 v[202:205], v145 offset:35840
	ds_read_b128 v[218:221], v145 offset:36864
	ds_read_b128 v[222:225], v145 offset:37888
	ds_read_b128 v[226:229], v145 offset:38912
	ds_read_b128 v[230:233], v145 offset:39936
	global_load_lds_dwordx4 v[212:213], off
	v_lshl_add_u64 v[212:213], s[14:15], 0, v[130:131]
	s_mov_b32 m0, s60
	s_nop 0
	global_load_lds_dwordx4 v[212:213], off
	s_waitcnt vmcnt(8)
	s_waitcnt lgkmcnt(0)
	s_barrier
	s_waitcnt lgkmcnt(0)
	v_mfma_f32_16x16x32_bf16 v[124:127], v[140:143], v[190:193], v[124:127]
	v_mfma_f32_16x16x32_bf16 v[120:123], v[162:165], v[190:193], v[120:123]
	v_mfma_f32_16x16x32_bf16 v[108:111], v[140:143], v[198:201], v[108:111]
	v_mfma_f32_16x16x32_bf16 v[104:107], v[162:165], v[198:201], v[104:107]
	v_mfma_f32_16x16x32_bf16 v[92:95], v[140:143], v[218:221], v[92:95]
	v_mfma_f32_16x16x32_bf16 v[88:91], v[162:165], v[218:221], v[88:91]
	v_mfma_f32_16x16x32_bf16 v[76:79], v[140:143], v[226:229], v[76:79]
	v_mfma_f32_16x16x32_bf16 v[72:75], v[162:165], v[226:229], v[72:75]
	v_mfma_f32_16x16x32_bf16 v[124:127], v[158:161], v[194:197], v[124:127]
	v_mfma_f32_16x16x32_bf16 v[120:123], v[166:169], v[194:197], v[120:123]
	v_mfma_f32_16x16x32_bf16 v[108:111], v[158:161], v[202:205], v[108:111]
	v_mfma_f32_16x16x32_bf16 v[104:107], v[166:169], v[202:205], v[104:107]
	v_mfma_f32_16x16x32_bf16 v[92:95], v[158:161], v[222:225], v[92:95]
	v_mfma_f32_16x16x32_bf16 v[88:91], v[166:169], v[222:225], v[88:91]
	v_mfma_f32_16x16x32_bf16 v[76:79], v[158:161], v[230:233], v[76:79]
	v_mfma_f32_16x16x32_bf16 v[72:75], v[166:169], v[230:233], v[72:75]
	v_mfma_f32_16x16x32_bf16 v[116:119], v[174:177], v[190:193], v[116:119]
	v_mfma_f32_16x16x32_bf16 v[112:115], v[182:185], v[190:193], v[112:115]
	v_mfma_f32_16x16x32_bf16 v[100:103], v[174:177], v[198:201], v[100:103]
	v_mfma_f32_16x16x32_bf16 v[96:99], v[182:185], v[198:201], v[96:99]
	v_mfma_f32_16x16x32_bf16 v[84:87], v[174:177], v[218:221], v[84:87]
	v_mfma_f32_16x16x32_bf16 v[80:83], v[182:185], v[218:221], v[80:83]
	v_mfma_f32_16x16x32_bf16 v[68:71], v[174:177], v[226:229], v[68:71]
	v_mfma_f32_16x16x32_bf16 v[64:67], v[182:185], v[226:229], v[64:67]
	v_mfma_f32_16x16x32_bf16 v[116:119], v[178:181], v[194:197], v[116:119]
	v_mfma_f32_16x16x32_bf16 v[112:115], v[186:189], v[194:197], v[112:115]
	v_mfma_f32_16x16x32_bf16 v[100:103], v[178:181], v[202:205], v[100:103]
	v_mfma_f32_16x16x32_bf16 v[96:99], v[186:189], v[202:205], v[96:99]
	v_mfma_f32_16x16x32_bf16 v[84:87], v[178:181], v[222:225], v[84:87]
	v_mfma_f32_16x16x32_bf16 v[80:83], v[186:189], v[222:225], v[80:83]
	v_mfma_f32_16x16x32_bf16 v[68:71], v[178:181], v[230:233], v[68:71]
	v_mfma_f32_16x16x32_bf16 v[64:67], v[186:189], v[230:233], v[64:67]
	s_barrier
	s_add_i32 s14, s44, s56
	v_lshl_add_u64 v[146:147], v[146:147], 0, s[28:29]
	s_mov_b32 m0, s14
	ds_read_b128 v[190:193], v145 offset:49152
	ds_read_b128 v[194:197], v145 offset:50176
	ds_read_b128 v[198:201], v145 offset:51200
	ds_read_b128 v[202:205], v145 offset:52224
	ds_read_b128 v[218:221], v145 offset:53248
	ds_read_b128 v[222:225], v145 offset:54272
	ds_read_b128 v[226:229], v145 offset:55296
	ds_read_b128 v[230:233], v145 offset:56320
	global_load_lds_dwordx4 v[146:147], off
	s_add_i32 m0, s14, 0x2000
	s_add_u32 s12, s12, 0x40080
	v_lshl_add_u64 v[146:147], v[154:155], 0, s[28:29]
	s_addc_u32 s13, s13, 0
	s_add_i32 s14, s45, s56
	global_load_lds_dwordx4 v[146:147], off
	v_lshl_add_u64 v[146:147], s[12:13], 0, v[132:133]
	s_mov_b32 m0, s14
	s_nop 0
	global_load_lds_dwordx4 v[146:147], off
	v_lshl_add_u64 v[146:147], s[12:13], 0, v[128:129]
	s_add_i32 m0, s14, 0x2000
	s_nop 0
	global_load_lds_dwordx4 v[146:147], off
	v_lshl_add_u64 v[146:147], v[156:157], 0, s[28:29]
	s_mov_b32 m0, s72
	s_nop 0
	global_load_lds_dwordx4 v[146:147], off
	v_lshl_add_u64 v[146:147], v[170:171], 0, s[28:29]
	s_mov_b32 m0, s73
	s_nop 0
	global_load_lds_dwordx4 v[146:147], off
	s_waitcnt vmcnt(8)
	s_waitcnt lgkmcnt(0)
	s_barrier
	s_waitcnt lgkmcnt(0)
	v_mfma_f32_16x16x32_bf16 v[60:63], v[140:143], v[190:193], v[60:63]
	v_mfma_f32_16x16x32_bf16 v[56:59], v[162:165], v[190:193], v[56:59]
	v_mfma_f32_16x16x32_bf16 v[44:47], v[140:143], v[198:201], v[44:47]
	v_mfma_f32_16x16x32_bf16 v[40:43], v[162:165], v[198:201], v[40:43]
	v_mfma_f32_16x16x32_bf16 v[28:31], v[140:143], v[218:221], v[28:31]
	v_mfma_f32_16x16x32_bf16 v[24:27], v[162:165], v[218:221], v[24:27]
	v_mfma_f32_16x16x32_bf16 v[12:15], v[140:143], v[226:229], v[12:15]
	v_mfma_f32_16x16x32_bf16 v[8:11], v[162:165], v[226:229], v[8:11]
	v_mfma_f32_16x16x32_bf16 v[60:63], v[158:161], v[194:197], v[60:63]
	v_mfma_f32_16x16x32_bf16 v[56:59], v[166:169], v[194:197], v[56:59]
	v_mfma_f32_16x16x32_bf16 v[44:47], v[158:161], v[202:205], v[44:47]
	v_mfma_f32_16x16x32_bf16 v[40:43], v[166:169], v[202:205], v[40:43]
	v_mfma_f32_16x16x32_bf16 v[28:31], v[158:161], v[222:225], v[28:31]
	v_mfma_f32_16x16x32_bf16 v[24:27], v[166:169], v[222:225], v[24:27]
	v_mfma_f32_16x16x32_bf16 v[12:15], v[158:161], v[230:233], v[12:15]
	v_mfma_f32_16x16x32_bf16 v[8:11], v[166:169], v[230:233], v[8:11]
	v_mfma_f32_16x16x32_bf16 v[52:55], v[174:177], v[190:193], v[52:55]
	v_mfma_f32_16x16x32_bf16 v[48:51], v[182:185], v[190:193], v[48:51]
	v_mfma_f32_16x16x32_bf16 v[36:39], v[174:177], v[198:201], v[36:39]
	v_mfma_f32_16x16x32_bf16 v[32:35], v[182:185], v[198:201], v[32:35]
	v_mfma_f32_16x16x32_bf16 v[20:23], v[174:177], v[218:221], v[20:23]
	v_mfma_f32_16x16x32_bf16 v[16:19], v[182:185], v[218:221], v[16:19]
	v_mfma_f32_16x16x32_bf16 v[4:7], v[174:177], v[226:229], v[4:7]
	v_mfma_f32_16x16x32_bf16 v[0:3], v[182:185], v[226:229], v[0:3]
	v_mfma_f32_16x16x32_bf16 v[52:55], v[178:181], v[194:197], v[52:55]
	v_mfma_f32_16x16x32_bf16 v[48:51], v[186:189], v[194:197], v[48:51]
	v_mfma_f32_16x16x32_bf16 v[36:39], v[178:181], v[202:205], v[36:39]
	v_mfma_f32_16x16x32_bf16 v[32:35], v[186:189], v[202:205], v[32:35]
	v_mfma_f32_16x16x32_bf16 v[20:23], v[178:181], v[222:225], v[20:23]
	v_mfma_f32_16x16x32_bf16 v[16:19], v[186:189], v[222:225], v[16:19]
	v_mfma_f32_16x16x32_bf16 v[4:7], v[178:181], v[230:233], v[4:7]
	v_mfma_f32_16x16x32_bf16 v[0:3], v[186:189], v[230:233], v[0:3]
	s_barrier
	s_add_i32 s43, s43, 2
	s_add_u32 s10, s10, 0x100
	s_addc_u32 s11, s11, 0
	s_add_u32 s37, s37, 0x100
	s_addc_u32 s42, s42, 0
	s_cmp_gt_u32 s43, 13
	s_cbranch_scc0 .LBB0_588
	s_and_b64 vcc, exec, s[26:27]
	s_cbranch_vccz .LBB0_591
	s_barrier

.LBB0_764:
	s_add_u32 s30, s26, 0xfffc0080
	s_addc_u32 s31, s27, -1
	s_add_i32 s53, 0, 0x10000
	s_cmp_eq_u32 s52, 12
	s_cselect_b32 s35, s21, s31
	s_cselect_b32 s34, s48, s30
	s_cselect_b32 s31, s19, s51
	s_cselect_b32 s30, s49, s50
	s_add_i32 s56, 0, 0x14000
	v_add_u32_e32 v140, s53, v173
	v_add_u32_e32 v150, s56, v173
	ds_read_b128 v[128:131], v140
	ds_read_b128 v[132:135], v140 offset:1024
	ds_read_b128 v[136:139], v140 offset:2048
	ds_read_b128 v[140:143], v140 offset:3072
	ds_read_b128 v[164:167], v150
	ds_read_b128 v[168:171], v150 offset:1024
	ds_read_b128 v[176:179], v150 offset:2048
	ds_read_b128 v[180:183], v150 offset:3072
	v_lshl_add_u64 v[154:155], s[26:27], 0, v[160:161]
	s_add_i32 m0, s37, 0xc000
	ds_read_b128 v[184:187], v174
	ds_read_b128 v[188:191], v174 offset:1024
	ds_read_b128 v[192:195], v174 offset:2048
	ds_read_b128 v[196:199], v174 offset:3072
	ds_read_b128 v[200:203], v174 offset:4096
	ds_read_b128 v[218:221], v174 offset:5120
	ds_read_b128 v[222:225], v174 offset:6144
	ds_read_b128 v[226:229], v174 offset:7168
	global_load_lds_dwordx4 v[154:155], off
	v_lshl_add_u64 v[154:155], s[26:27], 0, v[162:163]
	s_add_i32 m0, s37, 0xe000
	s_nop 0
	global_load_lds_dwordx4 v[154:155], off
	s_waitcnt vmcnt(8)
	s_waitcnt lgkmcnt(0)
	s_barrier
	s_waitcnt lgkmcnt(0)
	v_mfma_f32_16x16x32_bf16 v[124:127], v[128:131], v[184:187], v[124:127]
	v_mfma_f32_16x16x32_bf16 v[92:95], v[136:139], v[184:187], v[92:95]
	v_mfma_f32_16x16x32_bf16 v[120:123], v[128:131], v[192:195], v[120:123]
	v_mfma_f32_16x16x32_bf16 v[88:91], v[136:139], v[192:195], v[88:91]
	v_mfma_f32_16x16x32_bf16 v[116:119], v[128:131], v[200:203], v[116:119]
	v_mfma_f32_16x16x32_bf16 v[84:87], v[136:139], v[200:203], v[84:87]
	v_mfma_f32_16x16x32_bf16 v[112:115], v[128:131], v[222:225], v[112:115]
	v_mfma_f32_16x16x32_bf16 v[80:83], v[136:139], v[222:225], v[80:83]
	v_mfma_f32_16x16x32_bf16 v[124:127], v[132:135], v[188:191], v[124:127]
	v_mfma_f32_16x16x32_bf16 v[92:95], v[140:143], v[188:191], v[92:95]
	v_mfma_f32_16x16x32_bf16 v[120:123], v[132:135], v[196:199], v[120:123]
	v_mfma_f32_16x16x32_bf16 v[88:91], v[140:143], v[196:199], v[88:91]
	v_mfma_f32_16x16x32_bf16 v[116:119], v[132:135], v[218:221], v[116:119]
	v_mfma_f32_16x16x32_bf16 v[84:87], v[140:143], v[218:221], v[84:87]
	v_mfma_f32_16x16x32_bf16 v[112:115], v[132:135], v[226:229], v[112:115]
	v_mfma_f32_16x16x32_bf16 v[80:83], v[140:143], v[226:229], v[80:83]
	v_mfma_f32_16x16x32_bf16 v[60:63], v[164:167], v[184:187], v[60:63]
	v_mfma_f32_16x16x32_bf16 v[28:31], v[176:179], v[184:187], v[28:31]
	v_mfma_f32_16x16x32_bf16 v[56:59], v[164:167], v[192:195], v[56:59]
	v_mfma_f32_16x16x32_bf16 v[24:27], v[176:179], v[192:195], v[24:27]
	v_mfma_f32_16x16x32_bf16 v[52:55], v[164:167], v[200:203], v[52:55]
	v_mfma_f32_16x16x32_bf16 v[20:23], v[176:179], v[200:203], v[20:23]
	v_mfma_f32_16x16x32_bf16 v[48:51], v[164:167], v[222:225], v[48:51]
	v_mfma_f32_16x16x32_bf16 v[16:19], v[176:179], v[222:225], v[16:19]
	v_mfma_f32_16x16x32_bf16 v[60:63], v[168:171], v[188:191], v[60:63]
	v_mfma_f32_16x16x32_bf16 v[28:31], v[180:183], v[188:191], v[28:31]
	v_mfma_f32_16x16x32_bf16 v[56:59], v[168:171], v[196:199], v[56:59]
	v_mfma_f32_16x16x32_bf16 v[24:27], v[180:183], v[196:199], v[24:27]
	v_mfma_f32_16x16x32_bf16 v[52:55], v[168:171], v[218:221], v[52:55]
	v_mfma_f32_16x16x32_bf16 v[20:23], v[180:183], v[218:221], v[20:23]
	v_mfma_f32_16x16x32_bf16 v[48:51], v[168:171], v[226:229], v[48:51]
	v_mfma_f32_16x16x32_bf16 v[16:19], v[180:183], v[226:229], v[16:19]
	s_barrier
	s_add_i32 s53, s53, s36
	v_lshl_add_u64 v[154:155], s[30:31], 0, v[158:159]
	s_mov_b32 m0, s53
	ds_read_b128 v[184:187], v174 offset:16384
	ds_read_b128 v[188:191], v174 offset:17408
	ds_read_b128 v[192:195], v174 offset:18432
	ds_read_b128 v[196:199], v174 offset:19456
	ds_read_b128 v[200:203], v174 offset:20480
	ds_read_b128 v[218:221], v174 offset:21504
	ds_read_b128 v[222:225], v174 offset:22528
	ds_read_b128 v[226:229], v174 offset:23552
	global_load_lds_dwordx4 v[154:155], off
	s_add_i32 m0, s53, 0x2000
	s_add_u32 s54, s30, 0x40000
	v_lshl_add_u64 v[156:157], s[30:31], 0, v[144:145]
	s_addc_u32 s55, s31, 0
	s_add_i32 s53, s56, s36
	global_load_lds_dwordx4 v[156:157], off
	v_lshl_add_u64 v[204:205], s[54:55], 0, v[158:159]
	s_mov_b32 m0, s53
	v_lshl_add_u64 v[212:213], s[34:35], 0, v[146:147]
	global_load_lds_dwordx4 v[204:205], off
	v_lshl_add_u64 v[204:205], s[54:55], 0, v[144:145]
	s_add_i32 m0, s53, 0x2000
	s_nop 0
	global_load_lds_dwordx4 v[204:205], off
	v_lshl_add_u64 v[204:205], s[34:35], 0, v[148:149]
	s_mov_b32 m0, s37
	s_nop 0
	global_load_lds_dwordx4 v[204:205], off
	s_mov_b32 m0, s38
	s_nop 0
	global_load_lds_dwordx4 v[212:213], off
	s_waitcnt vmcnt(8)
	s_waitcnt lgkmcnt(0)
	s_barrier
	s_waitcnt lgkmcnt(0)
	v_mfma_f32_16x16x32_bf16 v[108:111], v[128:131], v[184:187], v[108:111]
	v_mfma_f32_16x16x32_bf16 v[76:79], v[136:139], v[184:187], v[76:79]
	v_mfma_f32_16x16x32_bf16 v[104:107], v[128:131], v[192:195], v[104:107]
	v_mfma_f32_16x16x32_bf16 v[72:75], v[136:139], v[192:195], v[72:75]
	v_mfma_f32_16x16x32_bf16 v[100:103], v[128:131], v[200:203], v[100:103]
	v_mfma_f32_16x16x32_bf16 v[68:71], v[136:139], v[200:203], v[68:71]
	v_mfma_f32_16x16x32_bf16 v[96:99], v[128:131], v[222:225], v[96:99]
	v_mfma_f32_16x16x32_bf16 v[64:67], v[136:139], v[222:225], v[64:67]
	v_mfma_f32_16x16x32_bf16 v[108:111], v[132:135], v[188:191], v[108:111]
	v_mfma_f32_16x16x32_bf16 v[76:79], v[140:143], v[188:191], v[76:79]
	v_mfma_f32_16x16x32_bf16 v[104:107], v[132:135], v[196:199], v[104:107]
	v_mfma_f32_16x16x32_bf16 v[72:75], v[140:143], v[196:199], v[72:75]
	v_mfma_f32_16x16x32_bf16 v[100:103], v[132:135], v[218:221], v[100:103]
	v_mfma_f32_16x16x32_bf16 v[68:71], v[140:143], v[218:221], v[68:71]
	v_mfma_f32_16x16x32_bf16 v[96:99], v[132:135], v[226:229], v[96:99]
	v_mfma_f32_16x16x32_bf16 v[64:67], v[140:143], v[226:229], v[64:67]
	v_mfma_f32_16x16x32_bf16 v[44:47], v[164:167], v[184:187], v[44:47]
	v_mfma_f32_16x16x32_bf16 v[12:15], v[176:179], v[184:187], v[12:15]
	v_mfma_f32_16x16x32_bf16 v[40:43], v[164:167], v[192:195], v[40:43]
	v_mfma_f32_16x16x32_bf16 v[8:11], v[176:179], v[192:195], v[8:11]
	v_mfma_f32_16x16x32_bf16 v[36:39], v[164:167], v[200:203], v[36:39]
	v_mfma_f32_16x16x32_bf16 v[4:7], v[176:179], v[200:203], v[4:7]
	v_mfma_f32_16x16x32_bf16 v[32:35], v[164:167], v[222:225], v[32:35]
	v_mfma_f32_16x16x32_bf16 v[0:3], v[176:179], v[222:225], v[0:3]
	v_mfma_f32_16x16x32_bf16 v[44:47], v[168:171], v[188:191], v[44:47]
	v_mfma_f32_16x16x32_bf16 v[12:15], v[180:183], v[188:191], v[12:15]
	v_mfma_f32_16x16x32_bf16 v[40:43], v[168:171], v[196:199], v[40:43]
	v_mfma_f32_16x16x32_bf16 v[8:11], v[180:183], v[196:199], v[8:11]
	v_mfma_f32_16x16x32_bf16 v[36:39], v[168:171], v[218:221], v[36:39]
	v_mfma_f32_16x16x32_bf16 v[4:7], v[180:183], v[218:221], v[4:7]
	v_mfma_f32_16x16x32_bf16 v[32:35], v[168:171], v[226:229], v[32:35]
	v_mfma_f32_16x16x32_bf16 v[0:3], v[180:183], v[226:229], v[0:3]
	s_barrier
	s_add_i32 s53, 0, 0x18000
	s_add_i32 s54, 0, 0x1c000
	v_add_u32_e32 v140, s53, v173
	v_add_u32_e32 v150, s54, v173
	ds_read_b128 v[128:131], v140
	ds_read_b128 v[132:135], v140 offset:1024
	ds_read_b128 v[136:139], v140 offset:2048
	ds_read_b128 v[140:143], v140 offset:3072
	ds_read_b128 v[164:167], v150
	ds_read_b128 v[168:171], v150 offset:1024
	ds_read_b128 v[176:179], v150 offset:2048
	ds_read_b128 v[180:183], v150 offset:3072
	s_add_u32 s34, s34, 0x40000
	s_addc_u32 s35, s35, 0
	s_mov_b32 m0, s39
	v_lshl_add_u64 v[214:215], s[34:35], 0, v[148:149]
	ds_read_b128 v[184:187], v174 offset:32768
	ds_read_b128 v[188:191], v174 offset:33792
	ds_read_b128 v[192:195], v174 offset:34816
	ds_read_b128 v[196:199], v174 offset:35840
	ds_read_b128 v[200:203], v174 offset:36864
	ds_read_b128 v[218:221], v174 offset:37888
	ds_read_b128 v[222:225], v174 offset:38912
	ds_read_b128 v[226:229], v174 offset:39936
	global_load_lds_dwordx4 v[214:215], off
	v_lshl_add_u64 v[214:215], s[34:35], 0, v[146:147]
	s_mov_b32 m0, s40
	s_nop 0
	global_load_lds_dwordx4 v[214:215], off
	s_waitcnt vmcnt(8)
	s_waitcnt lgkmcnt(0)
	s_barrier
	s_waitcnt lgkmcnt(0)
	v_mfma_f32_16x16x32_bf16 v[124:127], v[128:131], v[184:187], v[124:127]
	v_mfma_f32_16x16x32_bf16 v[92:95], v[136:139], v[184:187], v[92:95]
	v_mfma_f32_16x16x32_bf16 v[120:123], v[128:131], v[192:195], v[120:123]
	v_mfma_f32_16x16x32_bf16 v[88:91], v[136:139], v[192:195], v[88:91]
	v_mfma_f32_16x16x32_bf16 v[116:119], v[128:131], v[200:203], v[116:119]
	v_mfma_f32_16x16x32_bf16 v[84:87], v[136:139], v[200:203], v[84:87]
	v_mfma_f32_16x16x32_bf16 v[112:115], v[128:131], v[222:225], v[112:115]
	v_mfma_f32_16x16x32_bf16 v[80:83], v[136:139], v[222:225], v[80:83]
	v_mfma_f32_16x16x32_bf16 v[124:127], v[132:135], v[188:191], v[124:127]
	v_mfma_f32_16x16x32_bf16 v[92:95], v[140:143], v[188:191], v[92:95]
	v_mfma_f32_16x16x32_bf16 v[120:123], v[132:135], v[196:199], v[120:123]
	v_mfma_f32_16x16x32_bf16 v[88:91], v[140:143], v[196:199], v[88:91]
	v_mfma_f32_16x16x32_bf16 v[116:119], v[132:135], v[218:221], v[116:119]
	v_mfma_f32_16x16x32_bf16 v[84:87], v[140:143], v[218:221], v[84:87]
	v_mfma_f32_16x16x32_bf16 v[112:115], v[132:135], v[226:229], v[112:115]
	v_mfma_f32_16x16x32_bf16 v[80:83], v[140:143], v[226:229], v[80:83]
	v_mfma_f32_16x16x32_bf16 v[60:63], v[164:167], v[184:187], v[60:63]
	v_mfma_f32_16x16x32_bf16 v[28:31], v[176:179], v[184:187], v[28:31]
	v_mfma_f32_16x16x32_bf16 v[56:59], v[164:167], v[192:195], v[56:59]
	v_mfma_f32_16x16x32_bf16 v[24:27], v[176:179], v[192:195], v[24:27]
	v_mfma_f32_16x16x32_bf16 v[52:55], v[164:167], v[200:203], v[52:55]
	v_mfma_f32_16x16x32_bf16 v[20:23], v[176:179], v[200:203], v[20:23]
	v_mfma_f32_16x16x32_bf16 v[48:51], v[164:167], v[222:225], v[48:51]
	v_mfma_f32_16x16x32_bf16 v[16:19], v[176:179], v[222:225], v[16:19]
	v_mfma_f32_16x16x32_bf16 v[60:63], v[168:171], v[188:191], v[60:63]
	v_mfma_f32_16x16x32_bf16 v[28:31], v[180:183], v[188:191], v[28:31]
	v_mfma_f32_16x16x32_bf16 v[56:59], v[168:171], v[196:199], v[56:59]
	v_mfma_f32_16x16x32_bf16 v[24:27], v[180:183], v[196:199], v[24:27]
	v_mfma_f32_16x16x32_bf16 v[52:55], v[168:171], v[218:221], v[52:55]
	v_mfma_f32_16x16x32_bf16 v[20:23], v[180:183], v[218:221], v[20:23]
	v_mfma_f32_16x16x32_bf16 v[48:51], v[168:171], v[226:229], v[48:51]
	v_mfma_f32_16x16x32_bf16 v[16:19], v[180:183], v[226:229], v[16:19]
	s_barrier
	s_add_i32 s34, s53, s36
	v_lshl_add_u64 v[154:155], v[154:155], 0, s[28:29]
	s_mov_b32 m0, s34
	ds_read_b128 v[184:187], v174 offset:49152
	ds_read_b128 v[188:191], v174 offset:50176
	ds_read_b128 v[192:195], v174 offset:51200
	ds_read_b128 v[196:199], v174 offset:52224
	ds_read_b128 v[200:203], v174 offset:53248
	ds_read_b128 v[218:221], v174 offset:54272
	ds_read_b128 v[222:225], v174 offset:55296
	ds_read_b128 v[226:229], v174 offset:56320
	global_load_lds_dwordx4 v[154:155], off
	s_add_i32 m0, s34, 0x2000
	s_add_u32 s30, s30, 0x40080
	v_lshl_add_u64 v[154:155], v[156:157], 0, s[28:29]
	s_addc_u32 s31, s31, 0
	s_add_i32 s34, s54, s36
	global_load_lds_dwordx4 v[154:155], off
	v_lshl_add_u64 v[154:155], s[30:31], 0, v[158:159]
	s_mov_b32 m0, s34
	s_nop 0
	global_load_lds_dwordx4 v[154:155], off
	v_lshl_add_u64 v[154:155], s[30:31], 0, v[144:145]
	s_add_i32 m0, s34, 0x2000
	s_nop 0
	global_load_lds_dwordx4 v[154:155], off
	v_lshl_add_u64 v[154:155], v[204:205], 0, s[28:29]
	s_mov_b32 m0, s43
	s_nop 0
	global_load_lds_dwordx4 v[154:155], off
	v_lshl_add_u64 v[154:155], v[212:213], 0, s[28:29]
	s_mov_b32 m0, s44
	s_nop 0
	global_load_lds_dwordx4 v[154:155], off
	s_waitcnt vmcnt(8)
	s_waitcnt lgkmcnt(0)
	s_barrier
	s_waitcnt lgkmcnt(0)
	v_mfma_f32_16x16x32_bf16 v[108:111], v[128:131], v[184:187], v[108:111]
	v_mfma_f32_16x16x32_bf16 v[76:79], v[136:139], v[184:187], v[76:79]
	v_mfma_f32_16x16x32_bf16 v[104:107], v[128:131], v[192:195], v[104:107]
	v_mfma_f32_16x16x32_bf16 v[72:75], v[136:139], v[192:195], v[72:75]
	v_mfma_f32_16x16x32_bf16 v[100:103], v[128:131], v[200:203], v[100:103]
	v_mfma_f32_16x16x32_bf16 v[68:71], v[136:139], v[200:203], v[68:71]
	v_mfma_f32_16x16x32_bf16 v[96:99], v[128:131], v[222:225], v[96:99]
	v_mfma_f32_16x16x32_bf16 v[64:67], v[136:139], v[222:225], v[64:67]
	v_mfma_f32_16x16x32_bf16 v[108:111], v[132:135], v[188:191], v[108:111]
	v_mfma_f32_16x16x32_bf16 v[76:79], v[140:143], v[188:191], v[76:79]
	v_mfma_f32_16x16x32_bf16 v[104:107], v[132:135], v[196:199], v[104:107]
	v_mfma_f32_16x16x32_bf16 v[72:75], v[140:143], v[196:199], v[72:75]
	v_mfma_f32_16x16x32_bf16 v[100:103], v[132:135], v[218:221], v[100:103]
	v_mfma_f32_16x16x32_bf16 v[68:71], v[140:143], v[218:221], v[68:71]
	v_mfma_f32_16x16x32_bf16 v[96:99], v[132:135], v[226:229], v[96:99]
	v_mfma_f32_16x16x32_bf16 v[64:67], v[140:143], v[226:229], v[64:67]
	v_mfma_f32_16x16x32_bf16 v[44:47], v[164:167], v[184:187], v[44:47]
	v_mfma_f32_16x16x32_bf16 v[12:15], v[176:179], v[184:187], v[12:15]
	v_mfma_f32_16x16x32_bf16 v[40:43], v[164:167], v[192:195], v[40:43]
	v_mfma_f32_16x16x32_bf16 v[8:11], v[176:179], v[192:195], v[8:11]
	v_mfma_f32_16x16x32_bf16 v[36:39], v[164:167], v[200:203], v[36:39]
	v_mfma_f32_16x16x32_bf16 v[4:7], v[176:179], v[200:203], v[4:7]
	v_mfma_f32_16x16x32_bf16 v[32:35], v[164:167], v[222:225], v[32:35]
	v_mfma_f32_16x16x32_bf16 v[0:3], v[176:179], v[222:225], v[0:3]
	v_mfma_f32_16x16x32_bf16 v[44:47], v[168:171], v[188:191], v[44:47]
	v_mfma_f32_16x16x32_bf16 v[12:15], v[180:183], v[188:191], v[12:15]
	v_mfma_f32_16x16x32_bf16 v[40:43], v[168:171], v[196:199], v[40:43]
	v_mfma_f32_16x16x32_bf16 v[8:11], v[180:183], v[196:199], v[8:11]
	v_mfma_f32_16x16x32_bf16 v[36:39], v[168:171], v[218:221], v[36:39]
	v_mfma_f32_16x16x32_bf16 v[4:7], v[180:183], v[218:221], v[4:7]
	v_mfma_f32_16x16x32_bf16 v[32:35], v[168:171], v[226:229], v[32:35]
	v_mfma_f32_16x16x32_bf16 v[0:3], v[180:183], v[226:229], v[0:3]
	s_barrier
	s_add_i32 s52, s52, 2
	s_add_u32 s26, s26, 0x100
	s_addc_u32 s27, s27, 0
	s_add_u32 s50, s50, 0x100
	s_addc_u32 s51, s51, 0
	s_cmp_gt_u32 s52, 13
	s_cbranch_scc0 .LBB0_764
	s_and_b64 vcc, exec, s[16:17]
	s_mov_b32 s49, s57
	s_cbranch_vccz .LBB0_767
	s_barrier

.LBB0_853:
	s_ashr_i32 s19, s18, 31
	s_lshl_b64 s[22:23], s[18:19], 18
	s_add_u32 s22, s30, s22
	s_addc_u32 s23, s31, s23
	s_and_b64 s[0:1], s[0:1], exec
	s_cselect_b32 s1, s23, s25
	s_cselect_b32 s0, s22, s24
	s_add_i32 s50, 0, 0x10000
	s_add_i32 s51, 0, 0x14000
	v_add_u32_e32 v8, s50, v138
	v_add_u32_e32 v9, s51, v138
	ds_read_b128 v[10:13], v8
	ds_read_b128 v[14:17], v8 offset:1024
	ds_read_b128 v[18:21], v8 offset:2048
	ds_read_b128 v[22:25], v8 offset:3072
	ds_read_b128 v[26:29], v9
	ds_read_b128 v[30:33], v9 offset:1024
	ds_read_b128 v[34:37], v9 offset:2048
	ds_read_b128 v[38:41], v9 offset:3072
	s_add_u32 s48, s24, 0x20080
	s_addc_u32 s49, s25, 0
	s_add_i32 s53, s36, 0xc000
	v_lshl_add_u64 v[66:67], s[48:49], 0, v[132:133]
	s_mov_b32 m0, s53
	s_add_i32 s19, s36, 0xe000
	ds_read_b128 v[0:3], v139
	ds_read_b128 v[4:7], v139 offset:1024
	ds_read_b128 v[42:45], v139 offset:2048
	ds_read_b128 v[46:49], v139 offset:3072
	ds_read_b128 v[50:53], v139 offset:4096
	ds_read_b128 v[54:57], v139 offset:5120
	ds_read_b128 v[58:61], v139 offset:6144
	ds_read_b128 v[62:65], v139 offset:7168
	global_load_lds_dwordx4 v[66:67], off
	v_lshl_add_u64 v[66:67], s[48:49], 0, v[130:131]
	s_mov_b32 m0, s19
	s_nop 0
	global_load_lds_dwordx4 v[66:67], off
	s_waitcnt vmcnt(8)
	s_waitcnt lgkmcnt(0)
	s_barrier
	s_waitcnt lgkmcnt(0)
	v_mfma_f32_16x16x32_bf16 v[66:69], v[10:13], v[0:3], 0
	v_mfma_f32_16x16x32_bf16 v[70:73], v[18:21], v[0:3], 0
	v_mfma_f32_16x16x32_bf16 v[74:77], v[10:13], v[42:45], 0
	v_mfma_f32_16x16x32_bf16 v[78:81], v[18:21], v[42:45], 0
	v_mfma_f32_16x16x32_bf16 v[82:85], v[10:13], v[50:53], 0
	v_mfma_f32_16x16x32_bf16 v[86:89], v[18:21], v[50:53], 0
	v_mfma_f32_16x16x32_bf16 v[90:93], v[10:13], v[58:61], 0
	v_mfma_f32_16x16x32_bf16 v[94:97], v[18:21], v[58:61], 0
	v_mfma_f32_16x16x32_bf16 v[66:69], v[14:17], v[4:7], v[66:69]
	v_mfma_f32_16x16x32_bf16 v[70:73], v[22:25], v[4:7], v[70:73]
	v_mfma_f32_16x16x32_bf16 v[74:77], v[14:17], v[46:49], v[74:77]
	v_mfma_f32_16x16x32_bf16 v[78:81], v[22:25], v[46:49], v[78:81]
	v_mfma_f32_16x16x32_bf16 v[82:85], v[14:17], v[54:57], v[82:85]
	v_mfma_f32_16x16x32_bf16 v[86:89], v[22:25], v[54:57], v[86:89]
	v_mfma_f32_16x16x32_bf16 v[90:93], v[14:17], v[62:65], v[90:93]
	v_mfma_f32_16x16x32_bf16 v[94:97], v[22:25], v[62:65], v[94:97]
	v_mfma_f32_16x16x32_bf16 v[98:101], v[26:29], v[0:3], 0
	v_mfma_f32_16x16x32_bf16 v[0:3], v[34:37], v[0:3], 0
	v_mfma_f32_16x16x32_bf16 v[102:105], v[38:41], v[4:7], v[0:3]
	v_mfma_f32_16x16x32_bf16 v[0:3], v[26:29], v[42:45], 0
	v_mfma_f32_16x16x32_bf16 v[106:109], v[30:33], v[46:49], v[0:3]
	v_mfma_f32_16x16x32_bf16 v[0:3], v[34:37], v[42:45], 0
	v_mfma_f32_16x16x32_bf16 v[42:45], v[38:41], v[46:49], v[0:3]
	v_mfma_f32_16x16x32_bf16 v[0:3], v[26:29], v[50:53], 0
	v_mfma_f32_16x16x32_bf16 v[46:49], v[30:33], v[54:57], v[0:3]
	v_mfma_f32_16x16x32_bf16 v[0:3], v[34:37], v[50:53], 0
	v_mfma_f32_16x16x32_bf16 v[50:53], v[38:41], v[54:57], v[0:3]
	v_mfma_f32_16x16x32_bf16 v[0:3], v[26:29], v[58:61], 0
	v_mfma_f32_16x16x32_bf16 v[54:57], v[30:33], v[62:65], v[0:3]
	v_mfma_f32_16x16x32_bf16 v[0:3], v[34:37], v[58:61], 0
	v_mfma_f32_16x16x32_bf16 v[98:101], v[30:33], v[4:7], v[98:101]
	v_mfma_f32_16x16x32_bf16 v[58:61], v[38:41], v[62:65], v[0:3]
	s_barrier
	s_nop 3
	v_lshl_add_u64 v[0:1], s[26:27], 0, v[148:149]
	s_mov_b64 s[56:57], 0x100
	s_add_i32 s50, s50, s35
	v_lshl_add_u64 v[2:3], v[0:1], 0, s[56:57]
	s_mov_b32 m0, s50
	s_add_i32 s47, s50, 0x2000
	ds_read_b128 v[62:65], v139 offset:16384
	ds_read_b128 v[110:113], v139 offset:17408
	ds_read_b128 v[114:117], v139 offset:18432
	ds_read_b128 v[118:121], v139 offset:19456
	ds_read_b128 v[122:125], v139 offset:20480
	ds_read_b128 v[134:137], v139 offset:21504
	ds_read_b128 v[140:143], v139 offset:22528
	ds_read_b128 v[144:147], v139 offset:23552
	global_load_lds_dwordx4 v[2:3], off
	v_lshl_add_u64 v[2:3], s[26:27], 0, v[128:129]
	s_add_u32 s54, s26, 0x18100
	v_lshl_add_u64 v[4:5], v[2:3], 0, s[56:57]
	s_mov_b32 m0, s47
	s_addc_u32 s55, s27, 0
	s_add_i32 s48, s51, s35
	global_load_lds_dwordx4 v[4:5], off
	v_lshl_add_u64 v[4:5], s[54:55], 0, v[148:149]
	s_mov_b32 m0, s48
	s_add_i32 s49, s48, 0x2000
	global_load_lds_dwordx4 v[4:5], off
	v_lshl_add_u64 v[4:5], s[54:55], 0, v[128:129]
	s_mov_b32 m0, s49
	s_nop 0
	global_load_lds_dwordx4 v[4:5], off
	v_lshl_add_u64 v[4:5], s[24:25], 0, v[132:133]
	v_lshl_add_u64 v[6:7], v[4:5], 0, s[56:57]
	s_mov_b32 m0, s36
	s_nop 0
	global_load_lds_dwordx4 v[6:7], off
	v_lshl_add_u64 v[6:7], s[24:25], 0, v[130:131]
	v_lshl_add_u64 v[126:127], v[6:7], 0, s[56:57]
	s_mov_b32 m0, s37
	s_nop 0
	global_load_lds_dwordx4 v[126:127], off
	s_waitcnt vmcnt(8)
	s_waitcnt lgkmcnt(0)
	s_barrier
	s_waitcnt lgkmcnt(0)
	v_mfma_f32_16x16x32_bf16 v[158:161], v[10:13], v[62:65], 0
	v_mfma_f32_16x16x32_bf16 v[166:169], v[10:13], v[114:117], 0
	v_mfma_f32_16x16x32_bf16 v[174:177], v[10:13], v[122:125], 0
	v_mfma_f32_16x16x32_bf16 v[10:13], v[10:13], v[140:143], 0
	v_mfma_f32_16x16x32_bf16 v[158:161], v[14:17], v[110:113], v[158:161]
	v_mfma_f32_16x16x32_bf16 v[162:165], v[18:21], v[62:65], 0
	v_mfma_f32_16x16x32_bf16 v[166:169], v[14:17], v[118:121], v[166:169]
	v_mfma_f32_16x16x32_bf16 v[170:173], v[18:21], v[114:117], 0
	v_mfma_f32_16x16x32_bf16 v[174:177], v[14:17], v[134:137], v[174:177]
	v_mfma_f32_16x16x32_bf16 v[178:181], v[18:21], v[122:125], 0
	v_mfma_f32_16x16x32_bf16 v[12:15], v[14:17], v[144:147], v[10:13]
	v_mfma_f32_16x16x32_bf16 v[16:19], v[18:21], v[140:143], 0
	v_mfma_f32_16x16x32_bf16 v[16:19], v[22:25], v[144:147], v[16:19]
	v_mfma_f32_16x16x32_bf16 v[162:165], v[22:25], v[110:113], v[162:165]
	v_mfma_f32_16x16x32_bf16 v[170:173], v[22:25], v[118:121], v[170:173]
	v_mfma_f32_16x16x32_bf16 v[178:181], v[22:25], v[134:137], v[178:181]
	v_mfma_f32_16x16x32_bf16 v[20:23], v[26:29], v[62:65], 0
	v_mfma_f32_16x16x32_bf16 v[62:65], v[34:37], v[62:65], 0
	v_mfma_f32_16x16x32_bf16 v[20:23], v[30:33], v[110:113], v[20:23]
	v_mfma_f32_16x16x32_bf16 v[62:65], v[38:41], v[110:113], v[62:65]
	v_mfma_f32_16x16x32_bf16 v[110:113], v[26:29], v[114:117], 0
	v_mfma_f32_16x16x32_bf16 v[114:117], v[34:37], v[114:117], 0
	v_mfma_f32_16x16x32_bf16 v[110:113], v[30:33], v[118:121], v[110:113]
	v_mfma_f32_16x16x32_bf16 v[114:117], v[38:41], v[118:121], v[114:117]
	v_mfma_f32_16x16x32_bf16 v[118:121], v[26:29], v[122:125], 0
	v_mfma_f32_16x16x32_bf16 v[24:27], v[26:29], v[140:143], 0
	v_mfma_f32_16x16x32_bf16 v[118:121], v[30:33], v[134:137], v[118:121]
	v_mfma_f32_16x16x32_bf16 v[122:125], v[34:37], v[122:125], 0
	v_mfma_f32_16x16x32_bf16 v[24:27], v[30:33], v[144:147], v[24:27]
	v_mfma_f32_16x16x32_bf16 v[28:31], v[34:37], v[140:143], 0
	v_mfma_f32_16x16x32_bf16 v[122:125], v[38:41], v[134:137], v[122:125]
	v_mfma_f32_16x16x32_bf16 v[28:31], v[38:41], v[144:147], v[28:31]
	s_barrier
	s_add_i32 s51, 0, 0x18000
	s_add_i32 s52, 0, 0x1c000
	v_add_u32_e32 v10, s51, v138
	v_add_u32_e32 v11, s52, v138
	ds_read_b128 v[32:35], v10
	ds_read_b128 v[36:39], v10 offset:1024
	ds_read_b128 v[134:137], v10 offset:2048
	ds_read_b128 v[140:143], v10 offset:3072
	ds_read_b128 v[144:147], v11
	ds_read_b128 v[182:185], v11 offset:1024
	ds_read_b128 v[186:189], v11 offset:2048
	ds_read_b128 v[190:193], v11 offset:3072
	s_add_u32 s54, s24, 0x20100
	s_addc_u32 s55, s25, 0
	s_mov_b32 m0, s38
	v_lshl_add_u64 v[40:41], s[54:55], 0, v[132:133]
	ds_read_b128 v[194:197], v139 offset:32768
	ds_read_b128 v[198:201], v139 offset:33792
	ds_read_b128 v[202:205], v139 offset:34816
	ds_read_b128 v[218:221], v139 offset:35840
	ds_read_b128 v[222:225], v139 offset:36864
	ds_read_b128 v[226:229], v139 offset:37888
	ds_read_b128 v[230:233], v139 offset:38912
	ds_read_b128 v[234:237], v139 offset:39936
	global_load_lds_dwordx4 v[40:41], off
	v_lshl_add_u64 v[40:41], s[54:55], 0, v[130:131]
	s_mov_b32 m0, s39
	s_nop 0
	global_load_lds_dwordx4 v[40:41], off
	s_waitcnt vmcnt(8)
	s_waitcnt lgkmcnt(0)
	s_barrier
	s_waitcnt lgkmcnt(0)
	v_mfma_f32_16x16x32_bf16 v[66:69], v[32:35], v[194:197], v[66:69]
	v_mfma_f32_16x16x32_bf16 v[70:73], v[134:137], v[194:197], v[70:73]
	v_mfma_f32_16x16x32_bf16 v[74:77], v[32:35], v[202:205], v[74:77]
	v_mfma_f32_16x16x32_bf16 v[78:81], v[134:137], v[202:205], v[78:81]
	v_mfma_f32_16x16x32_bf16 v[82:85], v[32:35], v[222:225], v[82:85]
	v_mfma_f32_16x16x32_bf16 v[86:89], v[134:137], v[222:225], v[86:89]
	v_mfma_f32_16x16x32_bf16 v[90:93], v[32:35], v[230:233], v[90:93]
	v_mfma_f32_16x16x32_bf16 v[94:97], v[134:137], v[230:233], v[94:97]
	v_mfma_f32_16x16x32_bf16 v[66:69], v[36:39], v[198:201], v[66:69]
	v_mfma_f32_16x16x32_bf16 v[70:73], v[140:143], v[198:201], v[70:73]
	v_mfma_f32_16x16x32_bf16 v[74:77], v[36:39], v[218:221], v[74:77]
	v_mfma_f32_16x16x32_bf16 v[78:81], v[140:143], v[218:221], v[78:81]
	v_mfma_f32_16x16x32_bf16 v[82:85], v[36:39], v[226:229], v[82:85]
	v_mfma_f32_16x16x32_bf16 v[86:89], v[140:143], v[226:229], v[86:89]
	v_mfma_f32_16x16x32_bf16 v[90:93], v[36:39], v[234:237], v[90:93]
	v_mfma_f32_16x16x32_bf16 v[94:97], v[140:143], v[234:237], v[94:97]
	v_mfma_f32_16x16x32_bf16 v[98:101], v[144:147], v[194:197], v[98:101]
	v_mfma_f32_16x16x32_bf16 v[102:105], v[186:189], v[194:197], v[102:105]
	v_mfma_f32_16x16x32_bf16 v[106:109], v[144:147], v[202:205], v[106:109]
	v_mfma_f32_16x16x32_bf16 v[40:43], v[186:189], v[202:205], v[42:45]
	v_mfma_f32_16x16x32_bf16 v[44:47], v[144:147], v[222:225], v[46:49]
	v_mfma_f32_16x16x32_bf16 v[48:51], v[186:189], v[222:225], v[50:53]
	v_mfma_f32_16x16x32_bf16 v[52:55], v[144:147], v[230:233], v[54:57]
	v_mfma_f32_16x16x32_bf16 v[56:59], v[186:189], v[230:233], v[58:61]
	v_mfma_f32_16x16x32_bf16 v[98:101], v[182:185], v[198:201], v[98:101]
	v_mfma_f32_16x16x32_bf16 v[102:105], v[190:193], v[198:201], v[102:105]
	v_mfma_f32_16x16x32_bf16 v[106:109], v[182:185], v[218:221], v[106:109]
	v_mfma_f32_16x16x32_bf16 v[40:43], v[190:193], v[218:221], v[40:43]
	v_mfma_f32_16x16x32_bf16 v[44:47], v[182:185], v[226:229], v[44:47]
	v_mfma_f32_16x16x32_bf16 v[48:51], v[190:193], v[226:229], v[48:51]
	v_mfma_f32_16x16x32_bf16 v[52:55], v[182:185], v[234:237], v[52:55]
	v_mfma_f32_16x16x32_bf16 v[56:59], v[190:193], v[234:237], v[56:59]
	s_barrier
	s_add_i32 s55, s51, s35
	s_mov_b64 s[60:61], 0x180
	s_add_i32 s51, s55, 0x2000
	v_lshl_add_u64 v[60:61], v[0:1], 0, s[60:61]
	s_mov_b32 m0, s55
	s_add_u32 s56, s26, 0x18180
	ds_read_b128 v[194:197], v139 offset:49152
	ds_read_b128 v[198:201], v139 offset:50176
	ds_read_b128 v[202:205], v139 offset:51200
	ds_read_b128 v[218:221], v139 offset:52224
	ds_read_b128 v[222:225], v139 offset:53248
	ds_read_b128 v[226:229], v139 offset:54272
	ds_read_b128 v[230:233], v139 offset:55296
	ds_read_b128 v[234:237], v139 offset:56320
	global_load_lds_dwordx4 v[60:61], off
	v_lshl_add_u64 v[60:61], v[2:3], 0, s[60:61]
	s_mov_b32 m0, s51
	s_addc_u32 s57, s27, 0
	s_add_i32 s52, s52, s35
	global_load_lds_dwordx4 v[60:61], off
	v_lshl_add_u64 v[60:61], s[56:57], 0, v[148:149]
	s_mov_b32 m0, s52
	s_add_i32 s54, s52, 0x2000
	global_load_lds_dwordx4 v[60:61], off
	v_lshl_add_u64 v[60:61], s[56:57], 0, v[128:129]
	s_mov_b32 m0, s54
	s_nop 0
	global_load_lds_dwordx4 v[60:61], off
	v_lshl_add_u64 v[60:61], v[4:5], 0, s[60:61]
	s_mov_b32 m0, s42
	s_nop 0
	global_load_lds_dwordx4 v[60:61], off
	v_lshl_add_u64 v[60:61], v[6:7], 0, s[60:61]
	s_mov_b32 m0, s43
	s_nop 0
	global_load_lds_dwordx4 v[60:61], off
	s_waitcnt vmcnt(8)
	s_waitcnt lgkmcnt(0)
	s_barrier
	s_waitcnt lgkmcnt(0)
	v_mfma_f32_16x16x32_bf16 v[12:15], v[32:35], v[230:233], v[12:15]
	v_mfma_f32_16x16x32_bf16 v[16:19], v[134:137], v[230:233], v[16:19]
	v_mfma_f32_16x16x32_bf16 v[158:161], v[32:35], v[194:197], v[158:161]
	v_mfma_f32_16x16x32_bf16 v[162:165], v[134:137], v[194:197], v[162:165]
	v_mfma_f32_16x16x32_bf16 v[166:169], v[32:35], v[202:205], v[166:169]
	v_mfma_f32_16x16x32_bf16 v[170:173], v[134:137], v[202:205], v[170:173]
	v_mfma_f32_16x16x32_bf16 v[174:177], v[32:35], v[222:225], v[174:177]
	v_mfma_f32_16x16x32_bf16 v[178:181], v[134:137], v[222:225], v[178:181]
	v_mfma_f32_16x16x32_bf16 v[12:15], v[36:39], v[234:237], v[12:15]
	v_mfma_f32_16x16x32_bf16 v[16:19], v[140:143], v[234:237], v[16:19]
	v_mfma_f32_16x16x32_bf16 v[158:161], v[36:39], v[198:201], v[158:161]
	v_mfma_f32_16x16x32_bf16 v[162:165], v[140:143], v[198:201], v[162:165]
	v_mfma_f32_16x16x32_bf16 v[166:169], v[36:39], v[218:221], v[166:169]
	v_mfma_f32_16x16x32_bf16 v[170:173], v[140:143], v[218:221], v[170:173]
	v_mfma_f32_16x16x32_bf16 v[174:177], v[36:39], v[226:229], v[174:177]
	v_mfma_f32_16x16x32_bf16 v[178:181], v[140:143], v[226:229], v[178:181]
	v_mfma_f32_16x16x32_bf16 v[20:23], v[144:147], v[194:197], v[20:23]
	v_mfma_f32_16x16x32_bf16 v[32:35], v[186:189], v[194:197], v[62:65]
	v_mfma_f32_16x16x32_bf16 v[36:39], v[144:147], v[202:205], v[110:113]
	v_mfma_f32_16x16x32_bf16 v[60:63], v[186:189], v[202:205], v[114:117]
	v_mfma_f32_16x16x32_bf16 v[110:113], v[144:147], v[222:225], v[118:121]
	v_mfma_f32_16x16x32_bf16 v[114:117], v[186:189], v[222:225], v[122:125]
	v_mfma_f32_16x16x32_bf16 v[24:27], v[144:147], v[230:233], v[24:27]
	v_mfma_f32_16x16x32_bf16 v[28:31], v[186:189], v[230:233], v[28:31]
	v_mfma_f32_16x16x32_bf16 v[20:23], v[182:185], v[198:201], v[20:23]
	v_mfma_f32_16x16x32_bf16 v[32:35], v[190:193], v[198:201], v[32:35]
	v_mfma_f32_16x16x32_bf16 v[36:39], v[182:185], v[218:221], v[36:39]
	v_mfma_f32_16x16x32_bf16 v[60:63], v[190:193], v[218:221], v[60:63]
	v_mfma_f32_16x16x32_bf16 v[110:113], v[182:185], v[226:229], v[110:113]
	v_mfma_f32_16x16x32_bf16 v[114:117], v[190:193], v[226:229], v[114:117]
	v_mfma_f32_16x16x32_bf16 v[24:27], v[182:185], v[234:237], v[24:27]
	v_mfma_f32_16x16x32_bf16 v[28:31], v[190:193], v[234:237], v[28:31]
	s_barrier
	ds_read_b128 v[118:121], v8
	ds_read_b128 v[122:125], v8 offset:1024
	ds_read_b128 v[134:137], v8 offset:2048
	ds_read_b128 v[140:143], v8 offset:3072
	ds_read_b128 v[144:147], v9
	ds_read_b128 v[182:185], v9 offset:1024
	ds_read_b128 v[186:189], v9 offset:2048
	ds_read_b128 v[190:193], v9 offset:3072
	s_add_u32 s56, s24, 0x20180
	s_addc_u32 s57, s25, 0
	s_mov_b32 m0, s53
	v_lshl_add_u64 v[64:65], s[56:57], 0, v[132:133]
	ds_read_b128 v[194:197], v139
	ds_read_b128 v[198:201], v139 offset:1024
	ds_read_b128 v[202:205], v139 offset:2048
	ds_read_b128 v[218:221], v139 offset:3072
	ds_read_b128 v[222:225], v139 offset:4096
	ds_read_b128 v[226:229], v139 offset:5120
	ds_read_b128 v[230:233], v139 offset:6144
	ds_read_b128 v[234:237], v139 offset:7168
	global_load_lds_dwordx4 v[64:65], off
	v_lshl_add_u64 v[64:65], s[56:57], 0, v[130:131]
	s_mov_b32 m0, s19
	s_nop 0
	global_load_lds_dwordx4 v[64:65], off
	s_waitcnt vmcnt(8)
	s_waitcnt lgkmcnt(0)
	s_barrier
	s_waitcnt lgkmcnt(0)
	v_mfma_f32_16x16x32_bf16 v[64:67], v[118:121], v[194:197], v[66:69]
	v_mfma_f32_16x16x32_bf16 v[68:71], v[134:137], v[194:197], v[70:73]
	v_mfma_f32_16x16x32_bf16 v[72:75], v[118:121], v[202:205], v[74:77]
	v_mfma_f32_16x16x32_bf16 v[76:79], v[134:137], v[202:205], v[78:81]
	v_mfma_f32_16x16x32_bf16 v[80:83], v[118:121], v[222:225], v[82:85]
	v_mfma_f32_16x16x32_bf16 v[84:87], v[134:137], v[222:225], v[86:89]
	v_mfma_f32_16x16x32_bf16 v[88:91], v[118:121], v[230:233], v[90:93]
	v_mfma_f32_16x16x32_bf16 v[92:95], v[134:137], v[230:233], v[94:97]
	v_mfma_f32_16x16x32_bf16 v[64:67], v[122:125], v[198:201], v[64:67]
	v_mfma_f32_16x16x32_bf16 v[68:71], v[140:143], v[198:201], v[68:71]
	v_mfma_f32_16x16x32_bf16 v[72:75], v[122:125], v[218:221], v[72:75]
	v_mfma_f32_16x16x32_bf16 v[76:79], v[140:143], v[218:221], v[76:79]
	v_mfma_f32_16x16x32_bf16 v[80:83], v[122:125], v[226:229], v[80:83]
	v_mfma_f32_16x16x32_bf16 v[84:87], v[140:143], v[226:229], v[84:87]
	v_mfma_f32_16x16x32_bf16 v[88:91], v[122:125], v[234:237], v[88:91]
	v_mfma_f32_16x16x32_bf16 v[92:95], v[140:143], v[234:237], v[92:95]
	v_mfma_f32_16x16x32_bf16 v[96:99], v[144:147], v[194:197], v[98:101]
	v_mfma_f32_16x16x32_bf16 v[100:103], v[186:189], v[194:197], v[102:105]
	v_mfma_f32_16x16x32_bf16 v[104:107], v[144:147], v[202:205], v[106:109]
	v_mfma_f32_16x16x32_bf16 v[40:43], v[186:189], v[202:205], v[40:43]
	v_mfma_f32_16x16x32_bf16 v[44:47], v[144:147], v[222:225], v[44:47]
	v_mfma_f32_16x16x32_bf16 v[48:51], v[186:189], v[222:225], v[48:51]
	v_mfma_f32_16x16x32_bf16 v[52:55], v[144:147], v[230:233], v[52:55]
	v_mfma_f32_16x16x32_bf16 v[56:59], v[186:189], v[230:233], v[56:59]
	v_mfma_f32_16x16x32_bf16 v[96:99], v[182:185], v[198:201], v[96:99]
	v_mfma_f32_16x16x32_bf16 v[100:103], v[190:193], v[198:201], v[100:103]
	v_mfma_f32_16x16x32_bf16 v[104:107], v[182:185], v[218:221], v[104:107]
	v_mfma_f32_16x16x32_bf16 v[40:43], v[190:193], v[218:221], v[40:43]
	v_mfma_f32_16x16x32_bf16 v[44:47], v[182:185], v[226:229], v[44:47]
	v_mfma_f32_16x16x32_bf16 v[48:51], v[190:193], v[226:229], v[48:51]
	v_mfma_f32_16x16x32_bf16 v[52:55], v[182:185], v[234:237], v[52:55]
	v_mfma_f32_16x16x32_bf16 v[56:59], v[190:193], v[234:237], v[56:59]
	s_barrier
	s_mov_b64 s[60:61], 0x200
	s_mov_b32 m0, s50
	v_lshl_add_u64 v[108:109], v[0:1], 0, s[60:61]
	s_add_u32 s56, s26, 0x18200
	ds_read_b128 v[194:197], v139 offset:16384
	ds_read_b128 v[198:201], v139 offset:17408
	ds_read_b128 v[202:205], v139 offset:18432
	ds_read_b128 v[218:221], v139 offset:19456
	ds_read_b128 v[222:225], v139 offset:20480
	ds_read_b128 v[226:229], v139 offset:21504
	ds_read_b128 v[230:233], v139 offset:22528
	ds_read_b128 v[234:237], v139 offset:23552
	global_load_lds_dwordx4 v[108:109], off
	v_lshl_add_u64 v[108:109], v[2:3], 0, s[60:61]
	s_mov_b32 m0, s47
	s_addc_u32 s57, s27, 0
	global_load_lds_dwordx4 v[108:109], off
	v_lshl_add_u64 v[108:109], s[56:57], 0, v[148:149]
	s_mov_b32 m0, s48
	s_nop 0
	global_load_lds_dwordx4 v[108:109], off
	v_lshl_add_u64 v[108:109], s[56:57], 0, v[128:129]
	s_mov_b32 m0, s49
	s_nop 0
	global_load_lds_dwordx4 v[108:109], off
	v_lshl_add_u64 v[108:109], v[4:5], 0, s[60:61]
	s_mov_b32 m0, s36
	s_nop 0
	global_load_lds_dwordx4 v[108:109], off
	v_lshl_add_u64 v[108:109], v[6:7], 0, s[60:61]
	s_mov_b32 m0, s37
	s_nop 0
	global_load_lds_dwordx4 v[108:109], off
	s_waitcnt vmcnt(8)
	s_waitcnt lgkmcnt(0)
	s_barrier
	s_waitcnt lgkmcnt(0)
	v_mfma_f32_16x16x32_bf16 v[12:15], v[118:121], v[230:233], v[12:15]
	v_mfma_f32_16x16x32_bf16 v[16:19], v[134:137], v[230:233], v[16:19]
	v_mfma_f32_16x16x32_bf16 v[158:161], v[118:121], v[194:197], v[158:161]
	v_mfma_f32_16x16x32_bf16 v[162:165], v[134:137], v[194:197], v[162:165]
	v_mfma_f32_16x16x32_bf16 v[166:169], v[118:121], v[202:205], v[166:169]
	v_mfma_f32_16x16x32_bf16 v[170:173], v[134:137], v[202:205], v[170:173]
	v_mfma_f32_16x16x32_bf16 v[174:177], v[118:121], v[222:225], v[174:177]
	v_mfma_f32_16x16x32_bf16 v[178:181], v[134:137], v[222:225], v[178:181]
	v_mfma_f32_16x16x32_bf16 v[12:15], v[122:125], v[234:237], v[12:15]
	v_mfma_f32_16x16x32_bf16 v[16:19], v[140:143], v[234:237], v[16:19]
	v_mfma_f32_16x16x32_bf16 v[158:161], v[122:125], v[198:201], v[158:161]
	v_mfma_f32_16x16x32_bf16 v[162:165], v[140:143], v[198:201], v[162:165]
	v_mfma_f32_16x16x32_bf16 v[166:169], v[122:125], v[218:221], v[166:169]
	v_mfma_f32_16x16x32_bf16 v[170:173], v[140:143], v[218:221], v[170:173]
	v_mfma_f32_16x16x32_bf16 v[174:177], v[122:125], v[226:229], v[174:177]
	v_mfma_f32_16x16x32_bf16 v[178:181], v[140:143], v[226:229], v[178:181]
	v_mfma_f32_16x16x32_bf16 v[20:23], v[144:147], v[194:197], v[20:23]
	v_mfma_f32_16x16x32_bf16 v[32:35], v[186:189], v[194:197], v[32:35]
	v_mfma_f32_16x16x32_bf16 v[36:39], v[144:147], v[202:205], v[36:39]
	v_mfma_f32_16x16x32_bf16 v[60:63], v[186:189], v[202:205], v[60:63]
	v_mfma_f32_16x16x32_bf16 v[108:111], v[144:147], v[222:225], v[110:113]
	v_mfma_f32_16x16x32_bf16 v[112:115], v[186:189], v[222:225], v[114:117]
	v_mfma_f32_16x16x32_bf16 v[24:27], v[144:147], v[230:233], v[24:27]
	v_mfma_f32_16x16x32_bf16 v[28:31], v[186:189], v[230:233], v[28:31]
	v_mfma_f32_16x16x32_bf16 v[20:23], v[182:185], v[198:201], v[20:23]
	v_mfma_f32_16x16x32_bf16 v[32:35], v[190:193], v[198:201], v[32:35]
	v_mfma_f32_16x16x32_bf16 v[36:39], v[182:185], v[218:221], v[36:39]
	v_mfma_f32_16x16x32_bf16 v[60:63], v[190:193], v[218:221], v[60:63]
	v_mfma_f32_16x16x32_bf16 v[108:111], v[182:185], v[226:229], v[108:111]
	v_mfma_f32_16x16x32_bf16 v[112:115], v[190:193], v[226:229], v[112:115]
	v_mfma_f32_16x16x32_bf16 v[24:27], v[182:185], v[234:237], v[24:27]
	v_mfma_f32_16x16x32_bf16 v[28:31], v[190:193], v[234:237], v[28:31]
	s_barrier
	ds_read_b128 v[116:119], v10
	ds_read_b128 v[120:123], v10 offset:1024
	ds_read_b128 v[124:127], v10 offset:2048
	ds_read_b128 v[134:137], v10 offset:3072
	ds_read_b128 v[140:143], v11
	ds_read_b128 v[144:147], v11 offset:1024
	ds_read_b128 v[182:185], v11 offset:2048
	ds_read_b128 v[186:189], v11 offset:3072
	s_add_u32 s56, s24, 0x20200
	s_addc_u32 s57, s25, 0
	s_mov_b32 m0, s38
	v_lshl_add_u64 v[154:155], s[56:57], 0, v[132:133]
	ds_read_b128 v[190:193], v139 offset:32768
	ds_read_b128 v[194:197], v139 offset:33792
	ds_read_b128 v[198:201], v139 offset:34816
	ds_read_b128 v[202:205], v139 offset:35840
	ds_read_b128 v[218:221], v139 offset:36864
	ds_read_b128 v[222:225], v139 offset:37888
	ds_read_b128 v[226:229], v139 offset:38912
	ds_read_b128 v[230:233], v139 offset:39936
	global_load_lds_dwordx4 v[154:155], off
	v_lshl_add_u64 v[154:155], s[56:57], 0, v[130:131]
	s_mov_b32 m0, s39
	s_nop 0
	global_load_lds_dwordx4 v[154:155], off
	s_waitcnt vmcnt(8)
	s_waitcnt lgkmcnt(0)
	s_barrier
	s_waitcnt lgkmcnt(0)
	v_mfma_f32_16x16x32_bf16 v[64:67], v[116:119], v[190:193], v[64:67]
	v_mfma_f32_16x16x32_bf16 v[68:71], v[124:127], v[190:193], v[68:71]
	v_mfma_f32_16x16x32_bf16 v[72:75], v[116:119], v[198:201], v[72:75]
	v_mfma_f32_16x16x32_bf16 v[76:79], v[124:127], v[198:201], v[76:79]
	v_mfma_f32_16x16x32_bf16 v[80:83], v[116:119], v[218:221], v[80:83]
	v_mfma_f32_16x16x32_bf16 v[84:87], v[124:127], v[218:221], v[84:87]
	v_mfma_f32_16x16x32_bf16 v[88:91], v[116:119], v[226:229], v[88:91]
	v_mfma_f32_16x16x32_bf16 v[92:95], v[124:127], v[226:229], v[92:95]
	v_mfma_f32_16x16x32_bf16 v[64:67], v[120:123], v[194:197], v[64:67]
	v_mfma_f32_16x16x32_bf16 v[68:71], v[134:137], v[194:197], v[68:71]
	v_mfma_f32_16x16x32_bf16 v[72:75], v[120:123], v[202:205], v[72:75]
	v_mfma_f32_16x16x32_bf16 v[76:79], v[134:137], v[202:205], v[76:79]
	v_mfma_f32_16x16x32_bf16 v[80:83], v[120:123], v[222:225], v[80:83]
	v_mfma_f32_16x16x32_bf16 v[84:87], v[134:137], v[222:225], v[84:87]
	v_mfma_f32_16x16x32_bf16 v[88:91], v[120:123], v[230:233], v[88:91]
	v_mfma_f32_16x16x32_bf16 v[92:95], v[134:137], v[230:233], v[92:95]
	v_mfma_f32_16x16x32_bf16 v[96:99], v[140:143], v[190:193], v[96:99]
	v_mfma_f32_16x16x32_bf16 v[100:103], v[182:185], v[190:193], v[100:103]
	v_mfma_f32_16x16x32_bf16 v[104:107], v[140:143], v[198:201], v[104:107]
	v_mfma_f32_16x16x32_bf16 v[40:43], v[182:185], v[198:201], v[40:43]
	v_mfma_f32_16x16x32_bf16 v[44:47], v[140:143], v[218:221], v[44:47]
	v_mfma_f32_16x16x32_bf16 v[48:51], v[182:185], v[218:221], v[48:51]
	v_mfma_f32_16x16x32_bf16 v[52:55], v[140:143], v[226:229], v[52:55]
	v_mfma_f32_16x16x32_bf16 v[56:59], v[182:185], v[226:229], v[56:59]
	v_mfma_f32_16x16x32_bf16 v[96:99], v[144:147], v[194:197], v[96:99]
	v_mfma_f32_16x16x32_bf16 v[100:103], v[186:189], v[194:197], v[100:103]
	v_mfma_f32_16x16x32_bf16 v[104:107], v[144:147], v[202:205], v[104:107]
	v_mfma_f32_16x16x32_bf16 v[40:43], v[186:189], v[202:205], v[40:43]
	v_mfma_f32_16x16x32_bf16 v[44:47], v[144:147], v[222:225], v[44:47]
	v_mfma_f32_16x16x32_bf16 v[48:51], v[186:189], v[222:225], v[48:51]
	v_mfma_f32_16x16x32_bf16 v[52:55], v[144:147], v[230:233], v[52:55]
	v_mfma_f32_16x16x32_bf16 v[56:59], v[186:189], v[230:233], v[56:59]
	s_barrier
	s_mov_b64 s[56:57], 0x280
	s_mov_b32 m0, s55
	v_lshl_add_u64 v[0:1], v[0:1], 0, s[56:57]
	s_add_u32 s26, s26, 0x18280
	ds_read_b128 v[190:193], v139 offset:49152
	ds_read_b128 v[194:197], v139 offset:50176
	ds_read_b128 v[198:201], v139 offset:51200
	ds_read_b128 v[202:205], v139 offset:52224
	ds_read_b128 v[218:221], v139 offset:53248
	ds_read_b128 v[222:225], v139 offset:54272
	ds_read_b128 v[226:229], v139 offset:55296
	ds_read_b128 v[230:233], v139 offset:56320
	global_load_lds_dwordx4 v[0:1], off
	v_lshl_add_u64 v[0:1], v[2:3], 0, s[56:57]
	s_mov_b32 m0, s51
	s_addc_u32 s27, s27, 0
	global_load_lds_dwordx4 v[0:1], off
	v_lshl_add_u64 v[0:1], s[26:27], 0, v[148:149]
	s_mov_b32 m0, s52
	s_nop 0
	global_load_lds_dwordx4 v[0:1], off
	v_lshl_add_u64 v[0:1], s[26:27], 0, v[128:129]
	s_mov_b32 m0, s54
	s_nop 0
	global_load_lds_dwordx4 v[0:1], off
	v_lshl_add_u64 v[0:1], v[4:5], 0, s[56:57]
	s_mov_b32 m0, s42
	s_nop 0
	global_load_lds_dwordx4 v[0:1], off
	v_lshl_add_u64 v[0:1], v[6:7], 0, s[56:57]
	s_mov_b32 m0, s43
	s_nop 0
	global_load_lds_dwordx4 v[0:1], off
	s_waitcnt vmcnt(8)
	s_waitcnt lgkmcnt(0)
	s_barrier
	s_waitcnt lgkmcnt(0)
	v_mfma_f32_16x16x32_bf16 v[0:3], v[116:119], v[190:193], v[158:161]
	v_mfma_f32_16x16x32_bf16 v[4:7], v[124:127], v[190:193], v[162:165]
	v_mfma_f32_16x16x32_bf16 v[12:15], v[116:119], v[226:229], v[12:15]
	v_mfma_f32_16x16x32_bf16 v[16:19], v[124:127], v[226:229], v[16:19]
	v_mfma_f32_16x16x32_bf16 v[0:3], v[120:123], v[194:197], v[0:3]
	v_mfma_f32_16x16x32_bf16 v[4:7], v[134:137], v[194:197], v[4:7]
	v_mfma_f32_16x16x32_bf16 v[158:161], v[116:119], v[198:201], v[166:169]
	v_mfma_f32_16x16x32_bf16 v[162:165], v[124:127], v[198:201], v[170:173]
	v_mfma_f32_16x16x32_bf16 v[166:169], v[116:119], v[218:221], v[174:177]
	v_mfma_f32_16x16x32_bf16 v[170:173], v[124:127], v[218:221], v[178:181]
	v_mfma_f32_16x16x32_bf16 v[12:15], v[120:123], v[230:233], v[12:15]
	v_mfma_f32_16x16x32_bf16 v[16:19], v[134:137], v[230:233], v[16:19]
	v_mfma_f32_16x16x32_bf16 v[158:161], v[120:123], v[202:205], v[158:161]
	v_mfma_f32_16x16x32_bf16 v[162:165], v[134:137], v[202:205], v[162:165]
	v_mfma_f32_16x16x32_bf16 v[166:169], v[120:123], v[222:225], v[166:169]
	v_mfma_f32_16x16x32_bf16 v[170:173], v[134:137], v[222:225], v[170:173]
	v_mfma_f32_16x16x32_bf16 v[20:23], v[140:143], v[190:193], v[20:23]
	v_mfma_f32_16x16x32_bf16 v[32:35], v[182:185], v[190:193], v[32:35]
	v_mfma_f32_16x16x32_bf16 v[36:39], v[140:143], v[198:201], v[36:39]
	v_mfma_f32_16x16x32_bf16 v[60:63], v[182:185], v[198:201], v[60:63]
	v_mfma_f32_16x16x32_bf16 v[108:111], v[140:143], v[218:221], v[108:111]
	v_mfma_f32_16x16x32_bf16 v[112:115], v[182:185], v[218:221], v[112:115]
	v_mfma_f32_16x16x32_bf16 v[24:27], v[140:143], v[226:229], v[24:27]
	v_mfma_f32_16x16x32_bf16 v[28:31], v[182:185], v[226:229], v[28:31]
	v_mfma_f32_16x16x32_bf16 v[20:23], v[144:147], v[194:197], v[20:23]
	v_mfma_f32_16x16x32_bf16 v[32:35], v[186:189], v[194:197], v[32:35]
	v_mfma_f32_16x16x32_bf16 v[36:39], v[144:147], v[202:205], v[36:39]
	v_mfma_f32_16x16x32_bf16 v[60:63], v[186:189], v[202:205], v[60:63]
	v_mfma_f32_16x16x32_bf16 v[108:111], v[144:147], v[222:225], v[108:111]
	v_mfma_f32_16x16x32_bf16 v[112:115], v[186:189], v[222:225], v[112:115]
	v_mfma_f32_16x16x32_bf16 v[24:27], v[144:147], v[230:233], v[24:27]
	v_mfma_f32_16x16x32_bf16 v[28:31], v[186:189], v[230:233], v[28:31]
	s_barrier
	ds_read_b128 v[116:119], v8
	ds_read_b128 v[120:123], v8 offset:1024
	ds_read_b128 v[124:127], v8 offset:2048
	ds_read_b128 v[134:137], v8 offset:3072
	ds_read_b128 v[140:143], v9
	ds_read_b128 v[144:147], v9 offset:1024
	ds_read_b128 v[174:177], v9 offset:2048
	ds_read_b128 v[178:181], v9 offset:3072
	s_add_u32 s24, s24, 0x20280
	s_addc_u32 s25, s25, 0
	s_mov_b32 m0, s53
	v_lshl_add_u64 v[8:9], s[24:25], 0, v[132:133]
	ds_read_b128 v[182:185], v139
	ds_read_b128 v[186:189], v139 offset:1024
	ds_read_b128 v[190:193], v139 offset:2048
	ds_read_b128 v[194:197], v139 offset:3072
	ds_read_b128 v[198:201], v139 offset:4096
	ds_read_b128 v[202:205], v139 offset:5120
	ds_read_b128 v[218:221], v139 offset:6144
	ds_read_b128 v[222:225], v139 offset:7168
	global_load_lds_dwordx4 v[8:9], off
	v_lshl_add_u64 v[8:9], s[24:25], 0, v[130:131]
	s_mov_b32 m0, s19
	s_nop 0
	global_load_lds_dwordx4 v[8:9], off
	s_waitcnt vmcnt(8)
	s_waitcnt lgkmcnt(0)
	s_barrier
	s_waitcnt lgkmcnt(0)
	v_mfma_f32_16x16x32_bf16 v[64:67], v[116:119], v[182:185], v[64:67]
	v_mfma_f32_16x16x32_bf16 v[68:71], v[124:127], v[182:185], v[68:71]
	v_mfma_f32_16x16x32_bf16 v[72:75], v[116:119], v[190:193], v[72:75]
	v_mfma_f32_16x16x32_bf16 v[76:79], v[124:127], v[190:193], v[76:79]
	v_mfma_f32_16x16x32_bf16 v[80:83], v[116:119], v[198:201], v[80:83]
	v_mfma_f32_16x16x32_bf16 v[84:87], v[124:127], v[198:201], v[84:87]
	v_mfma_f32_16x16x32_bf16 v[88:91], v[116:119], v[218:221], v[88:91]
	v_mfma_f32_16x16x32_bf16 v[92:95], v[124:127], v[218:221], v[92:95]
	v_mfma_f32_16x16x32_bf16 v[64:67], v[120:123], v[186:189], v[64:67]
	v_mfma_f32_16x16x32_bf16 v[68:71], v[134:137], v[186:189], v[68:71]
	v_mfma_f32_16x16x32_bf16 v[72:75], v[120:123], v[194:197], v[72:75]
	v_mfma_f32_16x16x32_bf16 v[76:79], v[134:137], v[194:197], v[76:79]
	v_mfma_f32_16x16x32_bf16 v[80:83], v[120:123], v[202:205], v[80:83]
	v_mfma_f32_16x16x32_bf16 v[84:87], v[134:137], v[202:205], v[84:87]
	v_mfma_f32_16x16x32_bf16 v[88:91], v[120:123], v[222:225], v[88:91]
	v_mfma_f32_16x16x32_bf16 v[92:95], v[134:137], v[222:225], v[92:95]
	v_mfma_f32_16x16x32_bf16 v[96:99], v[140:143], v[182:185], v[96:99]
	v_mfma_f32_16x16x32_bf16 v[226:229], v[144:147], v[186:189], v[96:99]
	v_mfma_f32_16x16x32_bf16 v[96:99], v[174:177], v[182:185], v[100:103]
	v_mfma_f32_16x16x32_bf16 v[182:185], v[178:181], v[186:189], v[96:99]
	v_mfma_f32_16x16x32_bf16 v[96:99], v[140:143], v[190:193], v[104:107]
	v_mfma_f32_16x16x32_bf16 v[40:43], v[174:177], v[190:193], v[40:43]
	v_mfma_f32_16x16x32_bf16 v[44:47], v[140:143], v[198:201], v[44:47]
	v_mfma_f32_16x16x32_bf16 v[48:51], v[174:177], v[198:201], v[48:51]
	v_mfma_f32_16x16x32_bf16 v[52:55], v[140:143], v[218:221], v[52:55]
	v_mfma_f32_16x16x32_bf16 v[56:59], v[174:177], v[218:221], v[56:59]
	v_mfma_f32_16x16x32_bf16 v[104:107], v[144:147], v[194:197], v[96:99]
	v_mfma_f32_16x16x32_bf16 v[40:43], v[178:181], v[194:197], v[40:43]
	v_mfma_f32_16x16x32_bf16 v[44:47], v[144:147], v[202:205], v[44:47]
	v_mfma_f32_16x16x32_bf16 v[48:51], v[178:181], v[202:205], v[48:51]
	v_mfma_f32_16x16x32_bf16 v[52:55], v[144:147], v[222:225], v[52:55]
	v_mfma_f32_16x16x32_bf16 v[56:59], v[178:181], v[222:225], v[56:59]
	s_barrier
	s_mov_b32 m0, s50
	v_lshl_add_u64 v[154:155], s[20:21], 0, v[148:149]
	s_add_u32 s24, s20, 0x18000
	ds_read_b128 v[96:99], v139 offset:16384
	ds_read_b128 v[100:103], v139 offset:17408
	ds_read_b128 v[186:189], v139 offset:18432
	ds_read_b128 v[190:193], v139 offset:19456
	ds_read_b128 v[194:197], v139 offset:20480
	ds_read_b128 v[198:201], v139 offset:21504
	ds_read_b128 v[202:205], v139 offset:22528
	ds_read_b128 v[218:221], v139 offset:23552
	global_load_lds_dwordx4 v[154:155], off
	v_lshl_add_u64 v[156:157], s[20:21], 0, v[128:129]
	s_mov_b32 m0, s47
	s_addc_u32 s25, s21, 0
	global_load_lds_dwordx4 v[156:157], off
	v_lshl_add_u64 v[8:9], s[24:25], 0, v[148:149]
	s_mov_b32 m0, s48
	v_lshl_add_u64 v[212:213], s[0:1], 0, v[132:133]
	global_load_lds_dwordx4 v[8:9], off
	v_lshl_add_u64 v[8:9], s[24:25], 0, v[128:129]
	s_mov_b32 m0, s49
	v_lshl_add_u64 v[214:215], s[0:1], 0, v[130:131]
	global_load_lds_dwordx4 v[8:9], off
	s_mov_b32 m0, s36
	s_nop 0
	global_load_lds_dwordx4 v[212:213], off
	s_mov_b32 m0, s37
	s_nop 0
	global_load_lds_dwordx4 v[214:215], off
	s_waitcnt vmcnt(8)
	s_waitcnt lgkmcnt(0)
	s_barrier
	s_waitcnt lgkmcnt(0)
	v_mfma_f32_16x16x32_bf16 v[0:3], v[116:119], v[96:99], v[0:3]
	v_mfma_f32_16x16x32_bf16 v[4:7], v[124:127], v[96:99], v[4:7]
	v_mfma_f32_16x16x32_bf16 v[12:15], v[116:119], v[202:205], v[12:15]
	v_mfma_f32_16x16x32_bf16 v[0:3], v[120:123], v[100:103], v[0:3]
	v_mfma_f32_16x16x32_bf16 v[4:7], v[134:137], v[100:103], v[4:7]
	v_mfma_f32_16x16x32_bf16 v[158:161], v[116:119], v[186:189], v[158:161]
	v_mfma_f32_16x16x32_bf16 v[162:165], v[124:127], v[186:189], v[162:165]
	v_mfma_f32_16x16x32_bf16 v[166:169], v[116:119], v[194:197], v[166:169]
	v_mfma_f32_16x16x32_bf16 v[170:173], v[124:127], v[194:197], v[170:173]
	v_mfma_f32_16x16x32_bf16 v[12:15], v[120:123], v[218:221], v[12:15]
	v_mfma_f32_16x16x32_bf16 v[16:19], v[124:127], v[202:205], v[16:19]
	v_mfma_f32_16x16x32_bf16 v[158:161], v[120:123], v[190:193], v[158:161]
	v_mfma_f32_16x16x32_bf16 v[162:165], v[134:137], v[190:193], v[162:165]
	v_mfma_f32_16x16x32_bf16 v[166:169], v[120:123], v[198:201], v[166:169]
	v_mfma_f32_16x16x32_bf16 v[170:173], v[134:137], v[198:201], v[170:173]
	v_mfma_f32_16x16x32_bf16 v[134:137], v[134:137], v[218:221], v[16:19]
	v_mfma_f32_16x16x32_bf16 v[16:19], v[140:143], v[96:99], v[20:23]
	v_mfma_f32_16x16x32_bf16 v[222:225], v[144:147], v[100:103], v[16:19]
	v_mfma_f32_16x16x32_bf16 v[16:19], v[174:177], v[96:99], v[32:35]
	v_mfma_f32_16x16x32_bf16 v[230:233], v[178:181], v[100:103], v[16:19]
	v_mfma_f32_16x16x32_bf16 v[16:19], v[140:143], v[186:189], v[36:39]
	v_mfma_f32_16x16x32_bf16 v[234:237], v[144:147], v[190:193], v[16:19]
	v_mfma_f32_16x16x32_bf16 v[16:19], v[174:177], v[186:189], v[60:63]
	v_mfma_f32_16x16x32_bf16 v[186:189], v[178:181], v[190:193], v[16:19]
	v_mfma_f32_16x16x32_bf16 v[16:19], v[140:143], v[194:197], v[108:111]
	v_mfma_f32_16x16x32_bf16 v[190:193], v[144:147], v[198:201], v[16:19]
	v_mfma_f32_16x16x32_bf16 v[16:19], v[174:177], v[194:197], v[112:115]
	v_mfma_f32_16x16x32_bf16 v[194:197], v[178:181], v[198:201], v[16:19]
	v_mfma_f32_16x16x32_bf16 v[16:19], v[140:143], v[202:205], v[24:27]
	v_mfma_f32_16x16x32_bf16 v[140:143], v[144:147], v[218:221], v[16:19]
	v_mfma_f32_16x16x32_bf16 v[16:19], v[174:177], v[202:205], v[28:31]
	v_mfma_f32_16x16x32_bf16 v[144:147], v[178:181], v[218:221], v[16:19]
	s_barrier
	ds_read_b128 v[24:27], v10
	ds_read_b128 v[28:31], v10 offset:1024
	ds_read_b128 v[60:63], v10 offset:2048
	ds_read_b128 v[174:177], v10 offset:3072
	ds_read_b128 v[178:181], v11
	ds_read_b128 v[198:201], v11 offset:1024
	ds_read_b128 v[202:205], v11 offset:2048
	ds_read_b128 v[218:221], v11 offset:3072
	s_add_u32 s0, s0, 0x20000
	s_addc_u32 s1, s1, 0
	s_mov_b32 m0, s38
	v_lshl_add_u64 v[96:97], s[0:1], 0, v[132:133]
	ds_read_b128 v[8:11], v139 offset:32768
	ds_read_b128 v[16:19], v139 offset:33792
	ds_read_b128 v[20:23], v139 offset:34816
	ds_read_b128 v[32:35], v139 offset:35840
	ds_read_b128 v[36:39], v139 offset:36864
	ds_read_b128 v[238:241], v139 offset:37888
	ds_read_b128 v[242:245], v139 offset:38912
	ds_read_b128 v[246:249], v139 offset:39936
	global_load_lds_dwordx4 v[96:97], off
	v_lshl_add_u64 v[96:97], s[0:1], 0, v[130:131]
	s_mov_b32 m0, s39
	s_nop 0
	global_load_lds_dwordx4 v[96:97], off
	s_waitcnt vmcnt(8)
	s_waitcnt lgkmcnt(0)
	s_barrier
	s_waitcnt lgkmcnt(0)
	v_mfma_f32_16x16x32_bf16 v[64:67], v[24:27], v[8:11], v[64:67]
	v_mfma_f32_16x16x32_bf16 v[112:115], v[28:31], v[16:19], v[64:67]
	v_mfma_f32_16x16x32_bf16 v[64:67], v[60:63], v[8:11], v[68:71]
	v_mfma_f32_16x16x32_bf16 v[116:119], v[174:177], v[16:19], v[64:67]
	v_mfma_f32_16x16x32_bf16 v[64:67], v[24:27], v[20:23], v[72:75]
	v_mfma_f32_16x16x32_bf16 v[96:99], v[28:31], v[32:35], v[64:67]
	v_mfma_f32_16x16x32_bf16 v[64:67], v[60:63], v[20:23], v[76:79]
	v_mfma_f32_16x16x32_bf16 v[100:103], v[174:177], v[32:35], v[64:67]
	v_mfma_f32_16x16x32_bf16 v[64:67], v[24:27], v[36:39], v[80:83]
	v_mfma_f32_16x16x32_bf16 v[80:83], v[28:31], v[238:241], v[64:67]
	v_mfma_f32_16x16x32_bf16 v[64:67], v[60:63], v[36:39], v[84:87]
	v_mfma_f32_16x16x32_bf16 v[84:87], v[174:177], v[238:241], v[64:67]
	v_mfma_f32_16x16x32_bf16 v[64:67], v[24:27], v[242:245], v[88:91]
	v_mfma_f32_16x16x32_bf16 v[68:71], v[60:63], v[242:245], v[92:95]
	v_mfma_f32_16x16x32_bf16 v[64:67], v[28:31], v[246:249], v[64:67]
	v_mfma_f32_16x16x32_bf16 v[68:71], v[174:177], v[246:249], v[68:71]
	v_mfma_f32_16x16x32_bf16 v[72:75], v[178:181], v[8:11], v[226:229]
	v_mfma_f32_16x16x32_bf16 v[8:11], v[202:205], v[8:11], v[182:185]
	v_mfma_f32_16x16x32_bf16 v[124:127], v[218:221], v[16:19], v[8:11]
	v_mfma_f32_16x16x32_bf16 v[8:11], v[178:181], v[20:23], v[104:107]
	v_mfma_f32_16x16x32_bf16 v[104:107], v[198:201], v[32:35], v[8:11]
	v_mfma_f32_16x16x32_bf16 v[8:11], v[202:205], v[20:23], v[40:43]
	v_mfma_f32_16x16x32_bf16 v[108:111], v[218:221], v[32:35], v[8:11]
	v_mfma_f32_16x16x32_bf16 v[8:11], v[178:181], v[36:39], v[44:47]
	v_mfma_f32_16x16x32_bf16 v[88:91], v[198:201], v[238:241], v[8:11]
	v_mfma_f32_16x16x32_bf16 v[8:11], v[202:205], v[36:39], v[48:51]
	v_mfma_f32_16x16x32_bf16 v[92:95], v[218:221], v[238:241], v[8:11]
	v_mfma_f32_16x16x32_bf16 v[8:11], v[178:181], v[242:245], v[52:55]
	v_mfma_f32_16x16x32_bf16 v[120:123], v[198:201], v[16:19], v[72:75]
	v_mfma_f32_16x16x32_bf16 v[72:75], v[198:201], v[246:249], v[8:11]
	v_mfma_f32_16x16x32_bf16 v[8:11], v[202:205], v[242:245], v[56:59]
	v_mfma_f32_16x16x32_bf16 v[76:79], v[218:221], v[246:249], v[8:11]
	s_barrier
	s_mov_b32 m0, s55
	v_lshl_add_u64 v[16:17], v[154:155], 0, s[28:29]
	s_add_u32 s0, s20, 0x18080
	s_nop 1
	ds_read_b128 v[8:11], v139 offset:49152
	ds_read_b128 v[40:43], v139 offset:50176
	ds_read_b128 v[44:47], v139 offset:51200
	ds_read_b128 v[182:185], v139 offset:52224
	ds_read_b128 v[226:229], v139 offset:53248
	ds_read_b128 v[238:241], v139 offset:54272
	ds_read_b128 v[242:245], v139 offset:55296
	ds_read_b128 v[246:249], v139 offset:56320
	global_load_lds_dwordx4 v[16:17], off
	v_lshl_add_u64 v[16:17], v[156:157], 0, s[28:29]
	s_mov_b32 m0, s51
	s_addc_u32 s1, s21, 0
	global_load_lds_dwordx4 v[16:17], off
	v_lshl_add_u64 v[16:17], s[0:1], 0, v[148:149]
	s_mov_b32 m0, s52
	s_nop 0
	global_load_lds_dwordx4 v[16:17], off
	v_lshl_add_u64 v[16:17], s[0:1], 0, v[128:129]
	s_mov_b32 m0, s54
	s_nop 0
	global_load_lds_dwordx4 v[16:17], off
	v_lshl_add_u64 v[16:17], v[212:213], 0, s[28:29]
	s_mov_b32 m0, s42
	s_nop 0
	global_load_lds_dwordx4 v[16:17], off
	v_lshl_add_u64 v[16:17], v[214:215], 0, s[28:29]
	s_mov_b32 m0, s43
	s_nop 0
	global_load_lds_dwordx4 v[16:17], off
	s_waitcnt vmcnt(8)
	s_waitcnt lgkmcnt(0)
	s_barrier
	s_waitcnt lgkmcnt(0)
	v_mfma_f32_16x16x32_bf16 v[0:3], v[24:27], v[8:11], v[0:3]
	v_mfma_f32_16x16x32_bf16 v[48:51], v[28:31], v[40:43], v[0:3]
	v_mfma_f32_16x16x32_bf16 v[0:3], v[60:63], v[8:11], v[4:7]
	v_mfma_f32_16x16x32_bf16 v[52:55], v[174:177], v[40:43], v[0:3]
	v_mfma_f32_16x16x32_bf16 v[0:3], v[24:27], v[44:47], v[158:161]
	v_mfma_f32_16x16x32_bf16 v[32:35], v[28:31], v[182:185], v[0:3]
	v_mfma_f32_16x16x32_bf16 v[0:3], v[60:63], v[44:47], v[162:165]
	v_mfma_f32_16x16x32_bf16 v[36:39], v[174:177], v[182:185], v[0:3]
	v_mfma_f32_16x16x32_bf16 v[0:3], v[24:27], v[226:229], v[166:169]
	v_mfma_f32_16x16x32_bf16 v[16:19], v[28:31], v[238:241], v[0:3]
	v_mfma_f32_16x16x32_bf16 v[0:3], v[60:63], v[226:229], v[170:173]
	v_mfma_f32_16x16x32_bf16 v[20:23], v[174:177], v[238:241], v[0:3]
	v_mfma_f32_16x16x32_bf16 v[0:3], v[24:27], v[242:245], v[12:15]
	v_mfma_f32_16x16x32_bf16 v[4:7], v[60:63], v[242:245], v[134:137]
	v_mfma_f32_16x16x32_bf16 v[0:3], v[28:31], v[246:249], v[0:3]
	v_mfma_f32_16x16x32_bf16 v[4:7], v[174:177], v[246:249], v[4:7]
	v_mfma_f32_16x16x32_bf16 v[12:15], v[178:181], v[8:11], v[222:225]
	v_mfma_f32_16x16x32_bf16 v[8:11], v[202:205], v[8:11], v[230:233]
	v_mfma_f32_16x16x32_bf16 v[60:63], v[218:221], v[40:43], v[8:11]
	v_mfma_f32_16x16x32_bf16 v[8:11], v[178:181], v[44:47], v[234:237]
	v_mfma_f32_16x16x32_bf16 v[56:59], v[198:201], v[40:43], v[12:15]
	v_mfma_f32_16x16x32_bf16 v[40:43], v[198:201], v[182:185], v[8:11]
	v_mfma_f32_16x16x32_bf16 v[8:11], v[202:205], v[44:47], v[186:189]
	v_mfma_f32_16x16x32_bf16 v[44:47], v[218:221], v[182:185], v[8:11]
	v_mfma_f32_16x16x32_bf16 v[8:11], v[178:181], v[226:229], v[190:193]
	v_mfma_f32_16x16x32_bf16 v[24:27], v[198:201], v[238:241], v[8:11]
	v_mfma_f32_16x16x32_bf16 v[8:11], v[202:205], v[226:229], v[194:197]
	v_mfma_f32_16x16x32_bf16 v[28:31], v[218:221], v[238:241], v[8:11]
	v_mfma_f32_16x16x32_bf16 v[8:11], v[178:181], v[242:245], v[140:143]
	v_mfma_f32_16x16x32_bf16 v[12:15], v[202:205], v[242:245], v[144:147]
	v_mfma_f32_16x16x32_bf16 v[8:11], v[198:201], v[246:249], v[8:11]
	v_mfma_f32_16x16x32_bf16 v[12:15], v[218:221], v[246:249], v[12:15]
	s_barrier
	s_andn2_b64 vcc, exec, s[14:15]
	s_cbranch_vccnz .LBB0_855
	s_barrier

.LBB0_871:
	s_ashr_i32 s19, s18, 31
	s_lshl_b64 s[20:21], s[18:19], 17
	s_add_u32 s20, s33, s20
	s_addc_u32 s21, s36, s21
	s_and_b64 s[22:23], s[0:1], exec
	s_cselect_b32 s35, s21, s25
	s_cselect_b32 s34, s20, s24
	s_ashr_i32 s17, s16, 31
	s_lshl_b64 s[22:23], s[16:17], 17
	s_add_u32 s22, s37, s22
	s_addc_u32 s23, s38, s23
	s_and_b64 s[30:31], s[0:1], exec
	s_cselect_b32 s31, s23, s27
	s_cselect_b32 s30, s22, s26
	s_add_i32 s52, 0, 0x10000
	s_add_i32 s53, 0, 0x14000
	v_add_u32_e32 v150, s52, v138
	v_add_u32_e32 v151, s53, v138
	ds_read_b128 v[0:3], v150
	ds_read_b128 v[4:7], v150 offset:1024
	ds_read_b128 v[8:11], v150 offset:2048
	ds_read_b128 v[12:15], v150 offset:3072
	ds_read_b128 v[16:19], v151
	ds_read_b128 v[20:23], v151 offset:1024
	ds_read_b128 v[24:27], v151 offset:2048
	ds_read_b128 v[28:31], v151 offset:3072
	s_add_u32 s50, s24, 0x10080
	s_addc_u32 s51, s25, 0
	s_add_i32 s54, s40, 0xc000
	v_lshl_add_u64 v[64:65], s[50:51], 0, v[132:133]
	s_mov_b32 m0, s54
	s_add_i32 s17, s40, 0xe000
	ds_read_b128 v[32:35], v139
	ds_read_b128 v[36:39], v139 offset:1024
	ds_read_b128 v[40:43], v139 offset:2048
	ds_read_b128 v[44:47], v139 offset:3072
	ds_read_b128 v[48:51], v139 offset:4096
	ds_read_b128 v[52:55], v139 offset:5120
	ds_read_b128 v[56:59], v139 offset:6144
	ds_read_b128 v[60:63], v139 offset:7168
	global_load_lds_dwordx4 v[64:65], off
	v_lshl_add_u64 v[64:65], s[50:51], 0, v[130:131]
	s_mov_b32 m0, s17
	s_nop 0
	global_load_lds_dwordx4 v[64:65], off
	s_waitcnt vmcnt(8)
	s_waitcnt lgkmcnt(0)
	s_barrier
	s_waitcnt lgkmcnt(0)
	v_mfma_f32_16x16x32_bf16 v[64:67], v[0:3], v[32:35], 0
	v_mfma_f32_16x16x32_bf16 v[68:71], v[8:11], v[32:35], 0
	v_mfma_f32_16x16x32_bf16 v[72:75], v[0:3], v[40:43], 0
	v_mfma_f32_16x16x32_bf16 v[76:79], v[8:11], v[40:43], 0
	v_mfma_f32_16x16x32_bf16 v[80:83], v[0:3], v[48:51], 0
	v_mfma_f32_16x16x32_bf16 v[84:87], v[8:11], v[48:51], 0
	v_mfma_f32_16x16x32_bf16 v[88:91], v[0:3], v[56:59], 0
	v_mfma_f32_16x16x32_bf16 v[92:95], v[8:11], v[56:59], 0
	v_mfma_f32_16x16x32_bf16 v[64:67], v[4:7], v[36:39], v[64:67]
	v_mfma_f32_16x16x32_bf16 v[68:71], v[12:15], v[36:39], v[68:71]
	v_mfma_f32_16x16x32_bf16 v[72:75], v[4:7], v[44:47], v[72:75]
	v_mfma_f32_16x16x32_bf16 v[76:79], v[12:15], v[44:47], v[76:79]
	v_mfma_f32_16x16x32_bf16 v[80:83], v[4:7], v[52:55], v[80:83]
	v_mfma_f32_16x16x32_bf16 v[84:87], v[12:15], v[52:55], v[84:87]
	v_mfma_f32_16x16x32_bf16 v[88:91], v[4:7], v[60:63], v[88:91]
	v_mfma_f32_16x16x32_bf16 v[92:95], v[12:15], v[60:63], v[92:95]
	v_mfma_f32_16x16x32_bf16 v[96:99], v[16:19], v[32:35], 0
	v_mfma_f32_16x16x32_bf16 v[32:35], v[24:27], v[32:35], 0
	v_mfma_f32_16x16x32_bf16 v[96:99], v[20:23], v[36:39], v[96:99]
	v_mfma_f32_16x16x32_bf16 v[32:35], v[28:31], v[36:39], v[32:35]
	v_mfma_f32_16x16x32_bf16 v[36:39], v[16:19], v[40:43], 0
	v_mfma_f32_16x16x32_bf16 v[40:43], v[24:27], v[40:43], 0
	v_mfma_f32_16x16x32_bf16 v[36:39], v[20:23], v[44:47], v[36:39]
	v_mfma_f32_16x16x32_bf16 v[40:43], v[28:31], v[44:47], v[40:43]
	v_mfma_f32_16x16x32_bf16 v[44:47], v[16:19], v[48:51], 0
	v_mfma_f32_16x16x32_bf16 v[48:51], v[24:27], v[48:51], 0
	v_mfma_f32_16x16x32_bf16 v[44:47], v[20:23], v[52:55], v[44:47]
	v_mfma_f32_16x16x32_bf16 v[48:51], v[28:31], v[52:55], v[48:51]
	v_mfma_f32_16x16x32_bf16 v[52:55], v[16:19], v[56:59], 0
	v_mfma_f32_16x16x32_bf16 v[56:59], v[24:27], v[56:59], 0
	v_mfma_f32_16x16x32_bf16 v[52:55], v[20:23], v[60:63], v[52:55]
	v_mfma_f32_16x16x32_bf16 v[56:59], v[28:31], v[60:63], v[56:59]
	s_barrier
	s_add_i32 s52, s52, s39
	v_lshl_add_u64 v[154:155], s[26:27], 0, v[148:149]
	s_mov_b64 s[60:61], 0x100
	s_add_i32 s19, s52, 0x2000
	v_lshl_add_u64 v[134:135], v[154:155], 0, s[60:61]
	s_mov_b32 m0, s52
	v_lshl_add_u64 v[156:157], s[26:27], 0, v[128:129]
	s_add_u32 s56, s26, 0x10100
	ds_read_b128 v[60:63], v139 offset:16384
	ds_read_b128 v[100:103], v139 offset:17408
	ds_read_b128 v[104:107], v139 offset:18432
	ds_read_b128 v[108:111], v139 offset:19456
	ds_read_b128 v[112:115], v139 offset:20480
	ds_read_b128 v[116:119], v139 offset:21504
	ds_read_b128 v[120:123], v139 offset:22528
	ds_read_b128 v[124:127], v139 offset:23552
	global_load_lds_dwordx4 v[134:135], off
	v_lshl_add_u64 v[134:135], v[156:157], 0, s[60:61]
	s_mov_b32 m0, s19
	s_addc_u32 s57, s27, 0
	s_add_i32 s50, s53, s39
	global_load_lds_dwordx4 v[134:135], off
	v_lshl_add_u64 v[134:135], s[56:57], 0, v[148:149]
	s_mov_b32 m0, s50
	s_add_i32 s51, s50, 0x2000
	global_load_lds_dwordx4 v[134:135], off
	v_lshl_add_u64 v[134:135], s[56:57], 0, v[128:129]
	s_mov_b32 m0, s51
	v_lshl_add_u64 v[212:213], s[24:25], 0, v[132:133]
	global_load_lds_dwordx4 v[134:135], off
	v_lshl_add_u64 v[134:135], v[212:213], 0, s[60:61]
	s_mov_b32 m0, s40
	v_lshl_add_u64 v[214:215], s[24:25], 0, v[130:131]
	global_load_lds_dwordx4 v[134:135], off
	v_lshl_add_u64 v[134:135], v[214:215], 0, s[60:61]
	s_mov_b32 m0, s41
	s_nop 0
	global_load_lds_dwordx4 v[134:135], off
	s_waitcnt vmcnt(8)
	s_waitcnt lgkmcnt(0)
	s_barrier
	s_waitcnt lgkmcnt(0)
	v_mfma_f32_16x16x32_bf16 v[134:137], v[0:3], v[60:63], 0
	v_mfma_f32_16x16x32_bf16 v[144:147], v[0:3], v[104:107], 0
	v_mfma_f32_16x16x32_bf16 v[162:165], v[0:3], v[112:115], 0
	v_mfma_f32_16x16x32_bf16 v[0:3], v[0:3], v[120:123], 0
	v_mfma_f32_16x16x32_bf16 v[134:137], v[4:7], v[100:103], v[134:137]
	v_mfma_f32_16x16x32_bf16 v[144:147], v[4:7], v[108:111], v[144:147]
	v_mfma_f32_16x16x32_bf16 v[162:165], v[4:7], v[116:119], v[162:165]
	v_mfma_f32_16x16x32_bf16 v[0:3], v[4:7], v[124:127], v[0:3]
	v_mfma_f32_16x16x32_bf16 v[4:7], v[8:11], v[120:123], 0
	v_mfma_f32_16x16x32_bf16 v[140:143], v[8:11], v[60:63], 0
	v_mfma_f32_16x16x32_bf16 v[158:161], v[8:11], v[104:107], 0
	v_mfma_f32_16x16x32_bf16 v[166:169], v[8:11], v[112:115], 0
	v_mfma_f32_16x16x32_bf16 v[4:7], v[12:15], v[124:127], v[4:7]
	v_mfma_f32_16x16x32_bf16 v[140:143], v[12:15], v[100:103], v[140:143]
	v_mfma_f32_16x16x32_bf16 v[158:161], v[12:15], v[108:111], v[158:161]
	v_mfma_f32_16x16x32_bf16 v[166:169], v[12:15], v[116:119], v[166:169]
	v_mfma_f32_16x16x32_bf16 v[8:11], v[16:19], v[60:63], 0
	v_mfma_f32_16x16x32_bf16 v[12:15], v[24:27], v[60:63], 0
	v_mfma_f32_16x16x32_bf16 v[8:11], v[20:23], v[100:103], v[8:11]
	v_mfma_f32_16x16x32_bf16 v[12:15], v[28:31], v[100:103], v[12:15]
	v_mfma_f32_16x16x32_bf16 v[60:63], v[16:19], v[104:107], 0
	v_mfma_f32_16x16x32_bf16 v[100:103], v[24:27], v[104:107], 0
	v_mfma_f32_16x16x32_bf16 v[104:107], v[16:19], v[112:115], 0
	v_mfma_f32_16x16x32_bf16 v[16:19], v[16:19], v[120:123], 0
	v_mfma_f32_16x16x32_bf16 v[60:63], v[20:23], v[108:111], v[60:63]
	v_mfma_f32_16x16x32_bf16 v[100:103], v[28:31], v[108:111], v[100:103]
	v_mfma_f32_16x16x32_bf16 v[104:107], v[20:23], v[116:119], v[104:107]
	v_mfma_f32_16x16x32_bf16 v[108:111], v[24:27], v[112:115], 0
	v_mfma_f32_16x16x32_bf16 v[16:19], v[20:23], v[124:127], v[16:19]
	v_mfma_f32_16x16x32_bf16 v[20:23], v[24:27], v[120:123], 0
	v_mfma_f32_16x16x32_bf16 v[108:111], v[28:31], v[116:119], v[108:111]
	v_mfma_f32_16x16x32_bf16 v[20:23], v[28:31], v[124:127], v[20:23]
	s_barrier
	s_add_i32 s55, 0, 0x18000
	s_add_i32 s58, 0, 0x1c000
	v_add_u32_e32 v152, s55, v138
	v_add_u32_e32 v153, s58, v138
	ds_read_b128 v[24:27], v152
	ds_read_b128 v[28:31], v152 offset:1024
	ds_read_b128 v[112:115], v152 offset:2048
	ds_read_b128 v[116:119], v152 offset:3072
	ds_read_b128 v[120:123], v153
	ds_read_b128 v[124:127], v153 offset:1024
	ds_read_b128 v[170:173], v153 offset:2048
	ds_read_b128 v[174:177], v153 offset:3072
	s_add_u32 s56, s24, 0x10100
	s_addc_u32 s57, s25, 0
	s_mov_b32 m0, s42
	v_lshl_add_u64 v[222:223], s[56:57], 0, v[132:133]
	ds_read_b128 v[178:181], v139 offset:32768
	ds_read_b128 v[182:185], v139 offset:33792
	ds_read_b128 v[186:189], v139 offset:34816
	ds_read_b128 v[190:193], v139 offset:35840
	ds_read_b128 v[194:197], v139 offset:36864
	ds_read_b128 v[198:201], v139 offset:37888
	ds_read_b128 v[202:205], v139 offset:38912
	ds_read_b128 v[218:221], v139 offset:39936
	global_load_lds_dwordx4 v[222:223], off
	v_lshl_add_u64 v[222:223], s[56:57], 0, v[130:131]
	s_mov_b32 m0, s43
	s_nop 0
	global_load_lds_dwordx4 v[222:223], off
	s_waitcnt vmcnt(8)
	s_waitcnt lgkmcnt(0)
	s_barrier
	s_waitcnt lgkmcnt(0)
	v_mfma_f32_16x16x32_bf16 v[64:67], v[24:27], v[178:181], v[64:67]
	v_mfma_f32_16x16x32_bf16 v[68:71], v[112:115], v[178:181], v[68:71]
	v_mfma_f32_16x16x32_bf16 v[72:75], v[24:27], v[186:189], v[72:75]
	v_mfma_f32_16x16x32_bf16 v[76:79], v[112:115], v[186:189], v[76:79]
	v_mfma_f32_16x16x32_bf16 v[80:83], v[24:27], v[194:197], v[80:83]
	v_mfma_f32_16x16x32_bf16 v[84:87], v[112:115], v[194:197], v[84:87]
	v_mfma_f32_16x16x32_bf16 v[88:91], v[24:27], v[202:205], v[88:91]
	v_mfma_f32_16x16x32_bf16 v[92:95], v[112:115], v[202:205], v[92:95]
	v_mfma_f32_16x16x32_bf16 v[64:67], v[28:31], v[182:185], v[64:67]
	v_mfma_f32_16x16x32_bf16 v[68:71], v[116:119], v[182:185], v[68:71]
	v_mfma_f32_16x16x32_bf16 v[72:75], v[28:31], v[190:193], v[72:75]
	v_mfma_f32_16x16x32_bf16 v[76:79], v[116:119], v[190:193], v[76:79]
	v_mfma_f32_16x16x32_bf16 v[80:83], v[28:31], v[198:201], v[80:83]
	v_mfma_f32_16x16x32_bf16 v[84:87], v[116:119], v[198:201], v[84:87]
	v_mfma_f32_16x16x32_bf16 v[88:91], v[28:31], v[218:221], v[88:91]
	v_mfma_f32_16x16x32_bf16 v[92:95], v[116:119], v[218:221], v[92:95]
	v_mfma_f32_16x16x32_bf16 v[96:99], v[120:123], v[178:181], v[96:99]
	v_mfma_f32_16x16x32_bf16 v[32:35], v[170:173], v[178:181], v[32:35]
	v_mfma_f32_16x16x32_bf16 v[36:39], v[120:123], v[186:189], v[36:39]
	v_mfma_f32_16x16x32_bf16 v[40:43], v[170:173], v[186:189], v[40:43]
	v_mfma_f32_16x16x32_bf16 v[44:47], v[120:123], v[194:197], v[44:47]
	v_mfma_f32_16x16x32_bf16 v[48:51], v[170:173], v[194:197], v[48:51]
	v_mfma_f32_16x16x32_bf16 v[52:55], v[120:123], v[202:205], v[52:55]
	v_mfma_f32_16x16x32_bf16 v[56:59], v[170:173], v[202:205], v[56:59]
	v_mfma_f32_16x16x32_bf16 v[96:99], v[124:127], v[182:185], v[96:99]
	v_mfma_f32_16x16x32_bf16 v[32:35], v[174:177], v[182:185], v[32:35]
	v_mfma_f32_16x16x32_bf16 v[36:39], v[124:127], v[190:193], v[36:39]
	v_mfma_f32_16x16x32_bf16 v[40:43], v[174:177], v[190:193], v[40:43]
	v_mfma_f32_16x16x32_bf16 v[44:47], v[124:127], v[198:201], v[44:47]
	v_mfma_f32_16x16x32_bf16 v[48:51], v[174:177], v[198:201], v[48:51]
	v_mfma_f32_16x16x32_bf16 v[52:55], v[124:127], v[218:221], v[52:55]
	v_mfma_f32_16x16x32_bf16 v[56:59], v[174:177], v[218:221], v[56:59]
	s_barrier
	s_add_i32 s55, s55, s39
	s_mov_b64 s[60:61], 0x180
	s_add_i32 s53, s55, 0x2000
	v_lshl_add_u64 v[154:155], v[154:155], 0, s[60:61]
	s_mov_b32 m0, s55
	s_add_u32 s56, s26, 0x10180
	ds_read_b128 v[178:181], v139 offset:49152
	ds_read_b128 v[182:185], v139 offset:50176
	ds_read_b128 v[186:189], v139 offset:51200
	ds_read_b128 v[190:193], v139 offset:52224
	ds_read_b128 v[194:197], v139 offset:53248
	ds_read_b128 v[198:201], v139 offset:54272
	ds_read_b128 v[202:205], v139 offset:55296
	ds_read_b128 v[218:221], v139 offset:56320
	global_load_lds_dwordx4 v[154:155], off
	v_lshl_add_u64 v[154:155], v[156:157], 0, s[60:61]
	s_mov_b32 m0, s53
	s_addc_u32 s57, s27, 0
	s_add_i32 s26, s58, s39
	global_load_lds_dwordx4 v[154:155], off
	v_lshl_add_u64 v[154:155], s[56:57], 0, v[148:149]
	s_mov_b32 m0, s26
	s_add_i32 s27, s26, 0x2000
	global_load_lds_dwordx4 v[154:155], off
	v_lshl_add_u64 v[154:155], s[56:57], 0, v[128:129]
	s_mov_b32 m0, s27
	s_nop 0
	global_load_lds_dwordx4 v[154:155], off
	v_lshl_add_u64 v[154:155], v[212:213], 0, s[60:61]
	s_mov_b32 m0, s46
	s_nop 0
	global_load_lds_dwordx4 v[154:155], off
	v_lshl_add_u64 v[154:155], v[214:215], 0, s[60:61]
	s_mov_b32 m0, s47
	s_nop 0
	global_load_lds_dwordx4 v[154:155], off
	s_waitcnt vmcnt(8)
	s_waitcnt lgkmcnt(0)
	s_barrier
	s_waitcnt lgkmcnt(0)
	v_mfma_f32_16x16x32_bf16 v[0:3], v[24:27], v[202:205], v[0:3]
	v_mfma_f32_16x16x32_bf16 v[4:7], v[112:115], v[202:205], v[4:7]
	v_mfma_f32_16x16x32_bf16 v[134:137], v[24:27], v[178:181], v[134:137]
	v_mfma_f32_16x16x32_bf16 v[140:143], v[112:115], v[178:181], v[140:143]
	v_mfma_f32_16x16x32_bf16 v[144:147], v[24:27], v[186:189], v[144:147]
	v_mfma_f32_16x16x32_bf16 v[158:161], v[112:115], v[186:189], v[158:161]
	v_mfma_f32_16x16x32_bf16 v[162:165], v[24:27], v[194:197], v[162:165]
	v_mfma_f32_16x16x32_bf16 v[166:169], v[112:115], v[194:197], v[166:169]
	v_mfma_f32_16x16x32_bf16 v[0:3], v[28:31], v[218:221], v[0:3]
	v_mfma_f32_16x16x32_bf16 v[4:7], v[116:119], v[218:221], v[4:7]
	v_mfma_f32_16x16x32_bf16 v[134:137], v[28:31], v[182:185], v[134:137]
	v_mfma_f32_16x16x32_bf16 v[140:143], v[116:119], v[182:185], v[140:143]
	v_mfma_f32_16x16x32_bf16 v[144:147], v[28:31], v[190:193], v[144:147]
	v_mfma_f32_16x16x32_bf16 v[158:161], v[116:119], v[190:193], v[158:161]
	v_mfma_f32_16x16x32_bf16 v[162:165], v[28:31], v[198:201], v[162:165]
	v_mfma_f32_16x16x32_bf16 v[166:169], v[116:119], v[198:201], v[166:169]
	v_mfma_f32_16x16x32_bf16 v[8:11], v[120:123], v[178:181], v[8:11]
	v_mfma_f32_16x16x32_bf16 v[12:15], v[170:173], v[178:181], v[12:15]
	v_mfma_f32_16x16x32_bf16 v[24:27], v[120:123], v[186:189], v[60:63]
	v_mfma_f32_16x16x32_bf16 v[28:31], v[170:173], v[186:189], v[100:103]
	v_mfma_f32_16x16x32_bf16 v[60:63], v[120:123], v[194:197], v[104:107]
	v_mfma_f32_16x16x32_bf16 v[100:103], v[170:173], v[194:197], v[108:111]
	v_mfma_f32_16x16x32_bf16 v[16:19], v[120:123], v[202:205], v[16:19]
	v_mfma_f32_16x16x32_bf16 v[20:23], v[170:173], v[202:205], v[20:23]
	v_mfma_f32_16x16x32_bf16 v[8:11], v[124:127], v[182:185], v[8:11]
	v_mfma_f32_16x16x32_bf16 v[12:15], v[174:177], v[182:185], v[12:15]
	v_mfma_f32_16x16x32_bf16 v[24:27], v[124:127], v[190:193], v[24:27]
	v_mfma_f32_16x16x32_bf16 v[28:31], v[174:177], v[190:193], v[28:31]
	v_mfma_f32_16x16x32_bf16 v[60:63], v[124:127], v[198:201], v[60:63]
	v_mfma_f32_16x16x32_bf16 v[100:103], v[174:177], v[198:201], v[100:103]
	v_mfma_f32_16x16x32_bf16 v[16:19], v[124:127], v[218:221], v[16:19]
	v_mfma_f32_16x16x32_bf16 v[20:23], v[174:177], v[218:221], v[20:23]
	s_barrier
	ds_read_b128 v[104:107], v150
	ds_read_b128 v[108:111], v150 offset:1024
	ds_read_b128 v[112:115], v150 offset:2048
	ds_read_b128 v[116:119], v150 offset:3072
	ds_read_b128 v[120:123], v151
	ds_read_b128 v[124:127], v151 offset:1024
	ds_read_b128 v[170:173], v151 offset:2048
	ds_read_b128 v[174:177], v151 offset:3072
	s_add_u32 s24, s24, 0x10180
	s_addc_u32 s25, s25, 0
	s_mov_b32 m0, s54
	v_lshl_add_u64 v[154:155], s[24:25], 0, v[132:133]
	ds_read_b128 v[178:181], v139
	ds_read_b128 v[182:185], v139 offset:1024
	ds_read_b128 v[186:189], v139 offset:2048
	ds_read_b128 v[190:193], v139 offset:3072
	ds_read_b128 v[194:197], v139 offset:4096
	ds_read_b128 v[198:201], v139 offset:5120
	ds_read_b128 v[202:205], v139 offset:6144
	ds_read_b128 v[218:221], v139 offset:7168
	global_load_lds_dwordx4 v[154:155], off
	v_lshl_add_u64 v[154:155], s[24:25], 0, v[130:131]
	s_mov_b32 m0, s17
	s_nop 0
	global_load_lds_dwordx4 v[154:155], off
	s_waitcnt vmcnt(8)
	s_waitcnt lgkmcnt(0)
	s_barrier
	s_waitcnt lgkmcnt(0)
	v_mfma_f32_16x16x32_bf16 v[64:67], v[104:107], v[178:181], v[64:67]
	v_mfma_f32_16x16x32_bf16 v[68:71], v[112:115], v[178:181], v[68:71]
	v_mfma_f32_16x16x32_bf16 v[72:75], v[104:107], v[186:189], v[72:75]
	v_mfma_f32_16x16x32_bf16 v[76:79], v[112:115], v[186:189], v[76:79]
	v_mfma_f32_16x16x32_bf16 v[80:83], v[104:107], v[194:197], v[80:83]
	v_mfma_f32_16x16x32_bf16 v[84:87], v[112:115], v[194:197], v[84:87]
	v_mfma_f32_16x16x32_bf16 v[88:91], v[104:107], v[202:205], v[88:91]
	v_mfma_f32_16x16x32_bf16 v[92:95], v[112:115], v[202:205], v[92:95]
	v_mfma_f32_16x16x32_bf16 v[64:67], v[108:111], v[182:185], v[64:67]
	v_mfma_f32_16x16x32_bf16 v[68:71], v[116:119], v[182:185], v[68:71]
	v_mfma_f32_16x16x32_bf16 v[72:75], v[108:111], v[190:193], v[72:75]
	v_mfma_f32_16x16x32_bf16 v[76:79], v[116:119], v[190:193], v[76:79]
	v_mfma_f32_16x16x32_bf16 v[80:83], v[108:111], v[198:201], v[80:83]
	v_mfma_f32_16x16x32_bf16 v[84:87], v[116:119], v[198:201], v[84:87]
	v_mfma_f32_16x16x32_bf16 v[88:91], v[108:111], v[218:221], v[88:91]
	v_mfma_f32_16x16x32_bf16 v[92:95], v[116:119], v[218:221], v[92:95]
	v_mfma_f32_16x16x32_bf16 v[32:35], v[170:173], v[178:181], v[32:35]
	v_mfma_f32_16x16x32_bf16 v[36:39], v[120:123], v[186:189], v[36:39]
	v_mfma_f32_16x16x32_bf16 v[40:43], v[170:173], v[186:189], v[40:43]
	v_mfma_f32_16x16x32_bf16 v[44:47], v[120:123], v[194:197], v[44:47]
	v_mfma_f32_16x16x32_bf16 v[48:51], v[170:173], v[194:197], v[48:51]
	v_mfma_f32_16x16x32_bf16 v[52:55], v[120:123], v[202:205], v[52:55]
	v_mfma_f32_16x16x32_bf16 v[56:59], v[170:173], v[202:205], v[56:59]
	v_mfma_f32_16x16x32_bf16 v[96:99], v[120:123], v[178:181], v[96:99]
	v_mfma_f32_16x16x32_bf16 v[32:35], v[174:177], v[182:185], v[32:35]
	v_mfma_f32_16x16x32_bf16 v[36:39], v[124:127], v[190:193], v[36:39]
	v_mfma_f32_16x16x32_bf16 v[40:43], v[174:177], v[190:193], v[40:43]
	v_mfma_f32_16x16x32_bf16 v[44:47], v[124:127], v[198:201], v[44:47]
	v_mfma_f32_16x16x32_bf16 v[48:51], v[174:177], v[198:201], v[48:51]
	v_mfma_f32_16x16x32_bf16 v[52:55], v[124:127], v[218:221], v[52:55]
	v_mfma_f32_16x16x32_bf16 v[56:59], v[174:177], v[218:221], v[56:59]
	v_mfma_f32_16x16x32_bf16 v[222:225], v[124:127], v[182:185], v[96:99]
	s_barrier
	s_mov_b32 m0, s52
	v_lshl_add_u64 v[154:155], s[30:31], 0, v[148:149]
	s_add_u32 s24, s30, 0x10000
	ds_read_b128 v[96:99], v139 offset:16384
	ds_read_b128 v[178:181], v139 offset:17408
	ds_read_b128 v[182:185], v139 offset:18432
	ds_read_b128 v[186:189], v139 offset:19456
	ds_read_b128 v[190:193], v139 offset:20480
	ds_read_b128 v[194:197], v139 offset:21504
	ds_read_b128 v[198:201], v139 offset:22528
	ds_read_b128 v[202:205], v139 offset:23552
	global_load_lds_dwordx4 v[154:155], off
	v_lshl_add_u64 v[156:157], s[30:31], 0, v[128:129]
	s_mov_b32 m0, s19
	s_addc_u32 s25, s31, 0
	global_load_lds_dwordx4 v[156:157], off
	v_lshl_add_u64 v[212:213], s[24:25], 0, v[148:149]
	s_mov_b32 m0, s50
	v_lshl_add_u64 v[214:215], s[34:35], 0, v[130:131]
	global_load_lds_dwordx4 v[212:213], off
	v_lshl_add_u64 v[212:213], s[24:25], 0, v[128:129]
	s_mov_b32 m0, s51
	s_nop 0
	global_load_lds_dwordx4 v[212:213], off
	v_lshl_add_u64 v[212:213], s[34:35], 0, v[132:133]
	s_mov_b32 m0, s40
	s_nop 0
	global_load_lds_dwordx4 v[212:213], off
	s_mov_b32 m0, s41
	s_nop 0
	global_load_lds_dwordx4 v[214:215], off
	s_waitcnt vmcnt(8)
	s_waitcnt lgkmcnt(0)
	s_barrier
	s_waitcnt lgkmcnt(0)
	v_mfma_f32_16x16x32_bf16 v[0:3], v[104:107], v[198:201], v[0:3]
	v_mfma_f32_16x16x32_bf16 v[4:7], v[112:115], v[198:201], v[4:7]
	v_mfma_f32_16x16x32_bf16 v[134:137], v[104:107], v[96:99], v[134:137]
	v_mfma_f32_16x16x32_bf16 v[140:143], v[112:115], v[96:99], v[140:143]
	v_mfma_f32_16x16x32_bf16 v[144:147], v[104:107], v[182:185], v[144:147]
	v_mfma_f32_16x16x32_bf16 v[158:161], v[112:115], v[182:185], v[158:161]
	v_mfma_f32_16x16x32_bf16 v[162:165], v[104:107], v[190:193], v[162:165]
	v_mfma_f32_16x16x32_bf16 v[166:169], v[112:115], v[190:193], v[166:169]
	v_mfma_f32_16x16x32_bf16 v[0:3], v[108:111], v[202:205], v[0:3]
	v_mfma_f32_16x16x32_bf16 v[4:7], v[116:119], v[202:205], v[4:7]
	v_mfma_f32_16x16x32_bf16 v[134:137], v[108:111], v[178:181], v[134:137]
	v_mfma_f32_16x16x32_bf16 v[140:143], v[116:119], v[178:181], v[140:143]
	v_mfma_f32_16x16x32_bf16 v[144:147], v[108:111], v[186:189], v[144:147]
	v_mfma_f32_16x16x32_bf16 v[158:161], v[116:119], v[186:189], v[158:161]
	v_mfma_f32_16x16x32_bf16 v[162:165], v[108:111], v[194:197], v[162:165]
	v_mfma_f32_16x16x32_bf16 v[166:169], v[116:119], v[194:197], v[166:169]
	v_mfma_f32_16x16x32_bf16 v[8:11], v[120:123], v[96:99], v[8:11]
	v_mfma_f32_16x16x32_bf16 v[12:15], v[170:173], v[96:99], v[12:15]
	v_mfma_f32_16x16x32_bf16 v[24:27], v[120:123], v[182:185], v[24:27]
	v_mfma_f32_16x16x32_bf16 v[28:31], v[170:173], v[182:185], v[28:31]
	v_mfma_f32_16x16x32_bf16 v[60:63], v[120:123], v[190:193], v[60:63]
	v_mfma_f32_16x16x32_bf16 v[16:19], v[120:123], v[198:201], v[16:19]
	v_mfma_f32_16x16x32_bf16 v[8:11], v[124:127], v[178:181], v[8:11]
	v_mfma_f32_16x16x32_bf16 v[12:15], v[174:177], v[178:181], v[12:15]
	v_mfma_f32_16x16x32_bf16 v[24:27], v[124:127], v[186:189], v[24:27]
	v_mfma_f32_16x16x32_bf16 v[28:31], v[174:177], v[186:189], v[28:31]
	v_mfma_f32_16x16x32_bf16 v[178:181], v[124:127], v[194:197], v[60:63]
	v_mfma_f32_16x16x32_bf16 v[60:63], v[170:173], v[190:193], v[100:103]
	v_mfma_f32_16x16x32_bf16 v[186:189], v[124:127], v[202:205], v[16:19]
	v_mfma_f32_16x16x32_bf16 v[16:19], v[170:173], v[198:201], v[20:23]
	v_mfma_f32_16x16x32_bf16 v[182:185], v[174:177], v[194:197], v[60:63]
	v_mfma_f32_16x16x32_bf16 v[170:173], v[174:177], v[202:205], v[16:19]
	s_barrier
	s_nop 1
	ds_read_b128 v[60:63], v152
	ds_read_b128 v[174:177], v152 offset:1024
	ds_read_b128 v[190:193], v152 offset:2048
	ds_read_b128 v[194:197], v152 offset:3072
	ds_read_b128 v[198:201], v153
	ds_read_b128 v[202:205], v153 offset:1024
	ds_read_b128 v[218:221], v153 offset:2048
	ds_read_b128 v[226:229], v153 offset:3072
	s_add_u32 s24, s34, 0x10000
	s_addc_u32 s25, s35, 0
	s_mov_b32 m0, s42
	v_lshl_add_u64 v[96:97], s[24:25], 0, v[132:133]
	ds_read_b128 v[16:19], v139 offset:32768
	ds_read_b128 v[20:23], v139 offset:33792
	ds_read_b128 v[108:111], v139 offset:34816
	ds_read_b128 v[230:233], v139 offset:35840
	ds_read_b128 v[234:237], v139 offset:36864
	ds_read_b128 v[238:241], v139 offset:37888
	ds_read_b128 v[242:245], v139 offset:38912
	ds_read_b128 v[246:249], v139 offset:39936
	global_load_lds_dwordx4 v[96:97], off
	v_lshl_add_u64 v[96:97], s[24:25], 0, v[130:131]
	s_mov_b32 m0, s43
	s_nop 0
	global_load_lds_dwordx4 v[96:97], off
	s_waitcnt vmcnt(8)
	s_waitcnt lgkmcnt(0)
	s_barrier
	s_waitcnt lgkmcnt(0)
	v_mfma_f32_16x16x32_bf16 v[64:67], v[60:63], v[16:19], v[64:67]
	v_mfma_f32_16x16x32_bf16 v[112:115], v[174:177], v[20:23], v[64:67]
	v_mfma_f32_16x16x32_bf16 v[64:67], v[190:193], v[16:19], v[68:71]
	v_mfma_f32_16x16x32_bf16 v[116:119], v[194:197], v[20:23], v[64:67]
	v_mfma_f32_16x16x32_bf16 v[64:67], v[60:63], v[108:111], v[72:75]
	v_mfma_f32_16x16x32_bf16 v[96:99], v[174:177], v[230:233], v[64:67]
	v_mfma_f32_16x16x32_bf16 v[64:67], v[190:193], v[108:111], v[76:79]
	v_mfma_f32_16x16x32_bf16 v[100:103], v[194:197], v[230:233], v[64:67]
	v_mfma_f32_16x16x32_bf16 v[64:67], v[60:63], v[234:237], v[80:83]
	v_mfma_f32_16x16x32_bf16 v[80:83], v[174:177], v[238:241], v[64:67]
	v_mfma_f32_16x16x32_bf16 v[64:67], v[190:193], v[234:237], v[84:87]
	v_mfma_f32_16x16x32_bf16 v[84:87], v[194:197], v[238:241], v[64:67]
	v_mfma_f32_16x16x32_bf16 v[64:67], v[60:63], v[242:245], v[88:91]
	v_mfma_f32_16x16x32_bf16 v[68:71], v[190:193], v[242:245], v[92:95]
	v_mfma_f32_16x16x32_bf16 v[64:67], v[174:177], v[246:249], v[64:67]
	v_mfma_f32_16x16x32_bf16 v[68:71], v[194:197], v[246:249], v[68:71]
	v_mfma_f32_16x16x32_bf16 v[72:75], v[198:201], v[16:19], v[222:225]
	v_mfma_f32_16x16x32_bf16 v[16:19], v[218:221], v[16:19], v[32:35]
	v_mfma_f32_16x16x32_bf16 v[124:127], v[226:229], v[20:23], v[16:19]
	v_mfma_f32_16x16x32_bf16 v[16:19], v[198:201], v[108:111], v[36:39]
	v_mfma_f32_16x16x32_bf16 v[104:107], v[202:205], v[230:233], v[16:19]
	v_mfma_f32_16x16x32_bf16 v[16:19], v[218:221], v[108:111], v[40:43]
	v_mfma_f32_16x16x32_bf16 v[108:111], v[226:229], v[230:233], v[16:19]
	v_mfma_f32_16x16x32_bf16 v[16:19], v[198:201], v[234:237], v[44:47]
	v_mfma_f32_16x16x32_bf16 v[88:91], v[202:205], v[238:241], v[16:19]
	v_mfma_f32_16x16x32_bf16 v[16:19], v[218:221], v[234:237], v[48:51]
	v_mfma_f32_16x16x32_bf16 v[92:95], v[226:229], v[238:241], v[16:19]
	v_mfma_f32_16x16x32_bf16 v[16:19], v[198:201], v[242:245], v[52:55]
	v_mfma_f32_16x16x32_bf16 v[120:123], v[202:205], v[20:23], v[72:75]
	v_mfma_f32_16x16x32_bf16 v[72:75], v[202:205], v[246:249], v[16:19]
	v_mfma_f32_16x16x32_bf16 v[16:19], v[218:221], v[242:245], v[56:59]
	v_mfma_f32_16x16x32_bf16 v[76:79], v[226:229], v[246:249], v[16:19]
	s_barrier
	s_mov_b32 m0, s55
	s_nop 3
	v_lshl_add_u64 v[16:17], v[154:155], 0, s[28:29]
	s_add_u32 s24, s30, 0x10080
	ds_read_b128 v[40:43], v139 offset:49152
	ds_read_b128 v[44:47], v139 offset:50176
	ds_read_b128 v[222:225], v139 offset:51200
	ds_read_b128 v[230:233], v139 offset:52224
	ds_read_b128 v[234:237], v139 offset:53248
	ds_read_b128 v[238:241], v139 offset:54272
	ds_read_b128 v[242:245], v139 offset:55296
	ds_read_b128 v[246:249], v139 offset:56320
	global_load_lds_dwordx4 v[16:17], off
	v_lshl_add_u64 v[16:17], v[156:157], 0, s[28:29]
	s_mov_b32 m0, s53
	s_addc_u32 s25, s31, 0
	global_load_lds_dwordx4 v[16:17], off
	v_lshl_add_u64 v[16:17], s[24:25], 0, v[148:149]
	s_mov_b32 m0, s26
	s_nop 0
	global_load_lds_dwordx4 v[16:17], off
	v_lshl_add_u64 v[16:17], s[24:25], 0, v[128:129]
	s_mov_b32 m0, s27
	s_nop 0
	global_load_lds_dwordx4 v[16:17], off
	v_lshl_add_u64 v[16:17], v[212:213], 0, s[28:29]
	s_mov_b32 m0, s46
	s_nop 0
	global_load_lds_dwordx4 v[16:17], off
	v_lshl_add_u64 v[16:17], v[214:215], 0, s[28:29]
	s_mov_b32 m0, s47
	s_nop 0
	global_load_lds_dwordx4 v[16:17], off
	s_waitcnt vmcnt(8)
	s_waitcnt lgkmcnt(0)
	s_barrier
	s_waitcnt lgkmcnt(0)
	v_mfma_f32_16x16x32_bf16 v[16:19], v[60:63], v[40:43], v[134:137]
	v_mfma_f32_16x16x32_bf16 v[48:51], v[174:177], v[44:47], v[16:19]
	v_mfma_f32_16x16x32_bf16 v[16:19], v[190:193], v[40:43], v[140:143]
	v_mfma_f32_16x16x32_bf16 v[52:55], v[194:197], v[44:47], v[16:19]
	v_mfma_f32_16x16x32_bf16 v[16:19], v[60:63], v[222:225], v[144:147]
	v_mfma_f32_16x16x32_bf16 v[32:35], v[174:177], v[230:233], v[16:19]
	v_mfma_f32_16x16x32_bf16 v[16:19], v[190:193], v[222:225], v[158:161]
	v_mfma_f32_16x16x32_bf16 v[36:39], v[194:197], v[230:233], v[16:19]
	v_mfma_f32_16x16x32_bf16 v[16:19], v[60:63], v[234:237], v[162:165]
	v_mfma_f32_16x16x32_bf16 v[20:23], v[190:193], v[234:237], v[166:169]
	v_mfma_f32_16x16x32_bf16 v[0:3], v[60:63], v[242:245], v[0:3]
	v_mfma_f32_16x16x32_bf16 v[4:7], v[190:193], v[242:245], v[4:7]
	v_mfma_f32_16x16x32_bf16 v[16:19], v[174:177], v[238:241], v[16:19]
	v_mfma_f32_16x16x32_bf16 v[20:23], v[194:197], v[238:241], v[20:23]
	v_mfma_f32_16x16x32_bf16 v[0:3], v[174:177], v[246:249], v[0:3]
	v_mfma_f32_16x16x32_bf16 v[4:7], v[194:197], v[246:249], v[4:7]
	v_mfma_f32_16x16x32_bf16 v[8:11], v[198:201], v[40:43], v[8:11]
	v_mfma_f32_16x16x32_bf16 v[56:59], v[202:205], v[44:47], v[8:11]
	v_mfma_f32_16x16x32_bf16 v[8:11], v[218:221], v[40:43], v[12:15]
	v_mfma_f32_16x16x32_bf16 v[60:63], v[226:229], v[44:47], v[8:11]
	v_mfma_f32_16x16x32_bf16 v[8:11], v[198:201], v[222:225], v[24:27]
	v_mfma_f32_16x16x32_bf16 v[40:43], v[202:205], v[230:233], v[8:11]
	v_mfma_f32_16x16x32_bf16 v[8:11], v[218:221], v[222:225], v[28:31]
	v_mfma_f32_16x16x32_bf16 v[44:47], v[226:229], v[230:233], v[8:11]
	v_mfma_f32_16x16x32_bf16 v[8:11], v[198:201], v[234:237], v[178:181]
	v_mfma_f32_16x16x32_bf16 v[24:27], v[202:205], v[238:241], v[8:11]
	v_mfma_f32_16x16x32_bf16 v[8:11], v[218:221], v[234:237], v[182:185]
	v_mfma_f32_16x16x32_bf16 v[28:31], v[226:229], v[238:241], v[8:11]
	v_mfma_f32_16x16x32_bf16 v[8:11], v[198:201], v[242:245], v[186:189]
	v_mfma_f32_16x16x32_bf16 v[12:15], v[218:221], v[242:245], v[170:173]
	v_mfma_f32_16x16x32_bf16 v[8:11], v[202:205], v[246:249], v[8:11]
	v_mfma_f32_16x16x32_bf16 v[12:15], v[226:229], v[246:249], v[12:15]
	s_barrier
	s_andn2_b64 vcc, exec, s[12:13]
	s_cbranch_vccnz .LBB0_873
	s_barrier

.LBB0_889:
	s_ashr_i32 s15, s14, 31
	s_lshl_b64 s[16:17], s[14:15], 17
	s_add_u32 s16, s30, s16
	s_addc_u32 s17, s31, s17
	s_and_b64 s[18:19], s[6:7], exec
	s_cselect_b32 s27, s17, s21
	s_cselect_b32 s26, s16, s20
	s_ashr_i32 s13, s12, 31
	s_lshl_b64 s[18:19], s[12:13], 17
	s_add_u32 s18, s33, s18
	s_addc_u32 s19, s36, s19
	s_and_b64 s[24:25], s[6:7], exec
	s_cselect_b32 s25, s19, s23
	s_cselect_b32 s24, s18, s22
	s_add_i32 s48, 0, 0x10000
	s_add_i32 s49, 0, 0x14000
	v_add_u32_e32 v150, s48, v142
	v_add_u32_e32 v151, s49, v142
	ds_read_b128 v[0:3], v150
	ds_read_b128 v[4:7], v150 offset:1024
	ds_read_b128 v[8:11], v150 offset:2048
	ds_read_b128 v[12:15], v150 offset:3072
	ds_read_b128 v[16:19], v151
	ds_read_b128 v[20:23], v151 offset:1024
	ds_read_b128 v[24:27], v151 offset:2048
	ds_read_b128 v[28:31], v151 offset:3072
	s_add_u32 s46, s20, 0x10080
	s_addc_u32 s47, s21, 0
	s_add_i32 s50, s35, 0xc000
	v_lshl_add_u64 v[64:65], s[46:47], 0, v[132:133]
	s_mov_b32 m0, s50
	s_add_i32 s13, s35, 0xe000
	ds_read_b128 v[32:35], v143
	ds_read_b128 v[36:39], v143 offset:1024
	ds_read_b128 v[40:43], v143 offset:2048
	ds_read_b128 v[44:47], v143 offset:3072
	ds_read_b128 v[48:51], v143 offset:4096
	ds_read_b128 v[52:55], v143 offset:5120
	ds_read_b128 v[56:59], v143 offset:6144
	ds_read_b128 v[60:63], v143 offset:7168
	global_load_lds_dwordx4 v[64:65], off
	v_lshl_add_u64 v[64:65], s[46:47], 0, v[130:131]
	s_mov_b32 m0, s13
	s_nop 0
	global_load_lds_dwordx4 v[64:65], off
	s_waitcnt vmcnt(8)
	s_waitcnt lgkmcnt(0)
	s_barrier
	s_waitcnt lgkmcnt(0)
	v_mfma_f32_16x16x32_bf16 v[64:67], v[0:3], v[32:35], 0
	v_mfma_f32_16x16x32_bf16 v[68:71], v[8:11], v[32:35], 0
	v_mfma_f32_16x16x32_bf16 v[72:75], v[0:3], v[40:43], 0
	v_mfma_f32_16x16x32_bf16 v[76:79], v[8:11], v[40:43], 0
	v_mfma_f32_16x16x32_bf16 v[80:83], v[0:3], v[48:51], 0
	v_mfma_f32_16x16x32_bf16 v[84:87], v[8:11], v[48:51], 0
	v_mfma_f32_16x16x32_bf16 v[88:91], v[0:3], v[56:59], 0
	v_mfma_f32_16x16x32_bf16 v[92:95], v[8:11], v[56:59], 0
	v_mfma_f32_16x16x32_bf16 v[64:67], v[4:7], v[36:39], v[64:67]
	v_mfma_f32_16x16x32_bf16 v[68:71], v[12:15], v[36:39], v[68:71]
	v_mfma_f32_16x16x32_bf16 v[72:75], v[4:7], v[44:47], v[72:75]
	v_mfma_f32_16x16x32_bf16 v[76:79], v[12:15], v[44:47], v[76:79]
	v_mfma_f32_16x16x32_bf16 v[80:83], v[4:7], v[52:55], v[80:83]
	v_mfma_f32_16x16x32_bf16 v[84:87], v[12:15], v[52:55], v[84:87]
	v_mfma_f32_16x16x32_bf16 v[88:91], v[4:7], v[60:63], v[88:91]
	v_mfma_f32_16x16x32_bf16 v[92:95], v[12:15], v[60:63], v[92:95]
	v_mfma_f32_16x16x32_bf16 v[96:99], v[16:19], v[32:35], 0
	v_mfma_f32_16x16x32_bf16 v[32:35], v[24:27], v[32:35], 0
	v_mfma_f32_16x16x32_bf16 v[96:99], v[20:23], v[36:39], v[96:99]
	v_mfma_f32_16x16x32_bf16 v[32:35], v[28:31], v[36:39], v[32:35]
	v_mfma_f32_16x16x32_bf16 v[36:39], v[16:19], v[40:43], 0
	v_mfma_f32_16x16x32_bf16 v[40:43], v[24:27], v[40:43], 0
	v_mfma_f32_16x16x32_bf16 v[36:39], v[20:23], v[44:47], v[36:39]
	v_mfma_f32_16x16x32_bf16 v[40:43], v[28:31], v[44:47], v[40:43]
	v_mfma_f32_16x16x32_bf16 v[44:47], v[16:19], v[48:51], 0
	v_mfma_f32_16x16x32_bf16 v[48:51], v[24:27], v[48:51], 0
	v_mfma_f32_16x16x32_bf16 v[44:47], v[20:23], v[52:55], v[44:47]
	v_mfma_f32_16x16x32_bf16 v[48:51], v[28:31], v[52:55], v[48:51]
	v_mfma_f32_16x16x32_bf16 v[52:55], v[16:19], v[56:59], 0
	v_mfma_f32_16x16x32_bf16 v[56:59], v[24:27], v[56:59], 0
	v_mfma_f32_16x16x32_bf16 v[52:55], v[20:23], v[60:63], v[52:55]
	v_mfma_f32_16x16x32_bf16 v[56:59], v[28:31], v[60:63], v[56:59]
	s_barrier
	s_add_i32 s48, s48, s34
	v_lshl_add_u64 v[154:155], s[22:23], 0, v[148:149]
	s_mov_b64 s[54:55], 0x100
	s_add_i32 s15, s48, 0x2000
	v_lshl_add_u64 v[134:135], v[154:155], 0, s[54:55]
	s_mov_b32 m0, s48
	v_lshl_add_u64 v[156:157], s[22:23], 0, v[128:129]
	s_add_u32 s52, s22, 0x10100
	ds_read_b128 v[60:63], v143 offset:16384
	ds_read_b128 v[100:103], v143 offset:17408
	ds_read_b128 v[104:107], v143 offset:18432
	ds_read_b128 v[108:111], v143 offset:19456
	ds_read_b128 v[112:115], v143 offset:20480
	ds_read_b128 v[116:119], v143 offset:21504
	ds_read_b128 v[120:123], v143 offset:22528
	ds_read_b128 v[124:127], v143 offset:23552
	global_load_lds_dwordx4 v[134:135], off
	v_lshl_add_u64 v[134:135], v[156:157], 0, s[54:55]
	s_mov_b32 m0, s15
	s_addc_u32 s53, s23, 0
	s_add_i32 s46, s49, s34
	global_load_lds_dwordx4 v[134:135], off
	v_lshl_add_u64 v[134:135], s[52:53], 0, v[148:149]
	s_mov_b32 m0, s46
	s_add_i32 s47, s46, 0x2000
	global_load_lds_dwordx4 v[134:135], off
	v_lshl_add_u64 v[134:135], s[52:53], 0, v[128:129]
	s_mov_b32 m0, s47
	v_lshl_add_u64 v[212:213], s[20:21], 0, v[132:133]
	global_load_lds_dwordx4 v[134:135], off
	v_lshl_add_u64 v[134:135], v[212:213], 0, s[54:55]
	s_mov_b32 m0, s35
	v_lshl_add_u64 v[214:215], s[20:21], 0, v[130:131]
	global_load_lds_dwordx4 v[134:135], off
	v_lshl_add_u64 v[134:135], v[214:215], 0, s[54:55]
	s_mov_b32 m0, s37
	s_nop 0
	global_load_lds_dwordx4 v[134:135], off
	s_waitcnt vmcnt(8)
	s_waitcnt lgkmcnt(0)
	s_barrier
	s_waitcnt lgkmcnt(0)
	v_mfma_f32_16x16x32_bf16 v[134:137], v[0:3], v[60:63], 0
	v_mfma_f32_16x16x32_bf16 v[144:147], v[0:3], v[104:107], 0
	v_mfma_f32_16x16x32_bf16 v[162:165], v[0:3], v[112:115], 0
	v_mfma_f32_16x16x32_bf16 v[0:3], v[0:3], v[120:123], 0
	v_mfma_f32_16x16x32_bf16 v[134:137], v[4:7], v[100:103], v[134:137]
	v_mfma_f32_16x16x32_bf16 v[144:147], v[4:7], v[108:111], v[144:147]
	v_mfma_f32_16x16x32_bf16 v[162:165], v[4:7], v[116:119], v[162:165]
	v_mfma_f32_16x16x32_bf16 v[0:3], v[4:7], v[124:127], v[0:3]
	v_mfma_f32_16x16x32_bf16 v[4:7], v[8:11], v[120:123], 0
	v_mfma_f32_16x16x32_bf16 v[138:141], v[8:11], v[60:63], 0
	v_mfma_f32_16x16x32_bf16 v[158:161], v[8:11], v[104:107], 0
	v_mfma_f32_16x16x32_bf16 v[166:169], v[8:11], v[112:115], 0
	v_mfma_f32_16x16x32_bf16 v[4:7], v[12:15], v[124:127], v[4:7]
	v_mfma_f32_16x16x32_bf16 v[138:141], v[12:15], v[100:103], v[138:141]
	v_mfma_f32_16x16x32_bf16 v[158:161], v[12:15], v[108:111], v[158:161]
	v_mfma_f32_16x16x32_bf16 v[166:169], v[12:15], v[116:119], v[166:169]
	v_mfma_f32_16x16x32_bf16 v[8:11], v[16:19], v[60:63], 0
	v_mfma_f32_16x16x32_bf16 v[12:15], v[24:27], v[60:63], 0
	v_mfma_f32_16x16x32_bf16 v[8:11], v[20:23], v[100:103], v[8:11]
	v_mfma_f32_16x16x32_bf16 v[12:15], v[28:31], v[100:103], v[12:15]
	v_mfma_f32_16x16x32_bf16 v[60:63], v[16:19], v[104:107], 0
	v_mfma_f32_16x16x32_bf16 v[100:103], v[24:27], v[104:107], 0
	v_mfma_f32_16x16x32_bf16 v[104:107], v[16:19], v[112:115], 0
	v_mfma_f32_16x16x32_bf16 v[16:19], v[16:19], v[120:123], 0
	v_mfma_f32_16x16x32_bf16 v[60:63], v[20:23], v[108:111], v[60:63]
	v_mfma_f32_16x16x32_bf16 v[100:103], v[28:31], v[108:111], v[100:103]
	v_mfma_f32_16x16x32_bf16 v[104:107], v[20:23], v[116:119], v[104:107]
	v_mfma_f32_16x16x32_bf16 v[108:111], v[24:27], v[112:115], 0
	v_mfma_f32_16x16x32_bf16 v[16:19], v[20:23], v[124:127], v[16:19]
	v_mfma_f32_16x16x32_bf16 v[20:23], v[24:27], v[120:123], 0
	v_mfma_f32_16x16x32_bf16 v[108:111], v[28:31], v[116:119], v[108:111]
	v_mfma_f32_16x16x32_bf16 v[20:23], v[28:31], v[124:127], v[20:23]
	s_barrier
	s_add_i32 s51, 0, 0x18000
	s_add_i32 s54, 0, 0x1c000
	v_add_u32_e32 v217, s51, v142
	v_add_u32_e32 v246, s54, v142
	ds_read_b128 v[24:27], v217
	ds_read_b128 v[28:31], v217 offset:1024
	ds_read_b128 v[112:115], v217 offset:2048
	ds_read_b128 v[116:119], v217 offset:3072
	ds_read_b128 v[120:123], v246
	ds_read_b128 v[124:127], v246 offset:1024
	ds_read_b128 v[170:173], v246 offset:2048
	ds_read_b128 v[174:177], v246 offset:3072
	s_add_u32 s52, s20, 0x10100
	s_addc_u32 s53, s21, 0
	s_mov_b32 m0, s38
	v_lshl_add_u64 v[222:223], s[52:53], 0, v[132:133]
	ds_read_b128 v[178:181], v143 offset:32768
	ds_read_b128 v[182:185], v143 offset:33792
	ds_read_b128 v[186:189], v143 offset:34816
	ds_read_b128 v[190:193], v143 offset:35840
	ds_read_b128 v[194:197], v143 offset:36864
	ds_read_b128 v[198:201], v143 offset:37888
	ds_read_b128 v[202:205], v143 offset:38912
	ds_read_b128 v[218:221], v143 offset:39936
	global_load_lds_dwordx4 v[222:223], off
	v_lshl_add_u64 v[222:223], s[52:53], 0, v[130:131]
	s_mov_b32 m0, s39
	s_nop 0
	global_load_lds_dwordx4 v[222:223], off
	s_waitcnt vmcnt(8)
	s_waitcnt lgkmcnt(0)
	s_barrier
	s_waitcnt lgkmcnt(0)
	v_mfma_f32_16x16x32_bf16 v[64:67], v[24:27], v[178:181], v[64:67]
	v_mfma_f32_16x16x32_bf16 v[68:71], v[112:115], v[178:181], v[68:71]
	v_mfma_f32_16x16x32_bf16 v[72:75], v[24:27], v[186:189], v[72:75]
	v_mfma_f32_16x16x32_bf16 v[76:79], v[112:115], v[186:189], v[76:79]
	v_mfma_f32_16x16x32_bf16 v[80:83], v[24:27], v[194:197], v[80:83]
	v_mfma_f32_16x16x32_bf16 v[84:87], v[112:115], v[194:197], v[84:87]
	v_mfma_f32_16x16x32_bf16 v[88:91], v[24:27], v[202:205], v[88:91]
	v_mfma_f32_16x16x32_bf16 v[92:95], v[112:115], v[202:205], v[92:95]
	v_mfma_f32_16x16x32_bf16 v[64:67], v[28:31], v[182:185], v[64:67]
	v_mfma_f32_16x16x32_bf16 v[68:71], v[116:119], v[182:185], v[68:71]
	v_mfma_f32_16x16x32_bf16 v[72:75], v[28:31], v[190:193], v[72:75]
	v_mfma_f32_16x16x32_bf16 v[76:79], v[116:119], v[190:193], v[76:79]
	v_mfma_f32_16x16x32_bf16 v[80:83], v[28:31], v[198:201], v[80:83]
	v_mfma_f32_16x16x32_bf16 v[84:87], v[116:119], v[198:201], v[84:87]
	v_mfma_f32_16x16x32_bf16 v[88:91], v[28:31], v[218:221], v[88:91]
	v_mfma_f32_16x16x32_bf16 v[92:95], v[116:119], v[218:221], v[92:95]
	v_mfma_f32_16x16x32_bf16 v[96:99], v[120:123], v[178:181], v[96:99]
	v_mfma_f32_16x16x32_bf16 v[32:35], v[170:173], v[178:181], v[32:35]
	v_mfma_f32_16x16x32_bf16 v[36:39], v[120:123], v[186:189], v[36:39]
	v_mfma_f32_16x16x32_bf16 v[40:43], v[170:173], v[186:189], v[40:43]
	v_mfma_f32_16x16x32_bf16 v[44:47], v[120:123], v[194:197], v[44:47]
	v_mfma_f32_16x16x32_bf16 v[48:51], v[170:173], v[194:197], v[48:51]
	v_mfma_f32_16x16x32_bf16 v[52:55], v[120:123], v[202:205], v[52:55]
	v_mfma_f32_16x16x32_bf16 v[56:59], v[170:173], v[202:205], v[56:59]
	v_mfma_f32_16x16x32_bf16 v[96:99], v[124:127], v[182:185], v[96:99]
	v_mfma_f32_16x16x32_bf16 v[32:35], v[174:177], v[182:185], v[32:35]
	v_mfma_f32_16x16x32_bf16 v[36:39], v[124:127], v[190:193], v[36:39]
	v_mfma_f32_16x16x32_bf16 v[40:43], v[174:177], v[190:193], v[40:43]
	v_mfma_f32_16x16x32_bf16 v[44:47], v[124:127], v[198:201], v[44:47]
	v_mfma_f32_16x16x32_bf16 v[48:51], v[174:177], v[198:201], v[48:51]
	v_mfma_f32_16x16x32_bf16 v[52:55], v[124:127], v[218:221], v[52:55]
	v_mfma_f32_16x16x32_bf16 v[56:59], v[174:177], v[218:221], v[56:59]
	s_barrier
	s_add_i32 s51, s51, s34
	s_mov_b64 s[56:57], 0x180
	s_add_i32 s49, s51, 0x2000
	v_lshl_add_u64 v[154:155], v[154:155], 0, s[56:57]
	s_mov_b32 m0, s51
	s_add_u32 s52, s22, 0x10180
	ds_read_b128 v[178:181], v143 offset:49152
	ds_read_b128 v[182:185], v143 offset:50176
	ds_read_b128 v[186:189], v143 offset:51200
	ds_read_b128 v[190:193], v143 offset:52224
	ds_read_b128 v[194:197], v143 offset:53248
	ds_read_b128 v[198:201], v143 offset:54272
	ds_read_b128 v[202:205], v143 offset:55296
	ds_read_b128 v[218:221], v143 offset:56320
	global_load_lds_dwordx4 v[154:155], off
	v_lshl_add_u64 v[154:155], v[156:157], 0, s[56:57]
	s_mov_b32 m0, s49
	s_addc_u32 s53, s23, 0
	s_add_i32 s22, s54, s34
	global_load_lds_dwordx4 v[154:155], off
	v_lshl_add_u64 v[154:155], s[52:53], 0, v[148:149]
	s_mov_b32 m0, s22
	s_add_i32 s23, s22, 0x2000
	global_load_lds_dwordx4 v[154:155], off
	v_lshl_add_u64 v[154:155], s[52:53], 0, v[128:129]
	s_mov_b32 m0, s23
	s_nop 0
	global_load_lds_dwordx4 v[154:155], off
	v_lshl_add_u64 v[154:155], v[212:213], 0, s[56:57]
	s_mov_b32 m0, s42
	s_nop 0
	global_load_lds_dwordx4 v[154:155], off
	v_lshl_add_u64 v[154:155], v[214:215], 0, s[56:57]
	s_mov_b32 m0, s43
	s_nop 0
	global_load_lds_dwordx4 v[154:155], off
	s_waitcnt vmcnt(8)
	s_waitcnt lgkmcnt(0)
	s_barrier
	s_waitcnt lgkmcnt(0)
	v_mfma_f32_16x16x32_bf16 v[0:3], v[24:27], v[202:205], v[0:3]
	v_mfma_f32_16x16x32_bf16 v[4:7], v[112:115], v[202:205], v[4:7]
	v_mfma_f32_16x16x32_bf16 v[134:137], v[24:27], v[178:181], v[134:137]
	v_mfma_f32_16x16x32_bf16 v[138:141], v[112:115], v[178:181], v[138:141]
	v_mfma_f32_16x16x32_bf16 v[144:147], v[24:27], v[186:189], v[144:147]
	v_mfma_f32_16x16x32_bf16 v[158:161], v[112:115], v[186:189], v[158:161]
	v_mfma_f32_16x16x32_bf16 v[162:165], v[24:27], v[194:197], v[162:165]
	v_mfma_f32_16x16x32_bf16 v[166:169], v[112:115], v[194:197], v[166:169]
	v_mfma_f32_16x16x32_bf16 v[0:3], v[28:31], v[218:221], v[0:3]
	v_mfma_f32_16x16x32_bf16 v[4:7], v[116:119], v[218:221], v[4:7]
	v_mfma_f32_16x16x32_bf16 v[134:137], v[28:31], v[182:185], v[134:137]
	v_mfma_f32_16x16x32_bf16 v[138:141], v[116:119], v[182:185], v[138:141]
	v_mfma_f32_16x16x32_bf16 v[144:147], v[28:31], v[190:193], v[144:147]
	v_mfma_f32_16x16x32_bf16 v[158:161], v[116:119], v[190:193], v[158:161]
	v_mfma_f32_16x16x32_bf16 v[162:165], v[28:31], v[198:201], v[162:165]
	v_mfma_f32_16x16x32_bf16 v[166:169], v[116:119], v[198:201], v[166:169]
	v_mfma_f32_16x16x32_bf16 v[8:11], v[120:123], v[178:181], v[8:11]
	v_mfma_f32_16x16x32_bf16 v[12:15], v[170:173], v[178:181], v[12:15]
	v_mfma_f32_16x16x32_bf16 v[24:27], v[120:123], v[186:189], v[60:63]
	v_mfma_f32_16x16x32_bf16 v[28:31], v[170:173], v[186:189], v[100:103]
	v_mfma_f32_16x16x32_bf16 v[60:63], v[120:123], v[194:197], v[104:107]
	v_mfma_f32_16x16x32_bf16 v[100:103], v[170:173], v[194:197], v[108:111]
	v_mfma_f32_16x16x32_bf16 v[16:19], v[120:123], v[202:205], v[16:19]
	v_mfma_f32_16x16x32_bf16 v[20:23], v[170:173], v[202:205], v[20:23]
	v_mfma_f32_16x16x32_bf16 v[8:11], v[124:127], v[182:185], v[8:11]
	v_mfma_f32_16x16x32_bf16 v[12:15], v[174:177], v[182:185], v[12:15]
	v_mfma_f32_16x16x32_bf16 v[24:27], v[124:127], v[190:193], v[24:27]
	v_mfma_f32_16x16x32_bf16 v[28:31], v[174:177], v[190:193], v[28:31]
	v_mfma_f32_16x16x32_bf16 v[60:63], v[124:127], v[198:201], v[60:63]
	v_mfma_f32_16x16x32_bf16 v[100:103], v[174:177], v[198:201], v[100:103]
	v_mfma_f32_16x16x32_bf16 v[16:19], v[124:127], v[218:221], v[16:19]
	v_mfma_f32_16x16x32_bf16 v[20:23], v[174:177], v[218:221], v[20:23]
	s_barrier
	ds_read_b128 v[104:107], v150
	ds_read_b128 v[108:111], v150 offset:1024
	ds_read_b128 v[112:115], v150 offset:2048
	ds_read_b128 v[116:119], v150 offset:3072
	ds_read_b128 v[120:123], v151
	ds_read_b128 v[124:127], v151 offset:1024
	ds_read_b128 v[170:173], v151 offset:2048
	ds_read_b128 v[174:177], v151 offset:3072
	s_add_u32 s20, s20, 0x10180
	s_addc_u32 s21, s21, 0
	s_mov_b32 m0, s50
	v_lshl_add_u64 v[154:155], s[20:21], 0, v[132:133]
	ds_read_b128 v[178:181], v143
	ds_read_b128 v[182:185], v143 offset:1024
	ds_read_b128 v[186:189], v143 offset:2048
	ds_read_b128 v[190:193], v143 offset:3072
	ds_read_b128 v[194:197], v143 offset:4096
	ds_read_b128 v[198:201], v143 offset:5120
	ds_read_b128 v[202:205], v143 offset:6144
	ds_read_b128 v[218:221], v143 offset:7168
	global_load_lds_dwordx4 v[154:155], off
	v_lshl_add_u64 v[154:155], s[20:21], 0, v[130:131]
	s_mov_b32 m0, s13
	s_nop 0
	global_load_lds_dwordx4 v[154:155], off
	s_waitcnt vmcnt(8)
	s_waitcnt lgkmcnt(0)
	s_barrier
	s_waitcnt lgkmcnt(0)
	v_mfma_f32_16x16x32_bf16 v[84:87], v[112:115], v[194:197], v[84:87]
	v_mfma_f32_16x16x32_bf16 v[64:67], v[104:107], v[178:181], v[64:67]
	v_mfma_f32_16x16x32_bf16 v[68:71], v[112:115], v[178:181], v[68:71]
	v_mfma_f32_16x16x32_bf16 v[72:75], v[104:107], v[186:189], v[72:75]
	v_mfma_f32_16x16x32_bf16 v[76:79], v[112:115], v[186:189], v[76:79]
	v_mfma_f32_16x16x32_bf16 v[80:83], v[104:107], v[194:197], v[80:83]
	v_mfma_f32_16x16x32_bf16 v[222:225], v[116:119], v[198:201], v[84:87]
	v_mfma_f32_16x16x32_bf16 v[84:87], v[104:107], v[202:205], v[88:91]
	v_mfma_f32_16x16x32_bf16 v[64:67], v[108:111], v[182:185], v[64:67]
	v_mfma_f32_16x16x32_bf16 v[68:71], v[116:119], v[182:185], v[68:71]
	v_mfma_f32_16x16x32_bf16 v[72:75], v[108:111], v[190:193], v[72:75]
	v_mfma_f32_16x16x32_bf16 v[76:79], v[116:119], v[190:193], v[76:79]
	v_mfma_f32_16x16x32_bf16 v[80:83], v[108:111], v[198:201], v[80:83]
	v_mfma_f32_16x16x32_bf16 v[88:91], v[108:111], v[218:221], v[84:87]
	v_mfma_f32_16x16x32_bf16 v[84:87], v[112:115], v[202:205], v[92:95]
	v_mfma_f32_16x16x32_bf16 v[226:229], v[116:119], v[218:221], v[84:87]
	v_mfma_f32_16x16x32_bf16 v[40:43], v[170:173], v[186:189], v[40:43]
	v_mfma_f32_16x16x32_bf16 v[84:87], v[120:123], v[178:181], v[96:99]
	v_mfma_f32_16x16x32_bf16 v[32:35], v[170:173], v[178:181], v[32:35]
	v_mfma_f32_16x16x32_bf16 v[178:181], v[174:177], v[190:193], v[40:43]
	v_mfma_f32_16x16x32_bf16 v[40:43], v[120:123], v[194:197], v[44:47]
	v_mfma_f32_16x16x32_bf16 v[96:99], v[124:127], v[182:185], v[84:87]
	v_mfma_f32_16x16x32_bf16 v[32:35], v[174:177], v[182:185], v[32:35]
	v_mfma_f32_16x16x32_bf16 v[182:185], v[124:127], v[198:201], v[40:43]
	v_mfma_f32_16x16x32_bf16 v[40:43], v[170:173], v[194:197], v[48:51]
	v_mfma_f32_16x16x32_bf16 v[48:51], v[174:177], v[198:201], v[40:43]
	v_mfma_f32_16x16x32_bf16 v[40:43], v[120:123], v[202:205], v[52:55]
	v_mfma_f32_16x16x32_bf16 v[36:39], v[120:123], v[186:189], v[36:39]
	v_mfma_f32_16x16x32_bf16 v[52:55], v[124:127], v[218:221], v[40:43]
	v_mfma_f32_16x16x32_bf16 v[40:43], v[170:173], v[202:205], v[56:59]
	v_mfma_f32_16x16x32_bf16 v[36:39], v[124:127], v[190:193], v[36:39]
	v_mfma_f32_16x16x32_bf16 v[56:59], v[174:177], v[218:221], v[40:43]
	s_barrier
	s_mov_b32 m0, s48
	v_lshl_add_u64 v[250:251], s[24:25], 0, v[148:149]
	s_add_u32 s20, s24, 0x10000
	s_nop 0
	ds_read_b128 v[40:43], v143 offset:16384
	ds_read_b128 v[44:47], v143 offset:17408
	ds_read_b128 v[84:87], v143 offset:18432
	ds_read_b128 v[92:95], v143 offset:19456
	ds_read_b128 v[186:189], v143 offset:20480
	ds_read_b128 v[190:193], v143 offset:21504
	ds_read_b128 v[194:197], v143 offset:22528
	ds_read_b128 v[198:201], v143 offset:23552
	global_load_lds_dwordx4 v[250:251], off
	v_lshl_add_u64 v[208:209], s[24:25], 0, v[128:129]
	s_mov_b32 m0, s15
	s_addc_u32 s21, s25, 0
	global_load_lds_dwordx4 v[208:209], off
	v_lshl_add_u64 v[154:155], s[20:21], 0, v[148:149]
	s_mov_b32 m0, s46
	v_lshl_add_u64 v[150:151], s[26:27], 0, v[132:133]
	global_load_lds_dwordx4 v[154:155], off
	v_lshl_add_u64 v[154:155], s[20:21], 0, v[128:129]
	s_mov_b32 m0, s47
	v_lshl_add_u64 v[152:153], s[26:27], 0, v[130:131]
	global_load_lds_dwordx4 v[154:155], off
	s_mov_b32 m0, s35
	s_nop 0
	global_load_lds_dwordx4 v[150:151], off
	s_mov_b32 m0, s37
	s_nop 0
	global_load_lds_dwordx4 v[152:153], off
	s_waitcnt vmcnt(8)
	s_waitcnt lgkmcnt(0)
	s_barrier
	s_waitcnt lgkmcnt(0)
	v_mfma_f32_16x16x32_bf16 v[0:3], v[104:107], v[194:197], v[0:3]
	v_mfma_f32_16x16x32_bf16 v[134:137], v[104:107], v[40:43], v[134:137]
	v_mfma_f32_16x16x32_bf16 v[138:141], v[112:115], v[40:43], v[138:141]
	v_mfma_f32_16x16x32_bf16 v[144:147], v[104:107], v[84:87], v[144:147]
	v_mfma_f32_16x16x32_bf16 v[158:161], v[112:115], v[84:87], v[158:161]
	v_mfma_f32_16x16x32_bf16 v[162:165], v[104:107], v[186:189], v[162:165]
	v_mfma_f32_16x16x32_bf16 v[166:169], v[112:115], v[186:189], v[166:169]
	v_mfma_f32_16x16x32_bf16 v[202:205], v[108:111], v[198:201], v[0:3]
	v_mfma_f32_16x16x32_bf16 v[0:3], v[112:115], v[194:197], v[4:7]
	v_mfma_f32_16x16x32_bf16 v[134:137], v[108:111], v[44:47], v[134:137]
	v_mfma_f32_16x16x32_bf16 v[138:141], v[116:119], v[44:47], v[138:141]
	v_mfma_f32_16x16x32_bf16 v[144:147], v[108:111], v[92:95], v[144:147]
	v_mfma_f32_16x16x32_bf16 v[158:161], v[116:119], v[92:95], v[158:161]
	v_mfma_f32_16x16x32_bf16 v[162:165], v[108:111], v[190:193], v[162:165]
	v_mfma_f32_16x16x32_bf16 v[166:169], v[116:119], v[190:193], v[166:169]
	v_mfma_f32_16x16x32_bf16 v[218:221], v[116:119], v[198:201], v[0:3]
	v_mfma_f32_16x16x32_bf16 v[0:3], v[120:123], v[40:43], v[8:11]
	v_mfma_f32_16x16x32_bf16 v[230:233], v[124:127], v[44:47], v[0:3]
	v_mfma_f32_16x16x32_bf16 v[0:3], v[170:173], v[40:43], v[12:15]
	v_mfma_f32_16x16x32_bf16 v[234:237], v[174:177], v[44:47], v[0:3]
	v_mfma_f32_16x16x32_bf16 v[0:3], v[120:123], v[84:87], v[24:27]
	v_mfma_f32_16x16x32_bf16 v[24:27], v[124:127], v[92:95], v[0:3]
	v_mfma_f32_16x16x32_bf16 v[0:3], v[170:173], v[84:87], v[28:31]
	v_mfma_f32_16x16x32_bf16 v[238:241], v[174:177], v[92:95], v[0:3]
	v_mfma_f32_16x16x32_bf16 v[0:3], v[120:123], v[186:189], v[60:63]
	v_mfma_f32_16x16x32_bf16 v[242:245], v[124:127], v[190:193], v[0:3]
	v_mfma_f32_16x16x32_bf16 v[0:3], v[170:173], v[186:189], v[100:103]
	v_mfma_f32_16x16x32_bf16 v[186:189], v[174:177], v[190:193], v[0:3]
	v_mfma_f32_16x16x32_bf16 v[0:3], v[120:123], v[194:197], v[16:19]
	v_mfma_f32_16x16x32_bf16 v[16:19], v[124:127], v[198:201], v[0:3]
	v_mfma_f32_16x16x32_bf16 v[0:3], v[170:173], v[194:197], v[20:23]
	v_mfma_f32_16x16x32_bf16 v[170:173], v[174:177], v[198:201], v[0:3]
	s_barrier
	ds_read_b128 v[20:23], v217
	ds_read_b128 v[28:31], v217 offset:1024
	ds_read_b128 v[60:63], v217 offset:2048
	ds_read_b128 v[174:177], v217 offset:3072
	ds_read_b128 v[190:193], v246
	ds_read_b128 v[194:197], v246 offset:1024
	ds_read_b128 v[198:201], v246 offset:2048
	ds_read_b128 v[246:249], v246 offset:3072
	s_add_u32 s20, s26, 0x10000
	s_addc_u32 s21, s27, 0
	s_mov_b32 m0, s38
	v_lshl_add_u64 v[12:13], s[20:21], 0, v[132:133]
	ds_read_b128 v[0:3], v143 offset:32768
	ds_read_b128 v[4:7], v143 offset:33792
	ds_read_b128 v[8:11], v143 offset:34816
	ds_read_b128 v[100:103], v143 offset:35840
	ds_read_b128 v[104:107], v143 offset:36864
	ds_read_b128 v[108:111], v143 offset:37888
	ds_read_b128 v[212:215], v143 offset:38912
	ds_read_b128 v[154:157], v143 offset:39936
	global_load_lds_dwordx4 v[12:13], off
	v_lshl_add_u64 v[12:13], s[20:21], 0, v[130:131]
	s_mov_b32 m0, s39
	s_nop 0
	global_load_lds_dwordx4 v[12:13], off
	s_waitcnt vmcnt(8)
	s_waitcnt lgkmcnt(0)
	s_barrier
	s_waitcnt lgkmcnt(0)
	v_mfma_f32_16x16x32_bf16 v[12:15], v[20:23], v[0:3], v[64:67]
	v_mfma_f32_16x16x32_bf16 v[124:127], v[28:31], v[4:7], v[12:15]
	v_mfma_f32_16x16x32_bf16 v[12:15], v[60:63], v[0:3], v[68:71]
	v_mfma_f32_16x16x32_bf16 v[92:95], v[174:177], v[4:7], v[12:15]
	v_mfma_f32_16x16x32_bf16 v[12:15], v[20:23], v[8:11], v[72:75]
	v_mfma_f32_16x16x32_bf16 v[120:123], v[28:31], v[100:103], v[12:15]
	v_mfma_f32_16x16x32_bf16 v[12:15], v[60:63], v[8:11], v[76:79]
	v_mfma_f32_16x16x32_bf16 v[84:87], v[174:177], v[100:103], v[12:15]
	v_mfma_f32_16x16x32_bf16 v[12:15], v[20:23], v[104:107], v[80:83]
	v_mfma_f32_16x16x32_bf16 v[116:119], v[28:31], v[108:111], v[12:15]
	v_mfma_f32_16x16x32_bf16 v[12:15], v[60:63], v[104:107], v[222:225]
	v_mfma_f32_16x16x32_bf16 v[76:79], v[174:177], v[108:111], v[12:15]
	v_mfma_f32_16x16x32_bf16 v[12:15], v[20:23], v[212:215], v[88:91]
	v_mfma_f32_16x16x32_bf16 v[112:115], v[28:31], v[154:157], v[12:15]
	v_mfma_f32_16x16x32_bf16 v[12:15], v[60:63], v[212:215], v[226:229]
	v_mfma_f32_16x16x32_bf16 v[72:75], v[174:177], v[154:157], v[12:15]
	v_mfma_f32_16x16x32_bf16 v[12:15], v[190:193], v[0:3], v[96:99]
	v_mfma_f32_16x16x32_bf16 v[0:3], v[198:201], v[0:3], v[32:35]
	v_mfma_f32_16x16x32_bf16 v[44:47], v[194:197], v[4:7], v[12:15]
	v_mfma_f32_16x16x32_bf16 v[12:15], v[246:249], v[4:7], v[0:3]
	v_mfma_f32_16x16x32_bf16 v[0:3], v[190:193], v[8:11], v[36:39]
	v_mfma_f32_16x16x32_bf16 v[40:43], v[194:197], v[100:103], v[0:3]
	v_mfma_f32_16x16x32_bf16 v[0:3], v[198:201], v[8:11], v[178:181]
	v_mfma_f32_16x16x32_bf16 v[8:11], v[246:249], v[100:103], v[0:3]
	v_mfma_f32_16x16x32_bf16 v[0:3], v[190:193], v[104:107], v[182:185]
	v_mfma_f32_16x16x32_bf16 v[36:39], v[194:197], v[108:111], v[0:3]
	v_mfma_f32_16x16x32_bf16 v[0:3], v[198:201], v[104:107], v[48:51]
	v_mfma_f32_16x16x32_bf16 v[4:7], v[246:249], v[108:111], v[0:3]
	v_mfma_f32_16x16x32_bf16 v[0:3], v[190:193], v[212:215], v[52:55]
	v_mfma_f32_16x16x32_bf16 v[32:35], v[194:197], v[154:157], v[0:3]
	v_mfma_f32_16x16x32_bf16 v[0:3], v[198:201], v[212:215], v[56:59]
	v_mfma_f32_16x16x32_bf16 v[0:3], v[246:249], v[154:157], v[0:3]
	s_barrier
	s_mov_b32 m0, s51
	v_lshl_add_u64 v[56:57], v[250:251], 0, s[28:29]
	s_add_u32 s20, s24, 0x10080
	ds_read_b128 v[48:51], v143 offset:49152
	ds_read_b128 v[52:55], v143 offset:50176
	ds_read_b128 v[154:157], v143 offset:51200
	ds_read_b128 v[178:181], v143 offset:52224
	ds_read_b128 v[182:185], v143 offset:53248
	ds_read_b128 v[212:215], v143 offset:54272
	ds_read_b128 v[222:225], v143 offset:55296
	ds_read_b128 v[226:229], v143 offset:56320
	global_load_lds_dwordx4 v[56:57], off
	v_lshl_add_u64 v[56:57], v[208:209], 0, s[28:29]
	s_mov_b32 m0, s49
	s_addc_u32 s21, s25, 0
	global_load_lds_dwordx4 v[56:57], off
	v_lshl_add_u64 v[56:57], s[20:21], 0, v[148:149]
	s_mov_b32 m0, s22
	s_nop 0
	global_load_lds_dwordx4 v[56:57], off
	v_lshl_add_u64 v[56:57], s[20:21], 0, v[128:129]
	s_mov_b32 m0, s23
	s_nop 0
	global_load_lds_dwordx4 v[56:57], off
	v_lshl_add_u64 v[56:57], v[150:151], 0, s[28:29]
	s_mov_b32 m0, s42
	s_nop 0
	global_load_lds_dwordx4 v[56:57], off
	v_lshl_add_u64 v[56:57], v[152:153], 0, s[28:29]
	s_mov_b32 m0, s43
	s_nop 0
	global_load_lds_dwordx4 v[56:57], off
	s_waitcnt vmcnt(8)
	s_waitcnt lgkmcnt(0)
	s_barrier
	s_waitcnt lgkmcnt(0)
	v_mfma_f32_16x16x32_bf16 v[56:59], v[20:23], v[48:51], v[134:137]
	v_mfma_f32_16x16x32_bf16 v[108:111], v[28:31], v[52:55], v[56:59]
	v_mfma_f32_16x16x32_bf16 v[56:59], v[60:63], v[48:51], v[138:141]
	v_mfma_f32_16x16x32_bf16 v[88:91], v[174:177], v[52:55], v[56:59]
	v_mfma_f32_16x16x32_bf16 v[56:59], v[20:23], v[154:157], v[144:147]
	v_mfma_f32_16x16x32_bf16 v[104:107], v[28:31], v[178:181], v[56:59]
	v_mfma_f32_16x16x32_bf16 v[56:59], v[60:63], v[154:157], v[158:161]
	v_mfma_f32_16x16x32_bf16 v[80:83], v[174:177], v[178:181], v[56:59]
	v_mfma_f32_16x16x32_bf16 v[56:59], v[20:23], v[182:185], v[162:165]
	v_mfma_f32_16x16x32_bf16 v[20:23], v[20:23], v[222:225], v[202:205]
	v_mfma_f32_16x16x32_bf16 v[100:103], v[28:31], v[212:215], v[56:59]
	v_mfma_f32_16x16x32_bf16 v[56:59], v[60:63], v[182:185], v[166:169]
	v_mfma_f32_16x16x32_bf16 v[96:99], v[28:31], v[226:229], v[20:23]
	v_mfma_f32_16x16x32_bf16 v[20:23], v[60:63], v[222:225], v[218:221]
	v_mfma_f32_16x16x32_bf16 v[68:71], v[174:177], v[212:215], v[56:59]
	v_mfma_f32_16x16x32_bf16 v[64:67], v[174:177], v[226:229], v[20:23]
	v_mfma_f32_16x16x32_bf16 v[20:23], v[190:193], v[48:51], v[230:233]
	v_mfma_f32_16x16x32_bf16 v[60:63], v[194:197], v[52:55], v[20:23]
	v_mfma_f32_16x16x32_bf16 v[20:23], v[198:201], v[48:51], v[234:237]
	v_mfma_f32_16x16x32_bf16 v[28:31], v[246:249], v[52:55], v[20:23]
	v_mfma_f32_16x16x32_bf16 v[20:23], v[190:193], v[154:157], v[24:27]
	v_mfma_f32_16x16x32_bf16 v[56:59], v[194:197], v[178:181], v[20:23]
	v_mfma_f32_16x16x32_bf16 v[20:23], v[198:201], v[154:157], v[238:241]
	v_mfma_f32_16x16x32_bf16 v[24:27], v[246:249], v[178:181], v[20:23]
	v_mfma_f32_16x16x32_bf16 v[20:23], v[190:193], v[182:185], v[242:245]
	v_mfma_f32_16x16x32_bf16 v[16:19], v[190:193], v[222:225], v[16:19]
	v_mfma_f32_16x16x32_bf16 v[52:55], v[194:197], v[212:215], v[20:23]
	v_mfma_f32_16x16x32_bf16 v[20:23], v[198:201], v[182:185], v[186:189]
	v_mfma_f32_16x16x32_bf16 v[48:51], v[194:197], v[226:229], v[16:19]
	v_mfma_f32_16x16x32_bf16 v[16:19], v[198:201], v[222:225], v[170:173]
	v_mfma_f32_16x16x32_bf16 v[20:23], v[246:249], v[212:215], v[20:23]
	v_mfma_f32_16x16x32_bf16 v[16:19], v[246:249], v[226:229], v[16:19]
	s_barrier
	s_andn2_b64 vcc, exec, s[8:9]
	s_cbranch_vccnz .LBB0_891
	s_barrier

.LBB0_1335:
	s_add_u32 s22, s8, 0xfffe0080
	s_addc_u32 s23, s9, -1
	s_add_i32 s54, 0, 0x10000
	s_cmp_eq_u32 s53, 4
	s_cselect_b32 s25, s17, s23
	s_cselect_b32 s24, s49, s22
	v_add_u32_e32 v146, s54, v158
	s_cselect_b32 s23, s15, s52
	s_cselect_b32 s22, s50, s51
	s_add_i32 s56, 0, 0x14000
	ds_read_b128 v[138:141], v146
	ds_read_b128 v[142:145], v146 offset:1024
	ds_read_b128 v[154:157], v146 offset:2048
	ds_read_b128 v[160:163], v146 offset:3072
	v_add_u32_e32 v146, s56, v158
	ds_read_b128 v[164:167], v146
	ds_read_b128 v[168:171], v146 offset:1024
	ds_read_b128 v[172:175], v146 offset:2048
	ds_read_b128 v[176:179], v146 offset:3072
	v_lshl_add_u64 v[146:147], s[8:9], 0, v[134:135]
	s_add_i32 m0, s38, 0xc000
	ds_read_b128 v[180:183], v159
	ds_read_b128 v[184:187], v159 offset:1024
	ds_read_b128 v[188:191], v159 offset:2048
	ds_read_b128 v[192:195], v159 offset:3072
	ds_read_b128 v[196:199], v159 offset:4096
	ds_read_b128 v[200:203], v159 offset:5120
	ds_read_b128 v[212:215], v159 offset:6144
	ds_read_b128 v[220:223], v159 offset:7168
	global_load_lds_dwordx4 v[146:147], off
	v_lshl_add_u64 v[146:147], s[8:9], 0, v[136:137]
	s_add_i32 m0, s38, 0xe000
	s_nop 0
	global_load_lds_dwordx4 v[146:147], off
	s_waitcnt vmcnt(8)
	s_waitcnt lgkmcnt(0)
	s_barrier
	s_waitcnt lgkmcnt(0)
	v_mfma_f32_16x16x32_bf16 v[124:127], v[138:141], v[180:183], v[124:127]
	v_mfma_f32_16x16x32_bf16 v[120:123], v[154:157], v[180:183], v[120:123]
	v_mfma_f32_16x16x32_bf16 v[108:111], v[138:141], v[188:191], v[108:111]
	v_mfma_f32_16x16x32_bf16 v[104:107], v[154:157], v[188:191], v[104:107]
	v_mfma_f32_16x16x32_bf16 v[92:95], v[138:141], v[196:199], v[92:95]
	v_mfma_f32_16x16x32_bf16 v[88:91], v[154:157], v[196:199], v[88:91]
	v_mfma_f32_16x16x32_bf16 v[76:79], v[138:141], v[212:215], v[76:79]
	v_mfma_f32_16x16x32_bf16 v[72:75], v[154:157], v[212:215], v[72:75]
	v_mfma_f32_16x16x32_bf16 v[124:127], v[142:145], v[184:187], v[124:127]
	v_mfma_f32_16x16x32_bf16 v[120:123], v[160:163], v[184:187], v[120:123]
	v_mfma_f32_16x16x32_bf16 v[108:111], v[142:145], v[192:195], v[108:111]
	v_mfma_f32_16x16x32_bf16 v[104:107], v[160:163], v[192:195], v[104:107]
	v_mfma_f32_16x16x32_bf16 v[92:95], v[142:145], v[200:203], v[92:95]
	v_mfma_f32_16x16x32_bf16 v[88:91], v[160:163], v[200:203], v[88:91]
	v_mfma_f32_16x16x32_bf16 v[76:79], v[142:145], v[220:223], v[76:79]
	v_mfma_f32_16x16x32_bf16 v[72:75], v[160:163], v[220:223], v[72:75]
	v_mfma_f32_16x16x32_bf16 v[116:119], v[164:167], v[180:183], v[116:119]
	v_mfma_f32_16x16x32_bf16 v[112:115], v[172:175], v[180:183], v[112:115]
	v_mfma_f32_16x16x32_bf16 v[100:103], v[164:167], v[188:191], v[100:103]
	v_mfma_f32_16x16x32_bf16 v[96:99], v[172:175], v[188:191], v[96:99]
	v_mfma_f32_16x16x32_bf16 v[84:87], v[164:167], v[196:199], v[84:87]
	v_mfma_f32_16x16x32_bf16 v[80:83], v[172:175], v[196:199], v[80:83]
	v_mfma_f32_16x16x32_bf16 v[68:71], v[164:167], v[212:215], v[68:71]
	v_mfma_f32_16x16x32_bf16 v[64:67], v[172:175], v[212:215], v[64:67]
	v_mfma_f32_16x16x32_bf16 v[116:119], v[168:171], v[184:187], v[116:119]
	v_mfma_f32_16x16x32_bf16 v[112:115], v[176:179], v[184:187], v[112:115]
	v_mfma_f32_16x16x32_bf16 v[100:103], v[168:171], v[192:195], v[100:103]
	v_mfma_f32_16x16x32_bf16 v[96:99], v[176:179], v[192:195], v[96:99]
	v_mfma_f32_16x16x32_bf16 v[84:87], v[168:171], v[200:203], v[84:87]
	v_mfma_f32_16x16x32_bf16 v[80:83], v[176:179], v[200:203], v[80:83]
	v_mfma_f32_16x16x32_bf16 v[68:71], v[168:171], v[220:223], v[68:71]
	v_mfma_f32_16x16x32_bf16 v[64:67], v[176:179], v[220:223], v[64:67]
	s_barrier
	s_add_i32 s54, s54, s37
	v_lshl_add_u64 v[146:147], s[22:23], 0, v[148:149]
	s_mov_b32 m0, s54
	ds_read_b128 v[180:183], v159 offset:16384
	ds_read_b128 v[184:187], v159 offset:17408
	ds_read_b128 v[188:191], v159 offset:18432
	ds_read_b128 v[192:195], v159 offset:19456
	ds_read_b128 v[196:199], v159 offset:20480
	ds_read_b128 v[200:203], v159 offset:21504
	ds_read_b128 v[212:215], v159 offset:22528
	ds_read_b128 v[220:223], v159 offset:23552
	global_load_lds_dwordx4 v[146:147], off
	s_add_i32 m0, s54, 0x2000
	s_add_u32 s54, s22, 0x20000
	v_lshl_add_u64 v[150:151], s[22:23], 0, v[128:129]
	s_addc_u32 s55, s23, 0
	s_add_i32 s56, s56, s37
	global_load_lds_dwordx4 v[150:151], off
	v_lshl_add_u64 v[152:153], s[54:55], 0, v[148:149]
	s_mov_b32 m0, s56
	v_lshl_add_u64 v[204:205], s[24:25], 0, v[130:131]
	global_load_lds_dwordx4 v[152:153], off
	v_lshl_add_u64 v[152:153], s[54:55], 0, v[128:129]
	s_add_i32 m0, s56, 0x2000
	s_nop 0
	global_load_lds_dwordx4 v[152:153], off
	v_lshl_add_u64 v[152:153], s[24:25], 0, v[132:133]
	s_mov_b32 m0, s38
	s_nop 0
	global_load_lds_dwordx4 v[152:153], off
	s_mov_b32 m0, s39
	s_nop 0
	global_load_lds_dwordx4 v[204:205], off
	s_waitcnt vmcnt(8)
	s_waitcnt lgkmcnt(0)
	s_barrier
	s_waitcnt lgkmcnt(0)
	v_mfma_f32_16x16x32_bf16 v[60:63], v[138:141], v[180:183], v[60:63]
	v_mfma_f32_16x16x32_bf16 v[56:59], v[154:157], v[180:183], v[56:59]
	v_mfma_f32_16x16x32_bf16 v[44:47], v[138:141], v[188:191], v[44:47]
	v_mfma_f32_16x16x32_bf16 v[40:43], v[154:157], v[188:191], v[40:43]
	v_mfma_f32_16x16x32_bf16 v[28:31], v[138:141], v[196:199], v[28:31]
	v_mfma_f32_16x16x32_bf16 v[24:27], v[154:157], v[196:199], v[24:27]
	v_mfma_f32_16x16x32_bf16 v[12:15], v[138:141], v[212:215], v[12:15]
	v_mfma_f32_16x16x32_bf16 v[8:11], v[154:157], v[212:215], v[8:11]
	v_mfma_f32_16x16x32_bf16 v[60:63], v[142:145], v[184:187], v[60:63]
	v_mfma_f32_16x16x32_bf16 v[56:59], v[160:163], v[184:187], v[56:59]
	v_mfma_f32_16x16x32_bf16 v[44:47], v[142:145], v[192:195], v[44:47]
	v_mfma_f32_16x16x32_bf16 v[40:43], v[160:163], v[192:195], v[40:43]
	v_mfma_f32_16x16x32_bf16 v[28:31], v[142:145], v[200:203], v[28:31]
	v_mfma_f32_16x16x32_bf16 v[24:27], v[160:163], v[200:203], v[24:27]
	v_mfma_f32_16x16x32_bf16 v[12:15], v[142:145], v[220:223], v[12:15]
	v_mfma_f32_16x16x32_bf16 v[8:11], v[160:163], v[220:223], v[8:11]
	v_mfma_f32_16x16x32_bf16 v[52:55], v[164:167], v[180:183], v[52:55]
	v_mfma_f32_16x16x32_bf16 v[48:51], v[172:175], v[180:183], v[48:51]
	v_mfma_f32_16x16x32_bf16 v[36:39], v[164:167], v[188:191], v[36:39]
	v_mfma_f32_16x16x32_bf16 v[32:35], v[172:175], v[188:191], v[32:35]
	v_mfma_f32_16x16x32_bf16 v[20:23], v[164:167], v[196:199], v[20:23]
	v_mfma_f32_16x16x32_bf16 v[16:19], v[172:175], v[196:199], v[16:19]
	v_mfma_f32_16x16x32_bf16 v[4:7], v[164:167], v[212:215], v[4:7]
	v_mfma_f32_16x16x32_bf16 v[0:3], v[172:175], v[212:215], v[0:3]
	v_mfma_f32_16x16x32_bf16 v[52:55], v[168:171], v[184:187], v[52:55]
	v_mfma_f32_16x16x32_bf16 v[48:51], v[176:179], v[184:187], v[48:51]
	v_mfma_f32_16x16x32_bf16 v[36:39], v[168:171], v[192:195], v[36:39]
	v_mfma_f32_16x16x32_bf16 v[32:35], v[176:179], v[192:195], v[32:35]
	v_mfma_f32_16x16x32_bf16 v[20:23], v[168:171], v[200:203], v[20:23]
	v_mfma_f32_16x16x32_bf16 v[16:19], v[176:179], v[200:203], v[16:19]
	v_mfma_f32_16x16x32_bf16 v[4:7], v[168:171], v[220:223], v[4:7]
	v_mfma_f32_16x16x32_bf16 v[0:3], v[176:179], v[220:223], v[0:3]
	s_barrier
	s_add_i32 s54, 0, 0x18000
	s_add_i32 s55, 0, 0x1c000
	v_add_u32_e32 v160, s54, v158
	v_add_u32_e32 v176, s55, v158
	ds_read_b128 v[138:141], v160
	ds_read_b128 v[142:145], v160 offset:1024
	ds_read_b128 v[154:157], v160 offset:2048
	ds_read_b128 v[160:163], v160 offset:3072
	ds_read_b128 v[164:167], v176
	ds_read_b128 v[168:171], v176 offset:1024
	ds_read_b128 v[172:175], v176 offset:2048
	ds_read_b128 v[176:179], v176 offset:3072
	s_add_u32 s24, s24, 0x20000
	s_addc_u32 s25, s25, 0
	s_mov_b32 m0, s40
	v_lshl_add_u64 v[208:209], s[24:25], 0, v[132:133]
	ds_read_b128 v[180:183], v159 offset:32768
	ds_read_b128 v[184:187], v159 offset:33792
	ds_read_b128 v[188:191], v159 offset:34816
	ds_read_b128 v[192:195], v159 offset:35840
	ds_read_b128 v[196:199], v159 offset:36864
	ds_read_b128 v[200:203], v159 offset:37888
	ds_read_b128 v[212:215], v159 offset:38912
	ds_read_b128 v[220:223], v159 offset:39936
	global_load_lds_dwordx4 v[208:209], off
	v_lshl_add_u64 v[208:209], s[24:25], 0, v[130:131]
	s_mov_b32 m0, s41
	s_nop 0
	global_load_lds_dwordx4 v[208:209], off
	s_waitcnt vmcnt(8)
	s_waitcnt lgkmcnt(0)
	s_barrier
	s_waitcnt lgkmcnt(0)
	v_mfma_f32_16x16x32_bf16 v[124:127], v[138:141], v[180:183], v[124:127]
	v_mfma_f32_16x16x32_bf16 v[120:123], v[154:157], v[180:183], v[120:123]
	v_mfma_f32_16x16x32_bf16 v[108:111], v[138:141], v[188:191], v[108:111]
	v_mfma_f32_16x16x32_bf16 v[104:107], v[154:157], v[188:191], v[104:107]
	v_mfma_f32_16x16x32_bf16 v[92:95], v[138:141], v[196:199], v[92:95]
	v_mfma_f32_16x16x32_bf16 v[88:91], v[154:157], v[196:199], v[88:91]
	v_mfma_f32_16x16x32_bf16 v[76:79], v[138:141], v[212:215], v[76:79]
	v_mfma_f32_16x16x32_bf16 v[72:75], v[154:157], v[212:215], v[72:75]
	v_mfma_f32_16x16x32_bf16 v[124:127], v[142:145], v[184:187], v[124:127]
	v_mfma_f32_16x16x32_bf16 v[120:123], v[160:163], v[184:187], v[120:123]
	v_mfma_f32_16x16x32_bf16 v[108:111], v[142:145], v[192:195], v[108:111]
	v_mfma_f32_16x16x32_bf16 v[104:107], v[160:163], v[192:195], v[104:107]
	v_mfma_f32_16x16x32_bf16 v[92:95], v[142:145], v[200:203], v[92:95]
	v_mfma_f32_16x16x32_bf16 v[88:91], v[160:163], v[200:203], v[88:91]
	v_mfma_f32_16x16x32_bf16 v[76:79], v[142:145], v[220:223], v[76:79]
	v_mfma_f32_16x16x32_bf16 v[72:75], v[160:163], v[220:223], v[72:75]
	v_mfma_f32_16x16x32_bf16 v[116:119], v[164:167], v[180:183], v[116:119]
	v_mfma_f32_16x16x32_bf16 v[112:115], v[172:175], v[180:183], v[112:115]
	v_mfma_f32_16x16x32_bf16 v[100:103], v[164:167], v[188:191], v[100:103]
	v_mfma_f32_16x16x32_bf16 v[96:99], v[172:175], v[188:191], v[96:99]
	v_mfma_f32_16x16x32_bf16 v[84:87], v[164:167], v[196:199], v[84:87]
	v_mfma_f32_16x16x32_bf16 v[80:83], v[172:175], v[196:199], v[80:83]
	v_mfma_f32_16x16x32_bf16 v[68:71], v[164:167], v[212:215], v[68:71]
	v_mfma_f32_16x16x32_bf16 v[64:67], v[172:175], v[212:215], v[64:67]
	v_mfma_f32_16x16x32_bf16 v[116:119], v[168:171], v[184:187], v[116:119]
	v_mfma_f32_16x16x32_bf16 v[112:115], v[176:179], v[184:187], v[112:115]
	v_mfma_f32_16x16x32_bf16 v[100:103], v[168:171], v[192:195], v[100:103]
	v_mfma_f32_16x16x32_bf16 v[96:99], v[176:179], v[192:195], v[96:99]
	v_mfma_f32_16x16x32_bf16 v[84:87], v[168:171], v[200:203], v[84:87]
	v_mfma_f32_16x16x32_bf16 v[80:83], v[176:179], v[200:203], v[80:83]
	v_mfma_f32_16x16x32_bf16 v[68:71], v[168:171], v[220:223], v[68:71]
	v_mfma_f32_16x16x32_bf16 v[64:67], v[176:179], v[220:223], v[64:67]
	s_barrier
	s_add_i32 s24, s54, s37
	v_lshl_add_u64 v[146:147], v[146:147], 0, s[28:29]
	s_mov_b32 m0, s24
	ds_read_b128 v[180:183], v159 offset:49152
	ds_read_b128 v[184:187], v159 offset:50176
	ds_read_b128 v[188:191], v159 offset:51200
	ds_read_b128 v[192:195], v159 offset:52224
	ds_read_b128 v[196:199], v159 offset:53248
	ds_read_b128 v[200:203], v159 offset:54272
	ds_read_b128 v[212:215], v159 offset:55296
	ds_read_b128 v[220:223], v159 offset:56320
	global_load_lds_dwordx4 v[146:147], off
	s_add_i32 m0, s24, 0x2000
	s_add_u32 s22, s22, 0x20080
	v_lshl_add_u64 v[146:147], v[150:151], 0, s[28:29]
	s_addc_u32 s23, s23, 0
	s_add_i32 s24, s55, s37
	global_load_lds_dwordx4 v[146:147], off
	v_lshl_add_u64 v[146:147], s[22:23], 0, v[148:149]
	s_mov_b32 m0, s24
	s_nop 0
	global_load_lds_dwordx4 v[146:147], off
	v_lshl_add_u64 v[146:147], s[22:23], 0, v[128:129]
	s_add_i32 m0, s24, 0x2000
	s_nop 0
	global_load_lds_dwordx4 v[146:147], off
	v_lshl_add_u64 v[146:147], v[152:153], 0, s[28:29]
	s_mov_b32 m0, s45
	s_nop 0
	global_load_lds_dwordx4 v[146:147], off
	v_lshl_add_u64 v[146:147], v[204:205], 0, s[28:29]
	s_mov_b32 m0, s46
	s_nop 0
	global_load_lds_dwordx4 v[146:147], off
	s_waitcnt vmcnt(8)
	s_waitcnt lgkmcnt(0)
	s_barrier
	s_waitcnt lgkmcnt(0)
	v_mfma_f32_16x16x32_bf16 v[60:63], v[138:141], v[180:183], v[60:63]
	v_mfma_f32_16x16x32_bf16 v[56:59], v[154:157], v[180:183], v[56:59]
	v_mfma_f32_16x16x32_bf16 v[44:47], v[138:141], v[188:191], v[44:47]
	v_mfma_f32_16x16x32_bf16 v[40:43], v[154:157], v[188:191], v[40:43]
	v_mfma_f32_16x16x32_bf16 v[28:31], v[138:141], v[196:199], v[28:31]
	v_mfma_f32_16x16x32_bf16 v[24:27], v[154:157], v[196:199], v[24:27]
	v_mfma_f32_16x16x32_bf16 v[12:15], v[138:141], v[212:215], v[12:15]
	v_mfma_f32_16x16x32_bf16 v[8:11], v[154:157], v[212:215], v[8:11]
	v_mfma_f32_16x16x32_bf16 v[60:63], v[142:145], v[184:187], v[60:63]
	v_mfma_f32_16x16x32_bf16 v[56:59], v[160:163], v[184:187], v[56:59]
	v_mfma_f32_16x16x32_bf16 v[44:47], v[142:145], v[192:195], v[44:47]
	v_mfma_f32_16x16x32_bf16 v[40:43], v[160:163], v[192:195], v[40:43]
	v_mfma_f32_16x16x32_bf16 v[28:31], v[142:145], v[200:203], v[28:31]
	v_mfma_f32_16x16x32_bf16 v[24:27], v[160:163], v[200:203], v[24:27]
	v_mfma_f32_16x16x32_bf16 v[12:15], v[142:145], v[220:223], v[12:15]
	v_mfma_f32_16x16x32_bf16 v[8:11], v[160:163], v[220:223], v[8:11]
	v_mfma_f32_16x16x32_bf16 v[52:55], v[164:167], v[180:183], v[52:55]
	v_mfma_f32_16x16x32_bf16 v[48:51], v[172:175], v[180:183], v[48:51]
	v_mfma_f32_16x16x32_bf16 v[36:39], v[164:167], v[188:191], v[36:39]
	v_mfma_f32_16x16x32_bf16 v[32:35], v[172:175], v[188:191], v[32:35]
	v_mfma_f32_16x16x32_bf16 v[20:23], v[164:167], v[196:199], v[20:23]
	v_mfma_f32_16x16x32_bf16 v[16:19], v[172:175], v[196:199], v[16:19]
	v_mfma_f32_16x16x32_bf16 v[4:7], v[164:167], v[212:215], v[4:7]
	v_mfma_f32_16x16x32_bf16 v[0:3], v[172:175], v[212:215], v[0:3]
	v_mfma_f32_16x16x32_bf16 v[52:55], v[168:171], v[184:187], v[52:55]
	v_mfma_f32_16x16x32_bf16 v[48:51], v[176:179], v[184:187], v[48:51]
	v_mfma_f32_16x16x32_bf16 v[36:39], v[168:171], v[192:195], v[36:39]
	v_mfma_f32_16x16x32_bf16 v[32:35], v[176:179], v[192:195], v[32:35]
	v_mfma_f32_16x16x32_bf16 v[20:23], v[168:171], v[200:203], v[20:23]
	v_mfma_f32_16x16x32_bf16 v[16:19], v[176:179], v[200:203], v[16:19]
	v_mfma_f32_16x16x32_bf16 v[4:7], v[168:171], v[220:223], v[4:7]
	v_mfma_f32_16x16x32_bf16 v[0:3], v[176:179], v[220:223], v[0:3]
	s_barrier
	s_add_i32 s53, s53, 2
	s_add_u32 s8, s8, 0x100
	s_addc_u32 s9, s9, 0
	s_add_u32 s51, s51, 0x100
	s_addc_u32 s52, s52, 0
	s_cmp_gt_u32 s53, 5
	s_cbranch_scc0 .LBB0_1335
	s_and_b64 vcc, exec, s[12:13]
	s_cbranch_vccz .LBB0_1338
	s_barrier

.LBB0_1438:
	s_add_u32 s20, s18, 0xfffc0080
	s_addc_u32 s21, s19, -1
	s_add_i32 s49, 0, 0x10000
	s_cmp_eq_u32 s48, 12
	s_cselect_b32 s23, s13, s21
	s_cselect_b32 s22, s44, s20
	v_add_u32_e32 v142, s49, v144
	s_cselect_b32 s21, s11, s47
	s_cselect_b32 s20, s45, s46
	s_add_i32 s52, 0, 0x14000
	ds_read_b128 v[138:141], v142
	ds_read_b128 v[154:157], v142 offset:1024
	ds_read_b128 v[158:161], v142 offset:2048
	ds_read_b128 v[162:165], v142 offset:3072
	v_add_u32_e32 v142, s52, v144
	ds_read_b128 v[166:169], v142
	ds_read_b128 v[170:173], v142 offset:1024
	ds_read_b128 v[174:177], v142 offset:2048
	ds_read_b128 v[178:181], v142 offset:3072
	v_lshl_add_u64 v[142:143], s[18:19], 0, v[134:135]
	s_add_i32 m0, s31, 0xc000
	ds_read_b128 v[182:185], v145
	ds_read_b128 v[186:189], v145 offset:1024
	ds_read_b128 v[190:193], v145 offset:2048
	ds_read_b128 v[194:197], v145 offset:3072
	ds_read_b128 v[198:201], v145 offset:4096
	ds_read_b128 v[202:205], v145 offset:5120
	ds_read_b128 v[212:215], v145 offset:6144
	ds_read_b128 v[220:223], v145 offset:7168
	global_load_lds_dwordx4 v[142:143], off
	v_lshl_add_u64 v[142:143], s[18:19], 0, v[136:137]
	s_add_i32 m0, s31, 0xe000
	s_nop 0
	global_load_lds_dwordx4 v[142:143], off
	s_waitcnt vmcnt(8)
	s_waitcnt lgkmcnt(0)
	s_barrier
	s_waitcnt lgkmcnt(0)
	v_mfma_f32_16x16x32_bf16 v[124:127], v[138:141], v[182:185], v[124:127]
	v_mfma_f32_16x16x32_bf16 v[120:123], v[158:161], v[182:185], v[120:123]
	v_mfma_f32_16x16x32_bf16 v[108:111], v[138:141], v[190:193], v[108:111]
	v_mfma_f32_16x16x32_bf16 v[104:107], v[158:161], v[190:193], v[104:107]
	v_mfma_f32_16x16x32_bf16 v[92:95], v[138:141], v[198:201], v[92:95]
	v_mfma_f32_16x16x32_bf16 v[88:91], v[158:161], v[198:201], v[88:91]
	v_mfma_f32_16x16x32_bf16 v[76:79], v[138:141], v[212:215], v[76:79]
	v_mfma_f32_16x16x32_bf16 v[72:75], v[158:161], v[212:215], v[72:75]
	v_mfma_f32_16x16x32_bf16 v[124:127], v[154:157], v[186:189], v[124:127]
	v_mfma_f32_16x16x32_bf16 v[120:123], v[162:165], v[186:189], v[120:123]
	v_mfma_f32_16x16x32_bf16 v[108:111], v[154:157], v[194:197], v[108:111]
	v_mfma_f32_16x16x32_bf16 v[104:107], v[162:165], v[194:197], v[104:107]
	v_mfma_f32_16x16x32_bf16 v[92:95], v[154:157], v[202:205], v[92:95]
	v_mfma_f32_16x16x32_bf16 v[88:91], v[162:165], v[202:205], v[88:91]
	v_mfma_f32_16x16x32_bf16 v[76:79], v[154:157], v[220:223], v[76:79]
	v_mfma_f32_16x16x32_bf16 v[72:75], v[162:165], v[220:223], v[72:75]
	v_mfma_f32_16x16x32_bf16 v[116:119], v[166:169], v[182:185], v[116:119]
	v_mfma_f32_16x16x32_bf16 v[112:115], v[174:177], v[182:185], v[112:115]
	v_mfma_f32_16x16x32_bf16 v[100:103], v[166:169], v[190:193], v[100:103]
	v_mfma_f32_16x16x32_bf16 v[96:99], v[174:177], v[190:193], v[96:99]
	v_mfma_f32_16x16x32_bf16 v[84:87], v[166:169], v[198:201], v[84:87]
	v_mfma_f32_16x16x32_bf16 v[80:83], v[174:177], v[198:201], v[80:83]
	v_mfma_f32_16x16x32_bf16 v[68:71], v[166:169], v[212:215], v[68:71]
	v_mfma_f32_16x16x32_bf16 v[64:67], v[174:177], v[212:215], v[64:67]
	v_mfma_f32_16x16x32_bf16 v[116:119], v[170:173], v[186:189], v[116:119]
	v_mfma_f32_16x16x32_bf16 v[112:115], v[178:181], v[186:189], v[112:115]
	v_mfma_f32_16x16x32_bf16 v[100:103], v[170:173], v[194:197], v[100:103]
	v_mfma_f32_16x16x32_bf16 v[96:99], v[178:181], v[194:197], v[96:99]
	v_mfma_f32_16x16x32_bf16 v[84:87], v[170:173], v[202:205], v[84:87]
	v_mfma_f32_16x16x32_bf16 v[80:83], v[178:181], v[202:205], v[80:83]
	v_mfma_f32_16x16x32_bf16 v[68:71], v[170:173], v[220:223], v[68:71]
	v_mfma_f32_16x16x32_bf16 v[64:67], v[178:181], v[220:223], v[64:67]
	s_barrier
	s_add_i32 s49, s49, s30
	v_lshl_add_u64 v[142:143], s[20:21], 0, v[148:149]
	s_mov_b32 m0, s49
	ds_read_b128 v[182:185], v145 offset:16384
	ds_read_b128 v[186:189], v145 offset:17408
	ds_read_b128 v[190:193], v145 offset:18432
	ds_read_b128 v[194:197], v145 offset:19456
	ds_read_b128 v[198:201], v145 offset:20480
	ds_read_b128 v[202:205], v145 offset:21504
	ds_read_b128 v[212:215], v145 offset:22528
	ds_read_b128 v[220:223], v145 offset:23552
	global_load_lds_dwordx4 v[142:143], off
	s_add_i32 m0, s49, 0x2000
	s_add_u32 s50, s20, 0x40000
	v_lshl_add_u64 v[146:147], s[20:21], 0, v[128:129]
	s_addc_u32 s51, s21, 0
	s_add_i32 s49, s52, s30
	global_load_lds_dwordx4 v[146:147], off
	v_lshl_add_u64 v[150:151], s[50:51], 0, v[148:149]
	s_mov_b32 m0, s49
	v_lshl_add_u64 v[152:153], s[22:23], 0, v[130:131]
	global_load_lds_dwordx4 v[150:151], off
	v_lshl_add_u64 v[150:151], s[50:51], 0, v[128:129]
	s_add_i32 m0, s49, 0x2000
	s_nop 0
	global_load_lds_dwordx4 v[150:151], off
	v_lshl_add_u64 v[150:151], s[22:23], 0, v[132:133]
	s_mov_b32 m0, s31
	s_nop 0
	global_load_lds_dwordx4 v[150:151], off
	s_mov_b32 m0, s33
	s_nop 0
	global_load_lds_dwordx4 v[152:153], off
	s_waitcnt vmcnt(8)
	s_waitcnt lgkmcnt(0)
	s_barrier
	s_waitcnt lgkmcnt(0)
	v_mfma_f32_16x16x32_bf16 v[60:63], v[138:141], v[182:185], v[60:63]
	v_mfma_f32_16x16x32_bf16 v[56:59], v[158:161], v[182:185], v[56:59]
	v_mfma_f32_16x16x32_bf16 v[44:47], v[138:141], v[190:193], v[44:47]
	v_mfma_f32_16x16x32_bf16 v[40:43], v[158:161], v[190:193], v[40:43]
	v_mfma_f32_16x16x32_bf16 v[28:31], v[138:141], v[198:201], v[28:31]
	v_mfma_f32_16x16x32_bf16 v[24:27], v[158:161], v[198:201], v[24:27]
	v_mfma_f32_16x16x32_bf16 v[12:15], v[138:141], v[212:215], v[12:15]
	v_mfma_f32_16x16x32_bf16 v[8:11], v[158:161], v[212:215], v[8:11]
	v_mfma_f32_16x16x32_bf16 v[60:63], v[154:157], v[186:189], v[60:63]
	v_mfma_f32_16x16x32_bf16 v[56:59], v[162:165], v[186:189], v[56:59]
	v_mfma_f32_16x16x32_bf16 v[44:47], v[154:157], v[194:197], v[44:47]
	v_mfma_f32_16x16x32_bf16 v[40:43], v[162:165], v[194:197], v[40:43]
	v_mfma_f32_16x16x32_bf16 v[28:31], v[154:157], v[202:205], v[28:31]
	v_mfma_f32_16x16x32_bf16 v[24:27], v[162:165], v[202:205], v[24:27]
	v_mfma_f32_16x16x32_bf16 v[12:15], v[154:157], v[220:223], v[12:15]
	v_mfma_f32_16x16x32_bf16 v[8:11], v[162:165], v[220:223], v[8:11]
	v_mfma_f32_16x16x32_bf16 v[52:55], v[166:169], v[182:185], v[52:55]
	v_mfma_f32_16x16x32_bf16 v[48:51], v[174:177], v[182:185], v[48:51]
	v_mfma_f32_16x16x32_bf16 v[36:39], v[166:169], v[190:193], v[36:39]
	v_mfma_f32_16x16x32_bf16 v[32:35], v[174:177], v[190:193], v[32:35]
	v_mfma_f32_16x16x32_bf16 v[20:23], v[166:169], v[198:201], v[20:23]
	v_mfma_f32_16x16x32_bf16 v[16:19], v[174:177], v[198:201], v[16:19]
	v_mfma_f32_16x16x32_bf16 v[4:7], v[166:169], v[212:215], v[4:7]
	v_mfma_f32_16x16x32_bf16 v[0:3], v[174:177], v[212:215], v[0:3]
	v_mfma_f32_16x16x32_bf16 v[52:55], v[170:173], v[186:189], v[52:55]
	v_mfma_f32_16x16x32_bf16 v[48:51], v[178:181], v[186:189], v[48:51]
	v_mfma_f32_16x16x32_bf16 v[36:39], v[170:173], v[194:197], v[36:39]
	v_mfma_f32_16x16x32_bf16 v[32:35], v[178:181], v[194:197], v[32:35]
	v_mfma_f32_16x16x32_bf16 v[20:23], v[170:173], v[202:205], v[20:23]
	v_mfma_f32_16x16x32_bf16 v[16:19], v[178:181], v[202:205], v[16:19]
	v_mfma_f32_16x16x32_bf16 v[4:7], v[170:173], v[220:223], v[4:7]
	v_mfma_f32_16x16x32_bf16 v[0:3], v[178:181], v[220:223], v[0:3]
	s_barrier
	s_add_i32 s49, 0, 0x18000
	s_add_i32 s50, 0, 0x1c000
	v_add_u32_e32 v162, s49, v144
	v_add_u32_e32 v178, s50, v144
	ds_read_b128 v[138:141], v162
	ds_read_b128 v[154:157], v162 offset:1024
	ds_read_b128 v[158:161], v162 offset:2048
	ds_read_b128 v[162:165], v162 offset:3072
	ds_read_b128 v[166:169], v178
	ds_read_b128 v[170:173], v178 offset:1024
	ds_read_b128 v[174:177], v178 offset:2048
	ds_read_b128 v[178:181], v178 offset:3072
	s_add_u32 s22, s22, 0x40000
	s_addc_u32 s23, s23, 0
	s_mov_b32 m0, s34
	v_lshl_add_u64 v[208:209], s[22:23], 0, v[132:133]
	ds_read_b128 v[182:185], v145 offset:32768
	ds_read_b128 v[186:189], v145 offset:33792
	ds_read_b128 v[190:193], v145 offset:34816
	ds_read_b128 v[194:197], v145 offset:35840
	ds_read_b128 v[198:201], v145 offset:36864
	ds_read_b128 v[202:205], v145 offset:37888
	ds_read_b128 v[212:215], v145 offset:38912
	ds_read_b128 v[220:223], v145 offset:39936
	global_load_lds_dwordx4 v[208:209], off
	v_lshl_add_u64 v[208:209], s[22:23], 0, v[130:131]
	s_mov_b32 m0, s35
	s_nop 0
	global_load_lds_dwordx4 v[208:209], off
	s_waitcnt vmcnt(8)
	s_waitcnt lgkmcnt(0)
	s_barrier
	s_waitcnt lgkmcnt(0)
	v_mfma_f32_16x16x32_bf16 v[124:127], v[138:141], v[182:185], v[124:127]
	v_mfma_f32_16x16x32_bf16 v[120:123], v[158:161], v[182:185], v[120:123]
	v_mfma_f32_16x16x32_bf16 v[108:111], v[138:141], v[190:193], v[108:111]
	v_mfma_f32_16x16x32_bf16 v[104:107], v[158:161], v[190:193], v[104:107]
	v_mfma_f32_16x16x32_bf16 v[92:95], v[138:141], v[198:201], v[92:95]
	v_mfma_f32_16x16x32_bf16 v[88:91], v[158:161], v[198:201], v[88:91]
	v_mfma_f32_16x16x32_bf16 v[76:79], v[138:141], v[212:215], v[76:79]
	v_mfma_f32_16x16x32_bf16 v[72:75], v[158:161], v[212:215], v[72:75]
	v_mfma_f32_16x16x32_bf16 v[124:127], v[154:157], v[186:189], v[124:127]
	v_mfma_f32_16x16x32_bf16 v[120:123], v[162:165], v[186:189], v[120:123]
	v_mfma_f32_16x16x32_bf16 v[108:111], v[154:157], v[194:197], v[108:111]
	v_mfma_f32_16x16x32_bf16 v[104:107], v[162:165], v[194:197], v[104:107]
	v_mfma_f32_16x16x32_bf16 v[92:95], v[154:157], v[202:205], v[92:95]
	v_mfma_f32_16x16x32_bf16 v[88:91], v[162:165], v[202:205], v[88:91]
	v_mfma_f32_16x16x32_bf16 v[76:79], v[154:157], v[220:223], v[76:79]
	v_mfma_f32_16x16x32_bf16 v[72:75], v[162:165], v[220:223], v[72:75]
	v_mfma_f32_16x16x32_bf16 v[116:119], v[166:169], v[182:185], v[116:119]
	v_mfma_f32_16x16x32_bf16 v[112:115], v[174:177], v[182:185], v[112:115]
	v_mfma_f32_16x16x32_bf16 v[100:103], v[166:169], v[190:193], v[100:103]
	v_mfma_f32_16x16x32_bf16 v[96:99], v[174:177], v[190:193], v[96:99]
	v_mfma_f32_16x16x32_bf16 v[84:87], v[166:169], v[198:201], v[84:87]
	v_mfma_f32_16x16x32_bf16 v[80:83], v[174:177], v[198:201], v[80:83]
	v_mfma_f32_16x16x32_bf16 v[68:71], v[166:169], v[212:215], v[68:71]
	v_mfma_f32_16x16x32_bf16 v[64:67], v[174:177], v[212:215], v[64:67]
	v_mfma_f32_16x16x32_bf16 v[116:119], v[170:173], v[186:189], v[116:119]
	v_mfma_f32_16x16x32_bf16 v[112:115], v[178:181], v[186:189], v[112:115]
	v_mfma_f32_16x16x32_bf16 v[100:103], v[170:173], v[194:197], v[100:103]
	v_mfma_f32_16x16x32_bf16 v[96:99], v[178:181], v[194:197], v[96:99]
	v_mfma_f32_16x16x32_bf16 v[84:87], v[170:173], v[202:205], v[84:87]
	v_mfma_f32_16x16x32_bf16 v[80:83], v[178:181], v[202:205], v[80:83]
	v_mfma_f32_16x16x32_bf16 v[68:71], v[170:173], v[220:223], v[68:71]
	v_mfma_f32_16x16x32_bf16 v[64:67], v[178:181], v[220:223], v[64:67]
	s_barrier
	s_add_i32 s22, s49, s30
	v_lshl_add_u64 v[142:143], v[142:143], 0, s[28:29]
	s_mov_b32 m0, s22
	ds_read_b128 v[182:185], v145 offset:49152
	ds_read_b128 v[186:189], v145 offset:50176
	ds_read_b128 v[190:193], v145 offset:51200
	ds_read_b128 v[194:197], v145 offset:52224
	ds_read_b128 v[198:201], v145 offset:53248
	ds_read_b128 v[202:205], v145 offset:54272
	ds_read_b128 v[212:215], v145 offset:55296
	ds_read_b128 v[220:223], v145 offset:56320
	global_load_lds_dwordx4 v[142:143], off
	s_add_i32 m0, s22, 0x2000
	s_add_u32 s20, s20, 0x40080
	v_lshl_add_u64 v[142:143], v[146:147], 0, s[28:29]
	s_addc_u32 s21, s21, 0
	s_add_i32 s22, s50, s30
	global_load_lds_dwordx4 v[142:143], off
	v_lshl_add_u64 v[142:143], s[20:21], 0, v[148:149]
	s_mov_b32 m0, s22
	s_nop 0
	global_load_lds_dwordx4 v[142:143], off
	v_lshl_add_u64 v[142:143], s[20:21], 0, v[128:129]
	s_add_i32 m0, s22, 0x2000
	s_nop 0
	global_load_lds_dwordx4 v[142:143], off
	v_lshl_add_u64 v[142:143], v[150:151], 0, s[28:29]
	s_mov_b32 m0, s39
	s_nop 0
	global_load_lds_dwordx4 v[142:143], off
	v_lshl_add_u64 v[142:143], v[152:153], 0, s[28:29]
	s_mov_b32 m0, s40
	s_nop 0
	global_load_lds_dwordx4 v[142:143], off
	s_waitcnt vmcnt(8)
	s_waitcnt lgkmcnt(0)
	s_barrier
	s_waitcnt lgkmcnt(0)
	v_mfma_f32_16x16x32_bf16 v[60:63], v[138:141], v[182:185], v[60:63]
	v_mfma_f32_16x16x32_bf16 v[56:59], v[158:161], v[182:185], v[56:59]
	v_mfma_f32_16x16x32_bf16 v[44:47], v[138:141], v[190:193], v[44:47]
	v_mfma_f32_16x16x32_bf16 v[40:43], v[158:161], v[190:193], v[40:43]
	v_mfma_f32_16x16x32_bf16 v[28:31], v[138:141], v[198:201], v[28:31]
	v_mfma_f32_16x16x32_bf16 v[24:27], v[158:161], v[198:201], v[24:27]
	v_mfma_f32_16x16x32_bf16 v[12:15], v[138:141], v[212:215], v[12:15]
	v_mfma_f32_16x16x32_bf16 v[8:11], v[158:161], v[212:215], v[8:11]
	v_mfma_f32_16x16x32_bf16 v[60:63], v[154:157], v[186:189], v[60:63]
	v_mfma_f32_16x16x32_bf16 v[56:59], v[162:165], v[186:189], v[56:59]
	v_mfma_f32_16x16x32_bf16 v[44:47], v[154:157], v[194:197], v[44:47]
	v_mfma_f32_16x16x32_bf16 v[40:43], v[162:165], v[194:197], v[40:43]
	v_mfma_f32_16x16x32_bf16 v[28:31], v[154:157], v[202:205], v[28:31]
	v_mfma_f32_16x16x32_bf16 v[24:27], v[162:165], v[202:205], v[24:27]
	v_mfma_f32_16x16x32_bf16 v[12:15], v[154:157], v[220:223], v[12:15]
	v_mfma_f32_16x16x32_bf16 v[8:11], v[162:165], v[220:223], v[8:11]
	v_mfma_f32_16x16x32_bf16 v[52:55], v[166:169], v[182:185], v[52:55]
	v_mfma_f32_16x16x32_bf16 v[48:51], v[174:177], v[182:185], v[48:51]
	v_mfma_f32_16x16x32_bf16 v[36:39], v[166:169], v[190:193], v[36:39]
	v_mfma_f32_16x16x32_bf16 v[32:35], v[174:177], v[190:193], v[32:35]
	v_mfma_f32_16x16x32_bf16 v[20:23], v[166:169], v[198:201], v[20:23]
	v_mfma_f32_16x16x32_bf16 v[16:19], v[174:177], v[198:201], v[16:19]
	v_mfma_f32_16x16x32_bf16 v[4:7], v[166:169], v[212:215], v[4:7]
	v_mfma_f32_16x16x32_bf16 v[0:3], v[174:177], v[212:215], v[0:3]
	v_mfma_f32_16x16x32_bf16 v[52:55], v[170:173], v[186:189], v[52:55]
	v_mfma_f32_16x16x32_bf16 v[48:51], v[178:181], v[186:189], v[48:51]
	v_mfma_f32_16x16x32_bf16 v[36:39], v[170:173], v[194:197], v[36:39]
	v_mfma_f32_16x16x32_bf16 v[32:35], v[178:181], v[194:197], v[32:35]
	v_mfma_f32_16x16x32_bf16 v[20:23], v[170:173], v[202:205], v[20:23]
	v_mfma_f32_16x16x32_bf16 v[16:19], v[178:181], v[202:205], v[16:19]
	v_mfma_f32_16x16x32_bf16 v[4:7], v[170:173], v[220:223], v[4:7]
	v_mfma_f32_16x16x32_bf16 v[0:3], v[178:181], v[220:223], v[0:3]
	s_barrier
	s_add_i32 s48, s48, 2
	s_add_u32 s18, s18, 0x100
	s_addc_u32 s19, s19, 0
	s_add_u32 s46, s46, 0x100
	s_addc_u32 s47, s47, 0
	s_cmp_gt_u32 s48, 13
	s_cbranch_scc0 .LBB0_1438
	s_and_b64 vcc, exec, s[8:9]
	s_cbranch_vccz .LBB0_1441
	s_barrier
